# queries (q1) also kept in MFMA-fragment order by the in-proj epilogue (address-bit permutation of its element stores); intra-chunk phase and scan load whole fragments with coalesced loads, scan uses t
# baseline (speedup 1.0000x reference)
.LBB0_1061:
	s_andn2_b64 vcc, exec, s[0:1]
	s_cbranch_vccnz .LBB0_1035
	s_cmpk_gt_u32 s8, 0x3ff
	s_cselect_b64 s[2:3], -1, 0
	s_cmpk_lt_u32 s8, 0x400
	v_cmp_gt_i32_e32 vcc, s50, v114
	s_cselect_b64 s[4:5], -1, 0
	s_or_b64 s[0:1], s[2:3], vcc
	s_and_saveexec_b64 s[8:9], s[0:1]
	s_cbranch_execz .LBB0_1034
	v_add_u32_e32 v115, 0xfffffc00, v126
	v_cndmask_b32_e64 v0, v126, v115, s[2:3]
	v_ashrrev_i32_e32 v116, 8, v0
	v_ashrrev_i32_e32 v117, 31, v116
	v_lshl_add_u64 v[116:117], v[116:117], 2, s[54:55]
	global_load_dword v120, v[116:117], off
	s_nop 0
	global_load_dword v117, v[116:117], off offset:16
	v_lshl_add_u32 v116, v135, 2, v114
	v_cndmask_b32_e32 v118, v215, v216, vcc
	v_add_u32_e32 v118, v116, v118
	v_cvt_f32_i32_e32 v189, v118
	v_lshrrev_b32_e32 v118, 1, v0
	v_and_b32_e32 v187, 0x60, v118
	v_or_b32_e32 v137, v184, v187
	v_and_b32_e32 v119, 0x7c, v116
	v_cvt_f32_ubyte0_e32 v118, v137
	v_cvt_f32_ubyte0_e32 v122, v119
	v_mul_f32_e32 v119, 0xbdd64706, v118
	v_cndmask_b32_e32 v188, v205, v214, vcc
	v_cmp_gt_f32_e32 vcc, s26, v119
	v_and_b32_e32 v144, 0xffffff00, v0
	s_movk_i32 s0, 0x7f
	v_cndmask_b32_e32 v119, 0, v218, vcc
	v_fmac_f32_e32 v119, 0xbdd64706, v118
	v_exp_f32_e32 v118, v119
	v_cndmask_b32_e32 v0, 0, v219, vcc
	v_bitop3_b32 v121, v116, s0, v217 bitop3:0x6c
	v_cvt_f32_ubyte0_e32 v121, v121
	v_ldexp_f32 v141, v118, v0
	v_mul_f32_e32 v0, 0.15915494, v141
	v_mul_f32_e32 v119, v141, v189
	v_rndne_f32_e32 v0, v0
	v_mul_f32_e32 v124, 0.15915494, v119
	v_fmamk_f32 v125, v0, 0xc0c90000, v141
	v_rndne_f32_e32 v124, v124
	v_fmac_f32_e32 v125, 0xbafdaa22, v0
	v_fmac_f32_e32 v119, 0xc0c90000, v124
	v_mul_f32_e32 v118, v188, v141
	v_mul_f32_e32 v0, 0.15915494, v125
	v_fmac_f32_e32 v119, 0xbafdaa22, v124
	v_mul_f32_e32 v123, 0.15915494, v118
	v_sin_f32_e32 v140, v0
	v_mul_f32_e32 v119, 0.15915494, v119
	v_cos_f32_e32 v143, v0
	v_rndne_f32_e32 v123, v123
	v_cos_f32_e32 v132, v119
	v_fmac_f32_e32 v118, 0xc0c90000, v123
	v_sin_f32_e32 v128, v119
	v_fmac_f32_e32 v118, 0xbafdaa22, v123
	v_mul_f32_e32 v118, 0.15915494, v118
	v_mov_b32_e32 v138, v140
	v_mov_b32_e32 v139, v143
	v_sin_f32_e32 v134, v118
	v_cos_f32_e32 v136, v118
	v_pk_mul_f32 v[118:119], v[138:139], v[132:133] op_sel_hi:[1,0]
	s_mov_b32 s0, 0x3d800000
	v_pk_fma_f32 v[152:153], v[138:139], v[128:129], v[118:119] op_sel:[0,0,1] op_sel_hi:[1,0,0] neg_lo:[1,0,0] neg_hi:[1,0,0]
	v_pk_fma_f32 v[156:157], v[138:139], v[128:129], v[118:119] op_sel:[0,0,1] op_sel_hi:[1,0,0]
	v_mov_b32_e32 v154, v152
	v_pk_mov_b32 v[158:159], v[156:157], v[152:153] op_sel:[1,0]
	v_mov_b32_e32 v155, v157
	v_pk_mul_f32 v[158:159], v[140:141], v[158:159] op_sel_hi:[0,1]
	v_mov_b32_e32 v148, v106
	v_mov_b32_e32 v149, v108
	v_mov_b32_e32 v146, v110
	v_mov_b32_e32 v147, v112
	v_mov_b32_e32 v162, v128
	v_mov_b32_e32 v163, v157
	v_pk_mul_f32 v[178:179], v[134:135], v[162:163] op_sel_hi:[0,1]
	v_pk_mul_f32 v[162:163], v[136:137], v[162:163] op_sel_hi:[0,1]
	v_mov_b32_e32 v130, v107
	v_mov_b32_e32 v126, v111
	v_mov_b32_e32 v131, v109
	v_mov_b32_e32 v127, v113
	s_andn2_b64 vcc, exec, s[4:5]
	v_ashrrev_i32_e32 v145, 31, v144
	v_mov_b32_e32 v142, v143
	s_waitcnt vmcnt(1)
	v_mul_f32_e32 v0, 0x3fb8aa3b, v120
	s_waitcnt vmcnt(0)
	v_mul_f32_e32 v117, 0x3fb8aa3b, v117
	v_exp_f32_e32 v0, v0
	v_exp_f32_e32 v117, v117
	v_mul_f32_e32 v118, v121, v0
	v_mul_f32_e32 v119, v122, v117
	v_mul_f32_e32 v118, 0xbfb8aa3b, v118
	v_mul_f32_e32 v122, 0xbfb8aa3b, v119
	v_mul_f32_e32 v121, 0xbfb8aa3b, v117
	v_exp_f32_e32 v119, v118
	v_exp_f32_e32 v118, v122
	v_exp_f32_e32 v190, v121
	v_mul_f32_e32 v120, 0x3fb8aa3b, v0
	v_mul_f32_e32 v0, 0x41800000, v0
	v_mul_f32_e32 v0, 0x3fb8aa3b, v0
	v_pk_mul_f32 v[176:177], v[118:119], s[0:1] op_sel_hi:[1,0]
	v_exp_f32_e32 v151, v0
	v_mul_f32_e32 v0, v190, v176
	v_exp_f32_e32 v191, v120
	v_cndmask_b32_e64 v125, 1.0, v0, s[2:3]
	v_mul_f32_e32 v0, v190, v0
	v_mul_f32_e32 v121, v190, v0
	v_cndmask_b32_e64 v120, 1.0, v0, s[2:3]
	v_mov_b32_e32 v0, v143
	v_mul_f32_e32 v117, 0xc1800000, v117
	v_pk_fma_f32 v[160:161], v[0:1], v[154:155], v[158:159] op_sel_hi:[0,1,1] neg_lo:[0,0,1] neg_hi:[0,0,1]
	v_mul_f32_e32 v117, 0x3fb8aa3b, v117
	v_pk_fma_f32 v[158:159], v[0:1], v[154:155], v[158:159] op_sel_hi:[0,1,1]
	v_mov_b32_e32 v133, v160
	v_exp_f32_e32 v150, v117
	v_mul_f32_e32 v117, v191, v177
	v_pk_mul_f32 v[154:155], v[148:149], v[132:133]
	v_mov_b32_e32 v129, v159
	v_mul_f32_e32 v119, v191, v117
	v_pk_fma_f32 v[164:165], v[146:147], v[128:129], v[154:155]
	v_mov_b32_e32 v154, v132
	v_mov_b32_e32 v155, v152
	v_cndmask_b32_e64 v118, 1.0, v117, s[2:3]
	v_mul_f32_e32 v117, v191, v119
	v_pk_fma_f32 v[178:179], v[136:137], v[154:155], v[178:179] op_sel_hi:[0,1,1]
	v_pk_fma_f32 v[154:155], v[134:135], v[154:155], v[162:163] op_sel_hi:[0,1,1] neg_lo:[0,0,1] neg_hi:[0,0,1]
	v_cndmask_b32_e64 v123, 1.0, v119, s[2:3]
	v_cndmask_b32_e64 v119, 1.0, v117, s[2:3]
	v_mul_f32_e32 v0, v106, v154
	v_mul_f32_e32 v117, v107, v155
	v_pk_mul_f32 v[106:107], v[106:107], v[178:179]
	v_cndmask_b32_e64 v124, 1.0, v176, s[2:3]
	v_fma_f32 v0, v110, v178, -v0
	v_pk_fma_f32 v[106:107], v[110:111], v[154:155], v[106:107]
	v_mov_b32_e32 v161, v159
	v_mul_f32_e32 v180, v0, v124
	v_pk_mul_f32 v[154:155], v[106:107], v[124:125]
	v_pk_mul_f32 v[106:107], v[148:149], v[128:129]
	v_mov_b32_e32 v148, v143
	v_mov_b32_e32 v149, v140
	v_mul_f32_e32 v0, v140, v159
	v_fma_f32 v117, v111, v179, -v117
	v_pk_fma_f32 v[110:111], v[148:149], v[160:161], v[0:1] op_sel_hi:[1,1,0] neg_lo:[0,0,1] neg_hi:[0,0,1]
	v_mul_f32_e32 v0, v143, v159
	v_pk_fma_f32 v[106:107], v[146:147], v[132:133], v[106:107] neg_lo:[0,0,1] neg_hi:[0,0,1]
	v_pk_fma_f32 v[146:147], v[138:139], v[160:161], v[0:1] op_sel_hi:[1,1,0]
	v_mov_b32_e32 v153, v110
	v_pk_mov_b32 v[156:157], v[156:157], v[146:147] op_sel:[1,0]
	v_mov_b32_e32 v161, v110
	v_pk_mul_f32 v[162:163], v[130:131], v[156:157]
	v_pk_mul_f32 v[130:131], v[130:131], v[152:153]
	v_pk_mov_b32 v[110:111], v[158:159], v[146:147] op_sel:[1,0]
	v_pk_fma_f32 v[178:179], v[126:127], v[152:153], v[162:163] neg_lo:[0,0,1] neg_hi:[0,0,1]
	v_pk_fma_f32 v[126:127], v[126:127], v[156:157], v[130:131]
	v_pk_mul_f32 v[130:131], v[134:135], v[110:111] op_sel_hi:[0,1]
	v_pk_mul_f32 v[110:111], v[136:137], v[110:111] op_sel_hi:[0,1]
	v_pk_fma_f32 v[110:111], v[134:135], v[160:161], v[110:111] op_sel_hi:[0,1,1] neg_lo:[0,0,1] neg_hi:[0,0,1]
	v_pk_fma_f32 v[130:131], v[136:137], v[160:161], v[130:131] op_sel_hi:[0,1,1]
	v_mul_f32_e32 v0, v108, v110
	v_fma_f32 v0, v112, v130, -v0
	v_mul_f32_e32 v129, v0, v120
	v_mul_f32_e32 v0, v109, v111
	v_cndmask_b32_e64 v122, 1.0, v177, s[2:3]
	v_cndmask_b32_e64 v121, 1.0, v121, s[2:3]
	v_fma_f32 v0, v113, v131, -v0
	v_mul_f32_e32 v181, v117, v125
	v_pk_mul_f32 v[162:163], v[106:107], v[122:123]
	v_pk_mul_f32 v[106:107], v[108:109], v[130:131]
	v_mul_f32_e32 v108, v0, v121
	v_cndmask_b32_e64 v0, 0, 1, s[4:5]
	v_readlane_b32 s4, v251, 38
	v_pk_fma_f32 v[106:107], v[112:113], v[110:111], v[106:107]
	v_pk_mul_f32 v[160:161], v[126:127], v[118:119]
	v_bfe_u32 v109, v180, 16, 1
	v_or_b32_e32 v130, 1, v116
	v_bfe_u32 v110, v181, 16, 1
	v_or_b32_e32 v126, 2, v116
	v_bfe_u32 v113, v129, 16, 1
	v_or_b32_e32 v112, 3, v116
	v_bfe_u32 v133, v108, 16, 1
	v_readlane_b32 s5, v251, 39
	v_pk_mul_f32 v[158:159], v[164:165], v[122:123]
	v_pk_mul_f32 v[164:165], v[178:179], v[118:119]
	v_pk_mul_f32 v[156:157], v[106:107], v[120:121]
	v_pk_mul_f32 v[152:153], v[150:151], v[176:177]
	v_cmp_ne_u32_e64 s[0:1], 1, v0
	v_ashrrev_i32_e32 v117, 31, v116
	v_lshl_add_u64 v[106:107], v[144:145], 1, s[4:5]
	v_lshlrev_b32_e32 v0, 1, v137
	v_add3_u32 v109, v180, v109, s33
	v_ashrrev_i32_e32 v131, 31, v130
	v_add3_u32 v111, v181, v110, s33
	v_ashrrev_i32_e32 v127, 31, v126
	v_add3_u32 v129, v129, v113, s33
	v_ashrrev_i32_e32 v113, 31, v112
	v_add3_u32 v133, v108, v133, s33
	s_cbranch_vccnz .LBB0_1065
	v_lshl_add_u64 v[144:145], v[106:107], 0, v[0:1]
	v_lshlrev_b64 v[146:147], 11, v[116:117]
	v_bfe_u32 v108, v162, 16, 1
	v_lshl_add_u64 v[146:147], v[144:145], 0, v[146:147]
	v_add3_u32 v108, v162, v108, s33
	v_readlane_b32 s98, v251, 38
	s_nop 1
	v_subrev_u32_e32 v248, s98, v146
	v_bfe_u32 v249, v248, 11, 4
	v_lshlrev_b32_e32 v244, 4, v249
	v_bfe_u32 v249, v248, 9, 2
	v_lshl_or_b32 v244, v249, 13, v244
	v_bfe_u32 v249, v248, 6, 3
	v_lshl_or_b32 v244, v249, 10, v244
	v_bfe_u32 v249, v248, 4, 2
	v_lshl_or_b32 v244, v249, 8, v244
	v_and_b32_e32 v249, 0x7ff0, v248
	v_sub_u32_e32 v244, v244, v249
	v_add_u32_e32 v244, 0xa00, v244
	v_ashrrev_i32_e32 v245, 31, v244
	v_lshl_add_u64 v[244:245], v[146:147], 0, v[244:245]
	global_store_short_d16_hi v[244:245], v108, off offset:-2560
	v_bfe_u32 v108, v158, 16, 1
	v_add3_u32 v108, v158, v108, s33
	global_store_short_d16_hi v[244:245], v108, off offset:1536
	v_add_co_u32_e32 v146, vcc, s56, v146
	v_bfe_u32 v108, v154, 16, 1
	s_nop 0
	v_addc_co_u32_e32 v147, vcc, 0, v147, vcc
	v_add3_u32 v108, v154, v108, s33
	v_readlane_b32 s98, v251, 38
	s_nop 1
	v_subrev_u32_e32 v248, s98, v146
	v_bfe_u32 v249, v248, 11, 4
	v_lshlrev_b32_e32 v244, 4, v249
	v_bfe_u32 v249, v248, 9, 2
	v_lshl_or_b32 v244, v249, 13, v244
	v_bfe_u32 v249, v248, 6, 3
	v_lshl_or_b32 v244, v249, 10, v244
	v_bfe_u32 v249, v248, 4, 2
	v_lshl_or_b32 v244, v249, 8, v244
	v_and_b32_e32 v249, 0x7ff0, v248
	v_sub_u32_e32 v244, v244, v249
	v_add_u32_e32 v244, 0xa00, v244
	v_ashrrev_i32_e32 v245, 31, v244
	v_lshl_add_u64 v[244:245], v[146:147], 0, v[244:245]
	global_store_short_d16_hi v[244:245], v109, off offset:-2560
	global_store_short_d16_hi v[244:245], v108, off offset:1536
	v_lshlrev_b64 v[146:147], 11, v[130:131]
	v_bfe_u32 v108, v164, 16, 1
	v_lshl_add_u64 v[146:147], v[144:145], 0, v[146:147]
	v_add3_u32 v108, v164, v108, s33
	v_readlane_b32 s98, v251, 38
	s_nop 1
	v_subrev_u32_e32 v248, s98, v146
	v_bfe_u32 v249, v248, 11, 4
	v_lshlrev_b32_e32 v244, 4, v249
	v_bfe_u32 v249, v248, 9, 2
	v_lshl_or_b32 v244, v249, 13, v244
	v_bfe_u32 v249, v248, 6, 3
	v_lshl_or_b32 v244, v249, 10, v244
	v_bfe_u32 v249, v248, 4, 2
	v_lshl_or_b32 v244, v249, 8, v244
	v_and_b32_e32 v249, 0x7ff0, v248
	v_sub_u32_e32 v244, v244, v249
	v_add_u32_e32 v244, 0xa00, v244
	v_ashrrev_i32_e32 v245, 31, v244
	v_lshl_add_u64 v[244:245], v[146:147], 0, v[244:245]
	global_store_short_d16_hi v[244:245], v108, off offset:-2560
	v_bfe_u32 v108, v160, 16, 1
	v_add3_u32 v108, v160, v108, s33
	global_store_short_d16_hi v[244:245], v108, off offset:1536
	v_add_co_u32_e32 v146, vcc, s56, v146
	v_bfe_u32 v108, v155, 16, 1
	s_nop 0
	v_addc_co_u32_e32 v147, vcc, 0, v147, vcc
	v_add3_u32 v108, v155, v108, s33
	v_readlane_b32 s98, v251, 38
	s_nop 1
	v_subrev_u32_e32 v248, s98, v146
	v_bfe_u32 v249, v248, 11, 4
	v_lshlrev_b32_e32 v244, 4, v249
	v_bfe_u32 v249, v248, 9, 2
	v_lshl_or_b32 v244, v249, 13, v244
	v_bfe_u32 v249, v248, 6, 3
	v_lshl_or_b32 v244, v249, 10, v244
	v_bfe_u32 v249, v248, 4, 2
	v_lshl_or_b32 v244, v249, 8, v244
	v_and_b32_e32 v249, 0x7ff0, v248
	v_sub_u32_e32 v244, v244, v249
	v_add_u32_e32 v244, 0xa00, v244
	v_ashrrev_i32_e32 v245, 31, v244
	v_lshl_add_u64 v[244:245], v[146:147], 0, v[244:245]
	global_store_short_d16_hi v[244:245], v111, off offset:-2560
	global_store_short_d16_hi v[244:245], v108, off offset:1536
	v_lshlrev_b64 v[146:147], 11, v[126:127]
	v_bfe_u32 v108, v163, 16, 1
	v_lshl_add_u64 v[146:147], v[144:145], 0, v[146:147]
	v_add3_u32 v108, v163, v108, s33
	v_readlane_b32 s98, v251, 38
	s_nop 1
	v_subrev_u32_e32 v248, s98, v146
	v_bfe_u32 v249, v248, 11, 4
	v_lshlrev_b32_e32 v244, 4, v249
	v_bfe_u32 v249, v248, 9, 2
	v_lshl_or_b32 v244, v249, 13, v244
	v_bfe_u32 v249, v248, 6, 3
	v_lshl_or_b32 v244, v249, 10, v244
	v_bfe_u32 v249, v248, 4, 2
	v_lshl_or_b32 v244, v249, 8, v244
	v_and_b32_e32 v249, 0x7ff0, v248
	v_sub_u32_e32 v244, v244, v249
	v_add_u32_e32 v244, 0xa00, v244
	v_ashrrev_i32_e32 v245, 31, v244
	v_lshl_add_u64 v[244:245], v[146:147], 0, v[244:245]
	global_store_short_d16_hi v[244:245], v108, off offset:-2560
	v_bfe_u32 v108, v159, 16, 1
	v_add3_u32 v108, v159, v108, s33
	global_store_short_d16_hi v[244:245], v108, off offset:1536
	v_add_co_u32_e32 v146, vcc, s56, v146
	v_bfe_u32 v108, v156, 16, 1
	s_nop 0
	v_addc_co_u32_e32 v147, vcc, 0, v147, vcc
	v_add3_u32 v108, v156, v108, s33
	v_readlane_b32 s98, v251, 38
	s_nop 1
	v_subrev_u32_e32 v248, s98, v146
	v_bfe_u32 v249, v248, 11, 4
	v_lshlrev_b32_e32 v244, 4, v249
	v_bfe_u32 v249, v248, 9, 2
	v_lshl_or_b32 v244, v249, 13, v244
	v_bfe_u32 v249, v248, 6, 3
	v_lshl_or_b32 v244, v249, 10, v244
	v_bfe_u32 v249, v248, 4, 2
	v_lshl_or_b32 v244, v249, 8, v244
	v_and_b32_e32 v249, 0x7ff0, v248
	v_sub_u32_e32 v244, v244, v249
	v_add_u32_e32 v244, 0xa00, v244
	v_ashrrev_i32_e32 v245, 31, v244
	v_lshl_add_u64 v[244:245], v[146:147], 0, v[244:245]
	global_store_short_d16_hi v[244:245], v129, off offset:-2560
	global_store_short_d16_hi v[244:245], v108, off offset:1536
	v_lshlrev_b64 v[146:147], 11, v[112:113]
	v_bfe_u32 v108, v165, 16, 1
	v_lshl_add_u64 v[144:145], v[144:145], 0, v[146:147]
	v_add3_u32 v108, v165, v108, s33
	v_readlane_b32 s98, v251, 38
	s_nop 1
	v_subrev_u32_e32 v248, s98, v144
	v_bfe_u32 v249, v248, 11, 4
	v_lshlrev_b32_e32 v244, 4, v249
	v_bfe_u32 v249, v248, 9, 2
	v_lshl_or_b32 v244, v249, 13, v244
	v_bfe_u32 v249, v248, 6, 3
	v_lshl_or_b32 v244, v249, 10, v244
	v_bfe_u32 v249, v248, 4, 2
	v_lshl_or_b32 v244, v249, 8, v244
	v_and_b32_e32 v249, 0x7ff0, v248
	v_sub_u32_e32 v244, v244, v249
	v_add_u32_e32 v244, 0xa00, v244
	v_ashrrev_i32_e32 v245, 31, v244
	v_lshl_add_u64 v[244:245], v[144:145], 0, v[244:245]
	global_store_short_d16_hi v[244:245], v108, off offset:-2560
	v_bfe_u32 v108, v161, 16, 1
	v_add3_u32 v108, v161, v108, s33
	global_store_short_d16_hi v[244:245], v108, off offset:1536
	v_add_co_u32_e32 v144, vcc, 0x1000000, v144
	v_bfe_u32 v108, v157, 16, 1
	s_nop 0
	v_addc_co_u32_e32 v145, vcc, 0, v145, vcc
	v_add3_u32 v108, v157, v108, s33
	v_readlane_b32 s98, v251, 38
	s_nop 1
	v_subrev_u32_e32 v248, s98, v144
	v_bfe_u32 v249, v248, 11, 4
	v_lshlrev_b32_e32 v244, 4, v249
	v_bfe_u32 v249, v248, 9, 2
	v_lshl_or_b32 v244, v249, 13, v244
	v_bfe_u32 v249, v248, 6, 3
	v_lshl_or_b32 v244, v249, 10, v244
	v_bfe_u32 v249, v248, 4, 2
	v_lshl_or_b32 v244, v249, 8, v244
	v_and_b32_e32 v249, 0x7ff0, v248
	v_sub_u32_e32 v244, v244, v249
	v_add_u32_e32 v244, 0xa00, v244
	v_ashrrev_i32_e32 v245, 31, v244
	v_lshl_add_u64 v[244:245], v[144:145], 0, v[244:245]
	global_store_short_d16_hi v[244:245], v108, off offset:1536
	s_mov_b64 s[4:5], 0
	v_mov_b32_e32 v108, 1.0
	global_store_short_d16_hi v[244:245], v133, off offset:-2560
	s_branch .LBB0_1066

.LBB0_1068:
	v_mul_f32_e32 v109, 0x41800000, v141
	v_mul_f32_e32 v111, 0.15915494, v109
	v_rndne_f32_e32 v111, v111
	v_fmac_f32_e32 v109, 0xc0c90000, v111
	v_fmac_f32_e32 v109, 0xbafdaa22, v111
	v_mul_f32_e32 v109, 0.15915494, v109
	v_sin_f32_e32 v156, v109
	v_cos_f32_e32 v157, v109
	v_mov_b32_e32 v133, v132
	v_mov_b32_e32 v129, v128
	v_mov_b32_e32 v141, v140
	v_pk_mul_f32 v[132:133], v[156:157], v[132:133]
	v_mov_b32_e32 v158, v98
	v_pk_fma_f32 v[160:161], v[156:157], v[128:129], v[132:133] op_sel:[0,0,1] op_sel_hi:[1,1,0] neg_lo:[1,0,0] neg_hi:[1,0,0]
	v_pk_fma_f32 v[164:165], v[156:157], v[128:129], v[132:133] op_sel:[0,0,1] op_sel_hi:[1,1,0]
	v_mov_b32_e32 v162, v160
	v_mov_b32_e32 v163, v165
	v_pk_mul_f32 v[180:181], v[140:141], v[162:163]
	v_mov_b32_e32 v159, v101
	v_pk_fma_f32 v[182:183], v[142:143], v[162:163], v[180:181] op_sel:[0,0,1] op_sel_hi:[0,1,0] neg_lo:[0,0,1] neg_hi:[0,0,1]
	v_pk_fma_f32 v[180:181], v[142:143], v[162:163], v[180:181] op_sel:[0,0,1] op_sel_hi:[0,1,0]
	v_pk_mov_b32 v[194:195], v[180:181], v[182:183] op_sel:[1,0]
	v_mov_b32_e32 v192, v182
	v_mov_b32_e32 v193, v181
	v_pk_mul_f32 v[194:195], v[140:141], v[194:195]
	v_mov_b32_e32 v234, v160
	v_pk_fma_f32 v[196:197], v[142:143], v[192:193], v[194:195] op_sel_hi:[0,1,1] neg_lo:[0,0,1] neg_hi:[0,0,1]
	v_pk_fma_f32 v[192:193], v[142:143], v[192:193], v[194:195] op_sel_hi:[0,1,1]
	v_mov_b32_e32 v197, v193
	v_mul_f32_e32 v180, v149, v193
	v_pk_fma_f32 v[194:195], v[148:149], v[196:197], v[180:181] op_sel_hi:[1,1,0] neg_lo:[0,0,1] neg_hi:[0,0,1]
	v_mul_f32_e32 v180, v139, v193
	v_pk_fma_f32 v[198:199], v[138:139], v[196:197], v[180:181] op_sel_hi:[1,1,0]
	v_mov_b32_e32 v235, v194
	v_pk_mov_b32 v[238:239], v[164:165], v[198:199] op_sel:[1,0]
	v_mov_b32_e32 v137, v136
	v_mov_b32_e32 v135, v134
	v_mov_b32_e32 v154, v102
	v_mov_b32_e32 v155, v105
	v_pk_mul_f32 v[236:237], v[158:159], v[234:235]
	v_pk_mul_f32 v[158:159], v[158:159], v[238:239]
	v_mov_b32_e32 v180, v165
	v_pk_fma_f32 v[236:237], v[154:155], v[238:239], v[236:237]
	v_pk_fma_f32 v[154:155], v[154:155], v[234:235], v[158:159] neg_lo:[0,0,1] neg_hi:[0,0,1]
	v_mov_b32_e32 v158, v160
	v_mov_b32_e32 v159, v182
	v_pk_mul_f32 v[234:235], v[134:135], v[180:181]
	v_pk_mul_f32 v[238:239], v[136:137], v[180:181]
	v_pk_fma_f32 v[234:235], v[136:137], v[158:159], v[234:235]
	v_pk_fma_f32 v[158:159], v[134:135], v[158:159], v[238:239] neg_lo:[0,0,1] neg_hi:[0,0,1]
	v_mul_f32_e32 v128, v190, v152
	v_mul_f32_e32 v180, v98, v158
	v_pk_mul_f32 v[238:239], v[98:99], v[234:235]
	v_mul_f32_e32 v98, v99, v159
	v_cndmask_b32_e64 v109, 1.0, v128, s[2:3]
	v_fma_f32 v98, v103, v235, -v98
	v_mul_f32_e32 v111, v191, v153
	v_mov_b32_e32 v178, v99
	v_mov_b32_e32 v179, v100
	v_mul_f32_e32 v233, v98, v109
	v_mov_b32_e32 v183, v196
	v_mov_b32_e32 v98, v181
	v_mov_b32_e32 v99, v193
	v_mul_f32_e32 v129, v191, v111
	v_mov_b32_e32 v176, v103
	v_mov_b32_e32 v177, v104
	v_pk_fma_f32 v[238:239], v[102:103], v[158:159], v[238:239]
	v_pk_mul_f32 v[158:159], v[178:179], v[98:99]
	v_pk_mul_f32 v[178:179], v[178:179], v[182:183]
	v_cndmask_b32_e64 v132, 1.0, v111, s[2:3]
	v_cndmask_b32_e64 v133, 1.0, v129, s[2:3]
	v_pk_fma_f32 v[98:99], v[176:177], v[98:99], v[178:179]
	v_fma_f32 v180, v102, v234, -v180
	v_pk_fma_f32 v[158:159], v[176:177], v[182:183], v[158:159] neg_lo:[0,0,1] neg_hi:[0,0,1]
	v_pk_mul_f32 v[176:177], v[98:99], v[132:133]
	v_pk_mov_b32 v[98:99], v[192:193], v[198:199] op_sel:[1,0]
	v_mul_f32_e32 v195, v180, v108
	v_pk_mul_f32 v[180:181], v[158:159], v[132:133]
	v_mov_b32_e32 v197, v194
	v_pk_mul_f32 v[158:159], v[134:135], v[98:99]
	v_pk_mul_f32 v[98:99], v[136:137], v[98:99]
	v_mul_f32_e32 v128, v190, v128
	v_pk_fma_f32 v[98:99], v[134:135], v[196:197], v[98:99] neg_lo:[0,0,1] neg_hi:[0,0,1]
	v_pk_fma_f32 v[158:159], v[136:137], v[196:197], v[158:159]
	v_mul_f32_e32 v178, v100, v98
	v_mul_f32_e32 v111, v191, v129
	v_mul_f32_e32 v129, v190, v128
	v_cndmask_b32_e64 v128, 1.0, v128, s[2:3]
	v_fma_f32 v178, v104, v158, -v178
	v_mul_f32_e32 v194, v178, v128
	v_pk_mul_f32 v[178:179], v[100:101], v[158:159]
	v_cndmask_b32_e64 v129, 1.0, v129, s[2:3]
	v_pk_fma_f32 v[192:193], v[104:105], v[98:99], v[178:179]
	v_mul_f32_e32 v98, v101, v99
	v_fma_f32 v98, v105, v159, -v98
	v_mul_f32_e32 v98, v98, v129
	v_cndmask_b32_e64 v111, 1.0, v111, s[2:3]
	v_pk_mul_f32 v[158:159], v[150:151], v[152:153]
	v_bfe_u32 v99, v195, 16, 1
	v_bfe_u32 v100, v233, 16, 1
	v_bfe_u32 v152, v194, 16, 1
	v_bfe_u32 v153, v98, 16, 1
	v_pk_mul_f32 v[102:103], v[238:239], v[108:109]
	v_pk_mul_f32 v[182:183], v[154:155], v[110:111]
	v_pk_mul_f32 v[178:179], v[236:237], v[110:111]
	v_pk_mul_f32 v[104:105], v[192:193], v[128:129]
	s_and_b64 vcc, exec, s[0:1]
	v_add3_u32 v99, v195, v99, s33
	v_add3_u32 v101, v233, v100, s33
	v_add3_u32 v192, v194, v152, s33
	v_add3_u32 v193, v98, v153, s33
	s_cbranch_vccnz .LBB0_1070
	v_lshl_add_u64 v[152:153], v[106:107], 0, v[0:1]
	v_lshlrev_b64 v[154:155], 11, v[116:117]
	v_lshl_add_u64 v[152:153], v[152:153], 0, v[154:155]
	v_bfe_u32 v98, v182, 16, 1
	v_add_co_u32_e32 v194, vcc, 0x8000, v152
	v_add3_u32 v98, v182, v98, s33
	s_nop 0
	v_addc_co_u32_e32 v195, vcc, 0, v153, vcc
	s_mov_b64 s[4:5], 0x8000
	v_readlane_b32 s98, v251, 38
	s_nop 1
	v_subrev_u32_e32 v248, s98, v194
	v_bfe_u32 v249, v248, 11, 4
	v_lshlrev_b32_e32 v244, 4, v249
	v_bfe_u32 v249, v248, 9, 2
	v_lshl_or_b32 v244, v249, 13, v244
	v_bfe_u32 v249, v248, 6, 3
	v_lshl_or_b32 v244, v249, 10, v244
	v_bfe_u32 v249, v248, 4, 2
	v_lshl_or_b32 v244, v249, 8, v244
	v_and_b32_e32 v249, 0x7ff0, v248
	v_sub_u32_e32 v244, v244, v249
	v_add_u32_e32 v244, 0xa00, v244
	v_ashrrev_i32_e32 v245, 31, v244
	v_lshl_add_u64 v[244:245], v[194:195], 0, v[244:245]
	global_store_short_d16_hi v[244:245], v98, off offset:-2560
	v_bfe_u32 v98, v178, 16, 1
	v_lshl_add_u64 v[154:155], v[152:153], 0, s[4:5]
	v_add3_u32 v98, v178, v98, s33
	v_readlane_b32 s98, v251, 38
	s_nop 1
	v_subrev_u32_e32 v248, s98, v154
	v_bfe_u32 v249, v248, 11, 4
	v_lshlrev_b32_e32 v246, 4, v249
	v_bfe_u32 v249, v248, 9, 2
	v_lshl_or_b32 v246, v249, 13, v246
	v_bfe_u32 v249, v248, 6, 3
	v_lshl_or_b32 v246, v249, 10, v246
	v_bfe_u32 v249, v248, 4, 2
	v_lshl_or_b32 v246, v249, 8, v246
	v_and_b32_e32 v249, 0x7ff0, v248
	v_sub_u32_e32 v246, v246, v249
	v_add_u32_e32 v246, 0xa00, v246
	v_ashrrev_i32_e32 v247, 31, v246
	v_lshl_add_u64 v[246:247], v[154:155], 0, v[246:247]
	global_store_short_d16_hi v[246:247], v98, off offset:1536
	v_add_co_u32_e32 v154, vcc, 0x1008000, v152
	v_bfe_u32 v98, v102, 16, 1
	s_nop 0
	v_addc_co_u32_e32 v155, vcc, 0, v153, vcc
	v_add3_u32 v98, v102, v98, s33
	v_readlane_b32 s98, v251, 38
	s_nop 1
	v_subrev_u32_e32 v248, s98, v154
	v_bfe_u32 v249, v248, 11, 4
	v_lshlrev_b32_e32 v246, 4, v249
	v_bfe_u32 v249, v248, 9, 2
	v_lshl_or_b32 v246, v249, 13, v246
	v_bfe_u32 v249, v248, 6, 3
	v_lshl_or_b32 v246, v249, 10, v246
	v_bfe_u32 v249, v248, 4, 2
	v_lshl_or_b32 v246, v249, 8, v246
	v_and_b32_e32 v249, 0x7ff0, v248
	v_sub_u32_e32 v246, v246, v249
	v_add_u32_e32 v246, 0xa00, v246
	v_ashrrev_i32_e32 v247, 31, v246
	v_lshl_add_u64 v[246:247], v[154:155], 0, v[246:247]
	global_store_short_d16_hi v[246:247], v98, off offset:1536
	v_bfe_u32 v98, v180, 16, 1
	v_add3_u32 v98, v180, v98, s33
	s_mov_b64 s[4:5], 0x8800
	global_store_short_d16_hi v[244:245], v98, off offset:-2544
	v_bfe_u32 v98, v176, 16, 1
	v_lshl_add_u64 v[196:197], v[152:153], 0, s[4:5]
	v_add3_u32 v98, v176, v98, s33
	global_store_short_d16_hi v[246:247], v99, off offset:-2560
	v_readlane_b32 s98, v251, 38
	s_nop 1
	v_subrev_u32_e32 v248, s98, v196
	v_bfe_u32 v249, v248, 11, 4
	v_lshlrev_b32_e32 v244, 4, v249
	v_bfe_u32 v249, v248, 9, 2
	v_lshl_or_b32 v244, v249, 13, v244
	v_bfe_u32 v249, v248, 6, 3
	v_lshl_or_b32 v244, v249, 10, v244
	v_bfe_u32 v249, v248, 4, 2
	v_lshl_or_b32 v244, v249, 8, v244
	v_and_b32_e32 v249, 0x7ff0, v248
	v_sub_u32_e32 v244, v244, v249
	v_add_u32_e32 v244, 0xa00, v244
	v_ashrrev_i32_e32 v245, 31, v244
	v_lshl_add_u64 v[244:245], v[196:197], 0, v[244:245]
	global_store_short_d16_hi v[244:245], v98, off offset:1536
	global_store_short_d16_hi v[246:247], v101, off offset:-2544
	v_bfe_u32 v98, v103, 16, 1
	v_add3_u32 v98, v103, v98, s33
	s_mov_b64 s[4:5], 0x9000
	global_store_short_d16_hi v[246:247], v98, off offset:1552
	v_lshl_add_u64 v[154:155], v[152:153], 0, s[4:5]
	s_mov_b32 s4, 0x9000
	v_bfe_u32 v98, v181, 16, 1
	v_add_co_u32_e32 v194, vcc, s4, v152
	v_add3_u32 v98, v181, v98, s33
	s_nop 0
	v_addc_co_u32_e32 v195, vcc, 0, v153, vcc
	v_readlane_b32 s98, v251, 38
	s_nop 1
	v_subrev_u32_e32 v248, s98, v194
	v_bfe_u32 v249, v248, 11, 4
	v_lshlrev_b32_e32 v246, 4, v249
	v_bfe_u32 v249, v248, 9, 2
	v_lshl_or_b32 v246, v249, 13, v246
	v_bfe_u32 v249, v248, 6, 3
	v_lshl_or_b32 v246, v249, 10, v246
	v_bfe_u32 v249, v248, 4, 2
	v_lshl_or_b32 v246, v249, 8, v246
	v_and_b32_e32 v249, 0x7ff0, v248
	v_sub_u32_e32 v246, v246, v249
	v_add_u32_e32 v246, 0xa00, v246
	v_ashrrev_i32_e32 v247, 31, v246
	v_lshl_add_u64 v[246:247], v[194:195], 0, v[246:247]
	global_store_short_d16_hi v[246:247], v98, off offset:-2560
	v_bfe_u32 v98, v177, 16, 1
	v_add3_u32 v98, v177, v98, s33
	v_readlane_b32 s98, v251, 38
	s_nop 1
	v_subrev_u32_e32 v248, s98, v154
	v_bfe_u32 v249, v248, 11, 4
	v_lshlrev_b32_e32 v244, 4, v249
	v_bfe_u32 v249, v248, 9, 2
	v_lshl_or_b32 v244, v249, 13, v244
	v_bfe_u32 v249, v248, 6, 3
	v_lshl_or_b32 v244, v249, 10, v244
	v_bfe_u32 v249, v248, 4, 2
	v_lshl_or_b32 v244, v249, 8, v244
	v_and_b32_e32 v249, 0x7ff0, v248
	v_sub_u32_e32 v244, v244, v249
	v_add_u32_e32 v244, 0xa00, v244
	v_ashrrev_i32_e32 v245, 31, v244
	v_lshl_add_u64 v[244:245], v[154:155], 0, v[244:245]
	global_store_short_d16_hi v[244:245], v98, off offset:1536
	v_add_co_u32_e32 v154, vcc, s57, v152
	v_bfe_u32 v98, v104, 16, 1
	s_nop 0
	v_addc_co_u32_e32 v155, vcc, 0, v153, vcc
	v_add3_u32 v98, v104, v98, s33
	v_readlane_b32 s98, v251, 38
	s_nop 1
	v_subrev_u32_e32 v248, s98, v154
	v_bfe_u32 v249, v248, 11, 4
	v_lshlrev_b32_e32 v244, 4, v249
	v_bfe_u32 v249, v248, 9, 2
	v_lshl_or_b32 v244, v249, 13, v244
	v_bfe_u32 v249, v248, 6, 3
	v_lshl_or_b32 v244, v249, 10, v244
	v_bfe_u32 v249, v248, 4, 2
	v_lshl_or_b32 v244, v249, 8, v244
	v_and_b32_e32 v249, 0x7ff0, v248
	v_sub_u32_e32 v244, v244, v249
	v_add_u32_e32 v244, 0xa00, v244
	v_ashrrev_i32_e32 v245, 31, v244
	v_lshl_add_u64 v[244:245], v[154:155], 0, v[244:245]
	global_store_short_d16_hi v[244:245], v98, off offset:1536
	v_bfe_u32 v98, v183, 16, 1
	v_add3_u32 v98, v183, v98, s33
	s_mov_b64 s[4:5], 0x9800
	global_store_short_d16_hi v[246:247], v98, off offset:-2544
	v_bfe_u32 v98, v179, 16, 1
	v_lshl_add_u64 v[152:153], v[152:153], 0, s[4:5]
	v_add3_u32 v98, v179, v98, s33
	global_store_short_d16_hi v[244:245], v192, off offset:-2560
	v_readlane_b32 s98, v251, 38
	s_nop 1
	v_subrev_u32_e32 v248, s98, v152
	v_bfe_u32 v249, v248, 11, 4
	v_lshlrev_b32_e32 v246, 4, v249
	v_bfe_u32 v249, v248, 9, 2
	v_lshl_or_b32 v246, v249, 13, v246
	v_bfe_u32 v249, v248, 6, 3
	v_lshl_or_b32 v246, v249, 10, v246
	v_bfe_u32 v249, v248, 4, 2
	v_lshl_or_b32 v246, v249, 8, v246
	v_and_b32_e32 v249, 0x7ff0, v248
	v_sub_u32_e32 v246, v246, v249
	v_add_u32_e32 v246, 0xa00, v246
	v_ashrrev_i32_e32 v247, 31, v246
	v_lshl_add_u64 v[246:247], v[152:153], 0, v[246:247]
	global_store_short_d16_hi v[246:247], v98, off offset:1536
	global_store_short_d16_hi v[244:245], v193, off offset:-2544
	v_bfe_u32 v98, v105, 16, 1
	v_add3_u32 v98, v105, v98, s33
	global_store_short_d16_hi v[244:245], v98, off offset:1552
	s_mov_b64 s[4:5], 0
	v_mov_b32_e32 v98, 1.0
	s_branch .LBB0_1071

.LBB0_1073:
	v_pk_mov_b32 v[102:103], v[164:165], v[160:161] op_sel:[1,0]
	v_mov_b32_e32 v178, v90
	v_pk_mul_f32 v[102:103], v[156:157], v[102:103] op_sel_hi:[0,1]
	v_pk_fma_f32 v[160:161], v[156:157], v[162:163], v[102:103] op_sel:[1,0,0] neg_lo:[0,0,1] neg_hi:[0,0,1]
	v_pk_fma_f32 v[164:165], v[156:157], v[162:163], v[102:103] op_sel:[1,0,0]
	v_mov_b32_e32 v162, v160
	v_mov_b32_e32 v163, v165
	v_pk_mul_f32 v[192:193], v[140:141], v[162:163]
	v_mov_b32_e32 v179, v93
	v_pk_fma_f32 v[194:195], v[142:143], v[162:163], v[192:193] op_sel:[0,0,1] op_sel_hi:[1,1,0] neg_lo:[0,0,1] neg_hi:[0,0,1]
	v_pk_fma_f32 v[192:193], v[142:143], v[162:163], v[192:193] op_sel:[0,0,1] op_sel_hi:[1,1,0]
	v_mov_b32_e32 v196, v194
	v_pk_mov_b32 v[198:199], v[192:193], v[194:195] op_sel:[1,0]
	v_mov_b32_e32 v197, v193
	v_pk_mul_f32 v[198:199], v[140:141], v[198:199]
	v_mov_b32_e32 v238, v160
	v_pk_fma_f32 v[234:235], v[142:143], v[196:197], v[198:199] neg_lo:[0,0,1] neg_hi:[0,0,1]
	v_pk_fma_f32 v[196:197], v[142:143], v[196:197], v[198:199]
	v_mov_b32_e32 v176, v94
	v_mov_b32_e32 v235, v197
	v_mul_f32_e32 v192, v149, v197
	v_pk_fma_f32 v[198:199], v[148:149], v[234:235], v[192:193] op_sel_hi:[1,1,0] neg_lo:[0,0,1] neg_hi:[0,0,1]
	v_mul_f32_e32 v192, v139, v197
	v_pk_fma_f32 v[236:237], v[138:139], v[234:235], v[192:193] op_sel_hi:[1,1,0]
	v_mov_b32_e32 v239, v198
	v_pk_mov_b32 v[242:243], v[164:165], v[236:237] op_sel:[1,0]
	v_mov_b32_e32 v177, v97
	v_pk_mul_f32 v[240:241], v[178:179], v[238:239]
	v_pk_mul_f32 v[178:179], v[178:179], v[242:243]
	v_mov_b32_e32 v192, v165
	v_pk_fma_f32 v[240:241], v[176:177], v[242:243], v[240:241]
	v_pk_fma_f32 v[178:179], v[176:177], v[238:239], v[178:179] neg_lo:[0,0,1] neg_hi:[0,0,1]
	v_mov_b32_e32 v176, v160
	v_mov_b32_e32 v177, v194
	v_pk_mul_f32 v[238:239], v[134:135], v[192:193]
	v_pk_mul_f32 v[242:243], v[136:137], v[192:193]
	v_pk_fma_f32 v[238:239], v[136:137], v[176:177], v[238:239]
	v_pk_fma_f32 v[176:177], v[134:135], v[176:177], v[242:243] neg_lo:[0,0,1] neg_hi:[0,0,1]
	v_mul_f32_e32 v102, v190, v158
	v_mul_f32_e32 v192, v90, v176
	v_pk_mul_f32 v[242:243], v[90:91], v[238:239]
	v_mul_f32_e32 v90, v91, v177
	v_cndmask_b32_e64 v99, 1.0, v102, s[2:3]
	v_fma_f32 v90, v95, v239, -v90
	v_mul_f32_e32 v101, v191, v159
	v_mov_b32_e32 v182, v91
	v_mov_b32_e32 v183, v92
	v_mul_f32_e32 v233, v90, v99
	v_mov_b32_e32 v195, v234
	v_mov_b32_e32 v90, v193
	v_mov_b32_e32 v91, v197
	v_mul_f32_e32 v103, v191, v101
	v_mov_b32_e32 v180, v95
	v_mov_b32_e32 v181, v96
	v_pk_fma_f32 v[242:243], v[94:95], v[176:177], v[242:243]
	v_pk_mul_f32 v[176:177], v[182:183], v[90:91]
	v_pk_mul_f32 v[182:183], v[182:183], v[194:195]
	v_cndmask_b32_e64 v104, 1.0, v101, s[2:3]
	v_cndmask_b32_e64 v105, 1.0, v103, s[2:3]
	v_pk_fma_f32 v[176:177], v[180:181], v[194:195], v[176:177] neg_lo:[0,0,1] neg_hi:[0,0,1]
	v_pk_fma_f32 v[90:91], v[180:181], v[90:91], v[182:183]
	v_pk_mul_f32 v[180:181], v[176:177], v[104:105]
	v_pk_mul_f32 v[176:177], v[90:91], v[104:105]
	v_pk_mov_b32 v[90:91], v[196:197], v[236:237] op_sel:[1,0]
	v_mov_b32_e32 v235, v198
	v_pk_mul_f32 v[182:183], v[134:135], v[90:91]
	v_pk_mul_f32 v[90:91], v[136:137], v[90:91]
	v_fma_f32 v192, v94, v238, -v192
	v_pk_fma_f32 v[90:91], v[134:135], v[234:235], v[90:91] neg_lo:[0,0,1] neg_hi:[0,0,1]
	v_mul_f32_e32 v102, v190, v102
	v_mul_f32_e32 v199, v192, v98
	v_pk_fma_f32 v[192:193], v[136:137], v[234:235], v[182:183]
	v_mul_f32_e32 v182, v92, v90
	v_mul_f32_e32 v101, v191, v103
	v_mul_f32_e32 v103, v190, v102
	v_cndmask_b32_e64 v102, 1.0, v102, s[2:3]
	v_fma_f32 v182, v96, v192, -v182
	v_mul_f32_e32 v196, v182, v102
	v_pk_mul_f32 v[182:183], v[92:93], v[192:193]
	v_cndmask_b32_e64 v103, 1.0, v103, s[2:3]
	v_pk_fma_f32 v[194:195], v[96:97], v[90:91], v[182:183]
	v_mul_f32_e32 v90, v93, v91
	v_fma_f32 v90, v97, v193, -v90
	v_mul_f32_e32 v92, v90, v103
	v_cndmask_b32_e64 v101, 1.0, v101, s[2:3]
	v_pk_mul_f32 v[90:91], v[150:151], v[158:159]
	v_bfe_u32 v93, v199, 16, 1
	v_bfe_u32 v150, v233, 16, 1
	v_bfe_u32 v151, v196, 16, 1
	v_bfe_u32 v158, v92, 16, 1
	v_pk_mul_f32 v[94:95], v[242:243], v[98:99]
	v_pk_mul_f32 v[182:183], v[178:179], v[100:101]
	v_pk_mul_f32 v[178:179], v[240:241], v[100:101]
	v_pk_mul_f32 v[96:97], v[194:195], v[102:103]
	s_and_b64 vcc, exec, s[0:1]
	v_add3_u32 v93, v199, v93, s33
	v_add3_u32 v192, v233, v150, s33
	v_add3_u32 v193, v196, v151, s33
	v_add3_u32 v194, v92, v158, s33
	s_cbranch_vccnz .LBB0_1075
	v_lshl_add_u64 v[150:151], v[106:107], 0, v[0:1]
	v_lshlrev_b64 v[158:159], 11, v[116:117]
	v_lshl_add_u64 v[150:151], v[150:151], 0, v[158:159]
	v_bfe_u32 v92, v182, 16, 1
	v_add_co_u32_e32 v196, vcc, 0x10000, v150
	v_add3_u32 v92, v182, v92, s33
	s_nop 0
	v_addc_co_u32_e32 v197, vcc, 0, v151, vcc
	s_mov_b64 s[4:5], 0x10000
	v_readlane_b32 s98, v251, 38
	s_nop 1
	v_subrev_u32_e32 v248, s98, v196
	v_bfe_u32 v249, v248, 11, 4
	v_lshlrev_b32_e32 v244, 4, v249
	v_bfe_u32 v249, v248, 9, 2
	v_lshl_or_b32 v244, v249, 13, v244
	v_bfe_u32 v249, v248, 6, 3
	v_lshl_or_b32 v244, v249, 10, v244
	v_bfe_u32 v249, v248, 4, 2
	v_lshl_or_b32 v244, v249, 8, v244
	v_and_b32_e32 v249, 0x7ff0, v248
	v_sub_u32_e32 v244, v244, v249
	v_add_u32_e32 v244, 0xa00, v244
	v_ashrrev_i32_e32 v245, 31, v244
	v_lshl_add_u64 v[244:245], v[196:197], 0, v[244:245]
	global_store_short_d16_hi v[244:245], v92, off offset:-2560
	v_bfe_u32 v92, v178, 16, 1
	v_lshl_add_u64 v[158:159], v[150:151], 0, s[4:5]
	v_add3_u32 v92, v178, v92, s33
	v_readlane_b32 s98, v251, 38
	s_nop 1
	v_subrev_u32_e32 v248, s98, v158
	v_bfe_u32 v249, v248, 11, 4
	v_lshlrev_b32_e32 v246, 4, v249
	v_bfe_u32 v249, v248, 9, 2
	v_lshl_or_b32 v246, v249, 13, v246
	v_bfe_u32 v249, v248, 6, 3
	v_lshl_or_b32 v246, v249, 10, v246
	v_bfe_u32 v249, v248, 4, 2
	v_lshl_or_b32 v246, v249, 8, v246
	v_and_b32_e32 v249, 0x7ff0, v248
	v_sub_u32_e32 v246, v246, v249
	v_add_u32_e32 v246, 0xa00, v246
	v_ashrrev_i32_e32 v247, 31, v246
	v_lshl_add_u64 v[246:247], v[158:159], 0, v[246:247]
	global_store_short_d16_hi v[246:247], v92, off offset:1536
	v_add_co_u32_e32 v158, vcc, 0x1010000, v150
	v_bfe_u32 v92, v94, 16, 1
	s_nop 0
	v_addc_co_u32_e32 v159, vcc, 0, v151, vcc
	v_add3_u32 v92, v94, v92, s33
	v_readlane_b32 s98, v251, 38
	s_nop 1
	v_subrev_u32_e32 v248, s98, v158
	v_bfe_u32 v249, v248, 11, 4
	v_lshlrev_b32_e32 v246, 4, v249
	v_bfe_u32 v249, v248, 9, 2
	v_lshl_or_b32 v246, v249, 13, v246
	v_bfe_u32 v249, v248, 6, 3
	v_lshl_or_b32 v246, v249, 10, v246
	v_bfe_u32 v249, v248, 4, 2
	v_lshl_or_b32 v246, v249, 8, v246
	v_and_b32_e32 v249, 0x7ff0, v248
	v_sub_u32_e32 v246, v246, v249
	v_add_u32_e32 v246, 0xa00, v246
	v_ashrrev_i32_e32 v247, 31, v246
	v_lshl_add_u64 v[246:247], v[158:159], 0, v[246:247]
	global_store_short_d16_hi v[246:247], v92, off offset:1536
	v_bfe_u32 v92, v180, 16, 1
	v_add3_u32 v92, v180, v92, s33
	s_mov_b64 s[4:5], 0x10800
	global_store_short_d16_hi v[244:245], v92, off offset:-2544
	v_bfe_u32 v92, v176, 16, 1
	v_lshl_add_u64 v[198:199], v[150:151], 0, s[4:5]
	v_add3_u32 v92, v176, v92, s33
	global_store_short_d16_hi v[246:247], v93, off offset:-2560
	v_readlane_b32 s98, v251, 38
	s_nop 1
	v_subrev_u32_e32 v248, s98, v198
	v_bfe_u32 v249, v248, 11, 4
	v_lshlrev_b32_e32 v244, 4, v249
	v_bfe_u32 v249, v248, 9, 2
	v_lshl_or_b32 v244, v249, 13, v244
	v_bfe_u32 v249, v248, 6, 3
	v_lshl_or_b32 v244, v249, 10, v244
	v_bfe_u32 v249, v248, 4, 2
	v_lshl_or_b32 v244, v249, 8, v244
	v_and_b32_e32 v249, 0x7ff0, v248
	v_sub_u32_e32 v244, v244, v249
	v_add_u32_e32 v244, 0xa00, v244
	v_ashrrev_i32_e32 v245, 31, v244
	v_lshl_add_u64 v[244:245], v[198:199], 0, v[244:245]
	global_store_short_d16_hi v[244:245], v92, off offset:1536
	global_store_short_d16_hi v[246:247], v192, off offset:-2544
	v_bfe_u32 v92, v95, 16, 1
	v_add3_u32 v92, v95, v92, s33
	global_store_short_d16_hi v[246:247], v92, off offset:1552
	v_bfe_u32 v92, v181, 16, 1
	v_add_co_u32_e32 v196, vcc, s89, v150
	v_add3_u32 v92, v181, v92, s33
	s_nop 0
	v_addc_co_u32_e32 v197, vcc, 0, v151, vcc
	s_mov_b64 s[4:5], 0x11000
	v_readlane_b32 s98, v251, 38
	s_nop 1
	v_subrev_u32_e32 v248, s98, v196
	v_bfe_u32 v249, v248, 11, 4
	v_lshlrev_b32_e32 v244, 4, v249
	v_bfe_u32 v249, v248, 9, 2
	v_lshl_or_b32 v244, v249, 13, v244
	v_bfe_u32 v249, v248, 6, 3
	v_lshl_or_b32 v244, v249, 10, v244
	v_bfe_u32 v249, v248, 4, 2
	v_lshl_or_b32 v244, v249, 8, v244
	v_and_b32_e32 v249, 0x7ff0, v248
	v_sub_u32_e32 v244, v244, v249
	v_add_u32_e32 v244, 0xa00, v244
	v_ashrrev_i32_e32 v245, 31, v244
	v_lshl_add_u64 v[244:245], v[196:197], 0, v[244:245]
	global_store_short_d16_hi v[244:245], v92, off offset:-2560
	v_bfe_u32 v92, v177, 16, 1
	v_lshl_add_u64 v[158:159], v[150:151], 0, s[4:5]
	v_add3_u32 v92, v177, v92, s33
	v_readlane_b32 s98, v251, 38
	s_nop 1
	v_subrev_u32_e32 v248, s98, v158
	v_bfe_u32 v249, v248, 11, 4
	v_lshlrev_b32_e32 v246, 4, v249
	v_bfe_u32 v249, v248, 9, 2
	v_lshl_or_b32 v246, v249, 13, v246
	v_bfe_u32 v249, v248, 6, 3
	v_lshl_or_b32 v246, v249, 10, v246
	v_bfe_u32 v249, v248, 4, 2
	v_lshl_or_b32 v246, v249, 8, v246
	v_and_b32_e32 v249, 0x7ff0, v248
	v_sub_u32_e32 v246, v246, v249
	v_add_u32_e32 v246, 0xa00, v246
	v_ashrrev_i32_e32 v247, 31, v246
	v_lshl_add_u64 v[246:247], v[158:159], 0, v[246:247]
	global_store_short_d16_hi v[246:247], v92, off offset:1536
	v_add_co_u32_e32 v158, vcc, s58, v150
	v_bfe_u32 v92, v96, 16, 1
	s_nop 0
	v_addc_co_u32_e32 v159, vcc, 0, v151, vcc
	v_add3_u32 v92, v96, v92, s33
	v_readlane_b32 s98, v251, 38
	s_nop 1
	v_subrev_u32_e32 v248, s98, v158
	v_bfe_u32 v249, v248, 11, 4
	v_lshlrev_b32_e32 v246, 4, v249
	v_bfe_u32 v249, v248, 9, 2
	v_lshl_or_b32 v246, v249, 13, v246
	v_bfe_u32 v249, v248, 6, 3
	v_lshl_or_b32 v246, v249, 10, v246
	v_bfe_u32 v249, v248, 4, 2
	v_lshl_or_b32 v246, v249, 8, v246
	v_and_b32_e32 v249, 0x7ff0, v248
	v_sub_u32_e32 v246, v246, v249
	v_add_u32_e32 v246, 0xa00, v246
	v_ashrrev_i32_e32 v247, 31, v246
	v_lshl_add_u64 v[246:247], v[158:159], 0, v[246:247]
	global_store_short_d16_hi v[246:247], v92, off offset:1536
	v_bfe_u32 v92, v183, 16, 1
	v_add3_u32 v92, v183, v92, s33
	s_mov_b64 s[4:5], 0x11800
	global_store_short_d16_hi v[244:245], v92, off offset:-2544
	v_bfe_u32 v92, v179, 16, 1
	v_lshl_add_u64 v[150:151], v[150:151], 0, s[4:5]
	v_add3_u32 v92, v179, v92, s33
	global_store_short_d16_hi v[246:247], v193, off offset:-2560
	v_readlane_b32 s98, v251, 38
	s_nop 1
	v_subrev_u32_e32 v248, s98, v150
	v_bfe_u32 v249, v248, 11, 4
	v_lshlrev_b32_e32 v244, 4, v249
	v_bfe_u32 v249, v248, 9, 2
	v_lshl_or_b32 v244, v249, 13, v244
	v_bfe_u32 v249, v248, 6, 3
	v_lshl_or_b32 v244, v249, 10, v244
	v_bfe_u32 v249, v248, 4, 2
	v_lshl_or_b32 v244, v249, 8, v244
	v_and_b32_e32 v249, 0x7ff0, v248
	v_sub_u32_e32 v244, v244, v249
	v_add_u32_e32 v244, 0xa00, v244
	v_ashrrev_i32_e32 v245, 31, v244
	v_lshl_add_u64 v[244:245], v[150:151], 0, v[244:245]
	global_store_short_d16_hi v[244:245], v92, off offset:1536
	global_store_short_d16_hi v[246:247], v194, off offset:-2544
	v_bfe_u32 v92, v97, 16, 1
	v_add3_u32 v92, v97, v92, s33
	v_mov_b32_e32 v195, v90
	s_mov_b64 s[4:5], 0
	v_mov_b32_e32 v90, 1.0
	global_store_short_d16_hi v[246:247], v92, off offset:1552
	s_branch .LBB0_1076

.LBB0_1078:
	v_mov_b32_e32 v94, v157
	v_mov_b32_e32 v95, v157
	v_mov_b32_e32 v157, v156
	v_pk_mov_b32 v[96:97], v[164:165], v[160:161] op_sel:[1,0]
	v_mul_f32_e32 v93, v191, v196
	v_pk_mul_f32 v[96:97], v[156:157], v[96:97]
	v_mov_b32_e32 v178, v82
	v_pk_fma_f32 v[156:157], v[94:95], v[162:163], v[96:97] neg_lo:[0,0,1] neg_hi:[0,0,1]
	v_pk_fma_f32 v[160:161], v[94:95], v[162:163], v[96:97]
	v_mov_b32_e32 v162, v156
	v_pk_mov_b32 v[94:95], v[160:161], v[156:157] op_sel:[1,0]
	v_mov_b32_e32 v163, v161
	v_pk_mul_f32 v[164:165], v[140:141], v[94:95]
	v_mul_f32_e32 v94, v190, v195
	v_cndmask_b32_e64 v91, 1.0, v94, s[2:3]
	v_mul_f32_e32 v95, v191, v93
	v_mul_f32_e32 v94, v190, v94
	v_cndmask_b32_e64 v96, 1.0, v93, s[2:3]
	v_cndmask_b32_e64 v97, 1.0, v95, s[2:3]
	v_mul_f32_e32 v93, v191, v95
	v_mul_f32_e32 v95, v190, v94
	v_pk_fma_f32 v[190:191], v[142:143], v[162:163], v[164:165] neg_lo:[0,0,1] neg_hi:[0,0,1]
	v_pk_fma_f32 v[162:163], v[142:143], v[162:163], v[164:165]
	v_mov_b32_e32 v164, v190
	v_pk_mov_b32 v[192:193], v[162:163], v[190:191] op_sel:[1,0]
	v_mov_b32_e32 v165, v163
	v_pk_mul_f32 v[140:141], v[140:141], v[192:193]
	v_mov_b32_e32 v179, v85
	v_pk_fma_f32 v[192:193], v[142:143], v[164:165], v[140:141] neg_lo:[0,0,1] neg_hi:[0,0,1]
	v_pk_fma_f32 v[142:143], v[142:143], v[164:165], v[140:141]
	v_mov_b32_e32 v176, v86
	v_mov_b32_e32 v193, v143
	v_mul_f32_e32 v140, v149, v143
	v_pk_fma_f32 v[148:149], v[148:149], v[192:193], v[140:141] op_sel_hi:[1,1,0] neg_lo:[0,0,1] neg_hi:[0,0,1]
	v_mul_f32_e32 v140, v139, v143
	v_pk_fma_f32 v[164:165], v[138:139], v[192:193], v[140:141] op_sel_hi:[1,1,0]
	v_mov_b32_e32 v157, v148
	v_mov_b32_e32 v177, v89
	v_pk_mul_f32 v[138:139], v[178:179], v[156:157]
	v_pk_mov_b32 v[140:141], v[160:161], v[164:165] op_sel:[1,0]
	v_mov_b32_e32 v162, v161
	v_pk_fma_f32 v[194:195], v[176:177], v[140:141], v[138:139]
	v_pk_mul_f32 v[138:139], v[178:179], v[140:141]
	v_pk_mul_f32 v[140:141], v[136:137], v[162:163]
	v_pk_fma_f32 v[176:177], v[176:177], v[156:157], v[138:139] neg_lo:[0,0,1] neg_hi:[0,0,1]
	v_mov_b32_e32 v157, v190
	v_pk_mul_f32 v[138:139], v[134:135], v[162:163]
	v_pk_fma_f32 v[140:141], v[134:135], v[156:157], v[140:141] neg_lo:[0,0,1] neg_hi:[0,0,1]
	v_pk_fma_f32 v[138:139], v[136:137], v[156:157], v[138:139]
	v_mul_f32_e32 v149, v82, v140
	v_pk_mul_f32 v[156:157], v[82:83], v[138:139]
	v_mul_f32_e32 v82, v83, v141
	v_mov_b32_e32 v180, v87
	v_mov_b32_e32 v182, v83
	v_mov_b32_e32 v183, v84
	v_fma_f32 v149, v86, v138, -v149
	v_pk_fma_f32 v[156:157], v[86:87], v[140:141], v[156:157]
	v_fma_f32 v82, v87, v139, -v82
	v_mov_b32_e32 v191, v192
	v_mov_b32_e32 v86, v163
	v_mov_b32_e32 v87, v143
	v_mov_b32_e32 v181, v88
	v_pk_mul_f32 v[138:139], v[182:183], v[86:87]
	v_pk_mul_f32 v[140:141], v[182:183], v[190:191]
	v_pk_fma_f32 v[138:139], v[180:181], v[190:191], v[138:139] neg_lo:[0,0,1] neg_hi:[0,0,1]
	v_pk_fma_f32 v[86:87], v[180:181], v[86:87], v[140:141]
	v_pk_mul_f32 v[140:141], v[138:139], v[96:97]
	v_pk_mul_f32 v[138:139], v[86:87], v[96:97]
	v_pk_mov_b32 v[86:87], v[142:143], v[164:165] op_sel:[1,0]
	v_mov_b32_e32 v193, v148
	v_pk_mul_f32 v[142:143], v[134:135], v[86:87]
	v_pk_mul_f32 v[86:87], v[136:137], v[86:87]
	v_pk_fma_f32 v[142:143], v[136:137], v[192:193], v[142:143]
	v_pk_fma_f32 v[86:87], v[134:135], v[192:193], v[86:87] neg_lo:[0,0,1] neg_hi:[0,0,1]
	v_cndmask_b32_e64 v94, 1.0, v94, s[2:3]
	v_mul_f32_e32 v134, v84, v86
	v_fma_f32 v134, v88, v142, -v134
	v_mul_f32_e32 v161, v82, v91
	v_pk_mul_f32 v[82:83], v[156:157], v[90:91]
	v_mul_f32_e32 v156, v134, v94
	v_pk_mul_f32 v[134:135], v[84:85], v[142:143]
	v_mul_f32_e32 v84, v85, v87
	v_cndmask_b32_e64 v95, 1.0, v95, s[2:3]
	v_fma_f32 v84, v89, v143, -v84
	v_mul_f32_e32 v160, v149, v90
	v_pk_fma_f32 v[148:149], v[88:89], v[86:87], v[134:135]
	v_mul_f32_e32 v84, v84, v95
	v_cndmask_b32_e64 v93, 1.0, v93, s[2:3]
	v_pk_mul_f32 v[86:87], v[148:149], v[94:95]
	v_bfe_u32 v85, v160, 16, 1
	v_bfe_u32 v88, v161, 16, 1
	v_bfe_u32 v89, v156, 16, 1
	v_bfe_u32 v149, v84, 16, 1
	v_pk_mul_f32 v[136:137], v[176:177], v[92:93]
	v_pk_mul_f32 v[134:135], v[194:195], v[92:93]
	s_mov_b64 s[4:5], -1
	s_and_b64 vcc, exec, s[0:1]
	v_add3_u32 v142, v160, v85, s33
	v_add3_u32 v143, v161, v88, s33
	v_add3_u32 v148, v156, v89, s33
	v_add3_u32 v149, v84, v149, s33
	s_cbranch_vccnz .LBB0_1080
	v_lshl_add_u64 v[84:85], v[106:107], 0, v[0:1]
	v_lshlrev_b64 v[88:89], 11, v[116:117]
	v_lshl_add_u64 v[84:85], v[84:85], 0, v[88:89]
	v_bfe_u32 v0, v136, 16, 1
	v_add_co_u32_e32 v156, vcc, 0x18000, v84
	v_add3_u32 v0, v136, v0, s33
	s_nop 0
	v_addc_co_u32_e32 v157, vcc, 0, v85, vcc
	s_mov_b64 s[4:5], 0x18000
	v_readlane_b32 s98, v251, 38
	s_nop 1
	v_subrev_u32_e32 v248, s98, v156
	v_bfe_u32 v249, v248, 11, 4
	v_lshlrev_b32_e32 v244, 4, v249
	v_bfe_u32 v249, v248, 9, 2
	v_lshl_or_b32 v244, v249, 13, v244
	v_bfe_u32 v249, v248, 6, 3
	v_lshl_or_b32 v244, v249, 10, v244
	v_bfe_u32 v249, v248, 4, 2
	v_lshl_or_b32 v244, v249, 8, v244
	v_and_b32_e32 v249, 0x7ff0, v248
	v_sub_u32_e32 v244, v244, v249
	v_add_u32_e32 v244, 0xa00, v244
	v_ashrrev_i32_e32 v245, 31, v244
	v_lshl_add_u64 v[244:245], v[156:157], 0, v[244:245]
	global_store_short_d16_hi v[244:245], v0, off offset:-2560
	v_bfe_u32 v0, v134, 16, 1
	v_lshl_add_u64 v[88:89], v[84:85], 0, s[4:5]
	v_add3_u32 v0, v134, v0, s33
	v_readlane_b32 s98, v251, 38
	s_nop 1
	v_subrev_u32_e32 v248, s98, v88
	v_bfe_u32 v249, v248, 11, 4
	v_lshlrev_b32_e32 v246, 4, v249
	v_bfe_u32 v249, v248, 9, 2
	v_lshl_or_b32 v246, v249, 13, v246
	v_bfe_u32 v249, v248, 6, 3
	v_lshl_or_b32 v246, v249, 10, v246
	v_bfe_u32 v249, v248, 4, 2
	v_lshl_or_b32 v246, v249, 8, v246
	v_and_b32_e32 v249, 0x7ff0, v248
	v_sub_u32_e32 v246, v246, v249
	v_add_u32_e32 v246, 0xa00, v246
	v_ashrrev_i32_e32 v247, 31, v246
	v_lshl_add_u64 v[246:247], v[88:89], 0, v[246:247]
	global_store_short_d16_hi v[246:247], v0, off offset:1536
	v_add_co_u32_e32 v88, vcc, 0x1018000, v84
	v_bfe_u32 v0, v82, 16, 1
	s_nop 0
	v_addc_co_u32_e32 v89, vcc, 0, v85, vcc
	v_add3_u32 v0, v82, v0, s33
	v_readlane_b32 s98, v251, 38
	s_nop 1
	v_subrev_u32_e32 v248, s98, v88
	v_bfe_u32 v249, v248, 11, 4
	v_lshlrev_b32_e32 v246, 4, v249
	v_bfe_u32 v249, v248, 9, 2
	v_lshl_or_b32 v246, v249, 13, v246
	v_bfe_u32 v249, v248, 6, 3
	v_lshl_or_b32 v246, v249, 10, v246
	v_bfe_u32 v249, v248, 4, 2
	v_lshl_or_b32 v246, v249, 8, v246
	v_and_b32_e32 v249, 0x7ff0, v248
	v_sub_u32_e32 v246, v246, v249
	v_add_u32_e32 v246, 0xa00, v246
	v_ashrrev_i32_e32 v247, 31, v246
	v_lshl_add_u64 v[246:247], v[88:89], 0, v[246:247]
	global_store_short_d16_hi v[246:247], v0, off offset:1536
	v_bfe_u32 v0, v140, 16, 1
	v_add3_u32 v0, v140, v0, s33
	s_mov_b64 s[4:5], 0x18800
	global_store_short_d16_hi v[244:245], v0, off offset:-2544
	v_bfe_u32 v0, v138, 16, 1
	v_lshl_add_u64 v[160:161], v[84:85], 0, s[4:5]
	v_add3_u32 v0, v138, v0, s33
	global_store_short_d16_hi v[246:247], v142, off offset:-2560
	v_readlane_b32 s98, v251, 38
	s_nop 1
	v_subrev_u32_e32 v248, s98, v160
	v_bfe_u32 v249, v248, 11, 4
	v_lshlrev_b32_e32 v244, 4, v249
	v_bfe_u32 v249, v248, 9, 2
	v_lshl_or_b32 v244, v249, 13, v244
	v_bfe_u32 v249, v248, 6, 3
	v_lshl_or_b32 v244, v249, 10, v244
	v_bfe_u32 v249, v248, 4, 2
	v_lshl_or_b32 v244, v249, 8, v244
	v_and_b32_e32 v249, 0x7ff0, v248
	v_sub_u32_e32 v244, v244, v249
	v_add_u32_e32 v244, 0xa00, v244
	v_ashrrev_i32_e32 v245, 31, v244
	v_lshl_add_u64 v[244:245], v[160:161], 0, v[244:245]
	global_store_short_d16_hi v[244:245], v0, off offset:1536
	global_store_short_d16_hi v[246:247], v143, off offset:-2544
	v_bfe_u32 v0, v83, 16, 1
	v_add3_u32 v0, v83, v0, s33
	s_mov_b64 s[4:5], 0x19000
	global_store_short_d16_hi v[246:247], v0, off offset:1552
	v_lshl_add_u64 v[88:89], v[84:85], 0, s[4:5]
	s_mov_b32 s4, 0x19000
	v_bfe_u32 v0, v141, 16, 1
	v_add_co_u32_e32 v156, vcc, s4, v84
	v_add3_u32 v0, v141, v0, s33
	s_nop 0
	v_addc_co_u32_e32 v157, vcc, 0, v85, vcc
	v_readlane_b32 s98, v251, 38
	s_nop 1
	v_subrev_u32_e32 v248, s98, v156
	v_bfe_u32 v249, v248, 11, 4
	v_lshlrev_b32_e32 v246, 4, v249
	v_bfe_u32 v249, v248, 9, 2
	v_lshl_or_b32 v246, v249, 13, v246
	v_bfe_u32 v249, v248, 6, 3
	v_lshl_or_b32 v246, v249, 10, v246
	v_bfe_u32 v249, v248, 4, 2
	v_lshl_or_b32 v246, v249, 8, v246
	v_and_b32_e32 v249, 0x7ff0, v248
	v_sub_u32_e32 v246, v246, v249
	v_add_u32_e32 v246, 0xa00, v246
	v_ashrrev_i32_e32 v247, 31, v246
	v_lshl_add_u64 v[246:247], v[156:157], 0, v[246:247]
	global_store_short_d16_hi v[246:247], v0, off offset:-2560
	v_bfe_u32 v0, v139, 16, 1
	v_add3_u32 v0, v139, v0, s33
	v_readlane_b32 s98, v251, 38
	s_nop 1
	v_subrev_u32_e32 v248, s98, v88
	v_bfe_u32 v249, v248, 11, 4
	v_lshlrev_b32_e32 v244, 4, v249
	v_bfe_u32 v249, v248, 9, 2
	v_lshl_or_b32 v244, v249, 13, v244
	v_bfe_u32 v249, v248, 6, 3
	v_lshl_or_b32 v244, v249, 10, v244
	v_bfe_u32 v249, v248, 4, 2
	v_lshl_or_b32 v244, v249, 8, v244
	v_and_b32_e32 v249, 0x7ff0, v248
	v_sub_u32_e32 v244, v244, v249
	v_add_u32_e32 v244, 0xa00, v244
	v_ashrrev_i32_e32 v245, 31, v244
	v_lshl_add_u64 v[244:245], v[88:89], 0, v[244:245]
	global_store_short_d16_hi v[244:245], v0, off offset:1536
	v_add_co_u32_e32 v88, vcc, s59, v84
	v_bfe_u32 v0, v86, 16, 1
	s_nop 0
	v_addc_co_u32_e32 v89, vcc, 0, v85, vcc
	v_add3_u32 v0, v86, v0, s33
	v_readlane_b32 s98, v251, 38
	s_nop 1
	v_subrev_u32_e32 v248, s98, v88
	v_bfe_u32 v249, v248, 11, 4
	v_lshlrev_b32_e32 v244, 4, v249
	v_bfe_u32 v249, v248, 9, 2
	v_lshl_or_b32 v244, v249, 13, v244
	v_bfe_u32 v249, v248, 6, 3
	v_lshl_or_b32 v244, v249, 10, v244
	v_bfe_u32 v249, v248, 4, 2
	v_lshl_or_b32 v244, v249, 8, v244
	v_and_b32_e32 v249, 0x7ff0, v248
	v_sub_u32_e32 v244, v244, v249
	v_add_u32_e32 v244, 0xa00, v244
	v_ashrrev_i32_e32 v245, 31, v244
	v_lshl_add_u64 v[244:245], v[88:89], 0, v[244:245]
	global_store_short_d16_hi v[244:245], v0, off offset:1536
	v_bfe_u32 v0, v137, 16, 1
	v_add3_u32 v0, v137, v0, s33
	s_mov_b64 s[4:5], 0x19800
	global_store_short_d16_hi v[246:247], v0, off offset:-2544
	v_bfe_u32 v0, v135, 16, 1
	v_lshl_add_u64 v[84:85], v[84:85], 0, s[4:5]
	v_add3_u32 v0, v135, v0, s33
	global_store_short_d16_hi v[244:245], v148, off offset:-2560
	v_readlane_b32 s98, v251, 38
	s_nop 1
	v_subrev_u32_e32 v248, s98, v84
	v_bfe_u32 v249, v248, 11, 4
	v_lshlrev_b32_e32 v246, 4, v249
	v_bfe_u32 v249, v248, 9, 2
	v_lshl_or_b32 v246, v249, 13, v246
	v_bfe_u32 v249, v248, 6, 3
	v_lshl_or_b32 v246, v249, 10, v246
	v_bfe_u32 v249, v248, 4, 2
	v_lshl_or_b32 v246, v249, 8, v246
	v_and_b32_e32 v249, 0x7ff0, v248
	v_sub_u32_e32 v246, v246, v249
	v_add_u32_e32 v246, 0xa00, v246
	v_ashrrev_i32_e32 v247, 31, v246
	v_lshl_add_u64 v[246:247], v[84:85], 0, v[246:247]
	global_store_short_d16_hi v[246:247], v0, off offset:1536
	global_store_short_d16_hi v[244:245], v149, off offset:-2544
	v_bfe_u32 v0, v87, 16, 1
	v_add3_u32 v0, v87, v0, s33
	s_mov_b64 s[4:5], 0
	global_store_short_d16_hi v[244:245], v0, off offset:1552

.LBB0_1084:
	v_or_b32_e32 v146, 16, v187
	s_nop 0
	v_or_b32_e32 v84, v184, v146
	v_cvt_f32_ubyte0_e32 v84, v84
	v_mul_f32_e32 v85, 0xbdd64706, v84
	v_cmp_gt_f32_e32 vcc, s26, v85
	v_mov_b32_e32 v142, v74
	v_mov_b32_e32 v143, v76
	v_cndmask_b32_e32 v85, 0, v218, vcc
	v_fmac_f32_e32 v85, 0xbdd64706, v84
	v_exp_f32_e32 v84, v85
	v_cndmask_b32_e32 v85, 0, v219, vcc
	v_mov_b32_e32 v134, v78
	v_mov_b32_e32 v135, v80
	v_ldexp_f32 v137, v84, v85
	v_mul_f32_e32 v87, v137, v189
	v_mul_f32_e32 v84, 0.15915494, v137
	v_mul_f32_e32 v89, 0.15915494, v87
	v_rndne_f32_e32 v84, v84
	v_rndne_f32_e32 v89, v89
	v_fmamk_f32 v86, v84, 0xc0c90000, v137
	v_fmac_f32_e32 v87, 0xc0c90000, v89
	v_fmac_f32_e32 v86, 0xbafdaa22, v84
	v_fmac_f32_e32 v87, 0xbafdaa22, v89
	v_mul_f32_e32 v86, 0.15915494, v86
	v_mul_f32_e32 v87, 0.15915494, v87
	v_sin_f32_e32 v88, v86
	v_cos_f32_e32 v89, v86
	v_cos_f32_e32 v140, v87
	v_sin_f32_e32 v138, v87
	v_mul_f32_e32 v85, v188, v137
	v_mul_f32_e32 v84, 0.15915494, v85
	v_pk_mul_f32 v[152:153], v[88:89], v[140:141] op_sel_hi:[1,0]
	v_rndne_f32_e32 v84, v84
	v_pk_fma_f32 v[154:155], v[88:89], v[138:139], v[152:153] op_sel:[0,0,1] op_sel_hi:[1,0,0] neg_lo:[1,0,0] neg_hi:[1,0,0]
	v_pk_fma_f32 v[152:153], v[88:89], v[138:139], v[152:153] op_sel:[0,0,1] op_sel_hi:[1,0,0]
	v_mov_b32_e32 v158, v154
	v_pk_mov_b32 v[176:177], v[152:153], v[154:155] op_sel:[1,0]
	v_mov_b32_e32 v159, v153
	v_mov_b32_e32 v136, v89
	v_pk_mul_f32 v[176:177], v[88:89], v[176:177] op_sel_hi:[0,1]
	v_fmac_f32_e32 v85, 0xc0c90000, v84
	v_pk_fma_f32 v[178:179], v[136:137], v[158:159], v[176:177] op_sel_hi:[0,1,1] neg_lo:[0,0,1] neg_hi:[0,0,1]
	v_pk_fma_f32 v[158:159], v[136:137], v[158:159], v[176:177] op_sel_hi:[0,1,1]
	v_fmac_f32_e32 v85, 0xbafdaa22, v84
	v_mov_b32_e32 v141, v178
	v_mov_b32_e32 v139, v159
	v_mul_f32_e32 v85, 0.15915494, v85
	v_pk_mul_f32 v[176:177], v[142:143], v[140:141]
	v_pk_mul_f32 v[142:143], v[142:143], v[138:139]
	v_sin_f32_e32 v84, v85
	v_cos_f32_e32 v86, v85
	v_mov_b32_e32 v179, v159
	v_pk_fma_f32 v[176:177], v[134:135], v[138:139], v[176:177]
	v_pk_fma_f32 v[142:143], v[134:135], v[140:141], v[142:143] neg_lo:[0,0,1] neg_hi:[0,0,1]
	v_mov_b32_e32 v134, v89
	v_mov_b32_e32 v135, v88
	v_mul_f32_e32 v180, v88, v159
	v_mul_f32_e32 v182, v89, v159
	v_pk_fma_f32 v[180:181], v[134:135], v[178:179], v[180:181] op_sel_hi:[1,1,0] neg_lo:[0,0,1] neg_hi:[0,0,1]
	v_pk_fma_f32 v[182:183], v[88:89], v[178:179], v[182:183] op_sel_hi:[1,1,0]
	v_mov_b32_e32 v150, v75
	v_mov_b32_e32 v151, v77
	v_mov_b32_e32 v155, v180
	v_pk_mov_b32 v[188:189], v[152:153], v[182:183] op_sel:[1,0]
	v_mov_b32_e32 v144, v79
	v_mov_b32_e32 v145, v81
	v_pk_mul_f32 v[190:191], v[150:151], v[188:189]
	v_pk_mul_f32 v[150:151], v[150:151], v[154:155]
	v_mov_b32_e32 v139, v153
	v_pk_fma_f32 v[190:191], v[144:145], v[154:155], v[190:191] neg_lo:[0,0,1] neg_hi:[0,0,1]
	v_pk_fma_f32 v[150:151], v[144:145], v[188:189], v[150:151]
	v_mov_b32_e32 v141, v154
	v_pk_mul_f32 v[144:145], v[84:85], v[138:139] op_sel_hi:[0,1]
	v_pk_mul_f32 v[152:153], v[86:87], v[138:139] op_sel_hi:[0,1]
	v_pk_fma_f32 v[144:145], v[86:87], v[140:141], v[144:145] op_sel_hi:[0,1,1]
	v_pk_fma_f32 v[152:153], v[84:85], v[140:141], v[152:153] op_sel_hi:[0,1,1] neg_lo:[0,0,1] neg_hi:[0,0,1]
	v_mul_f32_e32 v85, v74, v152
	v_pk_mul_f32 v[154:155], v[74:75], v[144:145]
	v_mul_f32_e32 v74, v75, v153
	v_fma_f32 v85, v78, v144, -v85
	v_fma_f32 v74, v79, v145, -v74
	v_mul_f32_e32 v85, v85, v124
	v_mul_f32_e32 v87, v74, v125
	v_pk_mov_b32 v[74:75], v[158:159], v[182:183] op_sel:[1,0]
	v_pk_fma_f32 v[154:155], v[78:79], v[152:153], v[154:155]
	v_mov_b32_e32 v179, v180
	v_pk_mul_f32 v[78:79], v[84:85], v[74:75] op_sel_hi:[0,1]
	v_pk_fma_f32 v[78:79], v[86:87], v[178:179], v[78:79] op_sel_hi:[0,1,1]
	v_pk_mul_f32 v[74:75], v[86:87], v[74:75] op_sel_hi:[0,1]
	v_pk_fma_f32 v[74:75], v[84:85], v[178:179], v[74:75] op_sel_hi:[0,1,1] neg_lo:[0,0,1] neg_hi:[0,0,1]
	v_pk_mul_f32 v[144:145], v[76:77], v[78:79]
	v_mul_f32_e32 v139, v76, v74
	v_pk_fma_f32 v[152:153], v[80:81], v[74:75], v[144:145]
	v_mul_f32_e32 v74, v77, v75
	v_fma_f32 v139, v80, v78, -v139
	v_fma_f32 v74, v81, v79, -v74
	v_mul_f32_e32 v139, v139, v120
	v_mul_f32_e32 v74, v74, v121
	v_bfe_u32 v75, v85, 16, 1
	v_bfe_u32 v76, v87, 16, 1
	v_bfe_u32 v77, v139, 16, 1
	v_bfe_u32 v79, v74, 16, 1
	v_pk_mul_f32 v[124:125], v[154:155], v[124:125]
	v_pk_mul_f32 v[142:143], v[142:143], v[122:123]
	v_pk_mul_f32 v[122:123], v[176:177], v[122:123]
	v_pk_mul_f32 v[144:145], v[190:191], v[118:119]
	v_pk_mul_f32 v[118:119], v[150:151], v[118:119]
	v_pk_mul_f32 v[80:81], v[152:153], v[120:121]
	s_mov_b64 s[2:3], -1
	s_and_b64 vcc, exec, s[0:1]
	v_add_lshl_u32 v78, v184, v187, 1
	v_add3_u32 v85, v85, v75, s33
	v_add3_u32 v87, v87, v76, s33
	v_add3_u32 v120, v139, v77, s33
	v_add3_u32 v121, v74, v79, s33
	s_cbranch_vccnz .LBB0_1086
	v_mov_b32_e32 v79, v1
	v_lshl_add_u64 v[74:75], v[106:107], 0, v[78:79]
	v_lshlrev_b64 v[76:77], 11, v[116:117]
	v_bfe_u32 v79, v142, 16, 1
	v_lshl_add_u64 v[76:77], v[74:75], 0, v[76:77]
	v_add3_u32 v79, v142, v79, s33
	v_readlane_b32 s98, v251, 38
	s_nop 1
	v_subrev_u32_e32 v248, s98, v76
	v_bfe_u32 v249, v248, 11, 4
	v_lshlrev_b32_e32 v244, 4, v249
	v_bfe_u32 v249, v248, 9, 2
	v_lshl_or_b32 v244, v249, 13, v244
	v_bfe_u32 v249, v248, 6, 3
	v_lshl_or_b32 v244, v249, 10, v244
	v_bfe_u32 v249, v248, 4, 2
	v_lshl_or_b32 v244, v249, 8, v244
	v_and_b32_e32 v249, 0x7ff0, v248
	v_sub_u32_e32 v244, v244, v249
	v_add_u32_e32 v244, 0xa00, v244
	v_ashrrev_i32_e32 v245, 31, v244
	v_lshl_add_u64 v[244:245], v[76:77], 0, v[244:245]
	global_store_short_d16_hi v[244:245], v79, off offset:-2048
	v_bfe_u32 v79, v122, 16, 1
	v_add3_u32 v79, v122, v79, s33
	global_store_short_d16_hi v[244:245], v79, off offset:2048
	v_add_co_u32_e32 v76, vcc, s56, v76
	v_bfe_u32 v79, v124, 16, 1
	s_nop 0
	v_addc_co_u32_e32 v77, vcc, 0, v77, vcc
	v_add3_u32 v79, v124, v79, s33
	v_readlane_b32 s98, v251, 38
	s_nop 1
	v_subrev_u32_e32 v248, s98, v76
	v_bfe_u32 v249, v248, 11, 4
	v_lshlrev_b32_e32 v244, 4, v249
	v_bfe_u32 v249, v248, 9, 2
	v_lshl_or_b32 v244, v249, 13, v244
	v_bfe_u32 v249, v248, 6, 3
	v_lshl_or_b32 v244, v249, 10, v244
	v_bfe_u32 v249, v248, 4, 2
	v_lshl_or_b32 v244, v249, 8, v244
	v_and_b32_e32 v249, 0x7ff0, v248
	v_sub_u32_e32 v244, v244, v249
	v_add_u32_e32 v244, 0xa00, v244
	v_ashrrev_i32_e32 v245, 31, v244
	v_lshl_add_u64 v[244:245], v[76:77], 0, v[244:245]
	global_store_short_d16_hi v[244:245], v85, off offset:-2048
	global_store_short_d16_hi v[244:245], v79, off offset:2048
	v_lshlrev_b64 v[76:77], 11, v[130:131]
	v_bfe_u32 v79, v144, 16, 1
	v_lshl_add_u64 v[76:77], v[74:75], 0, v[76:77]
	v_add3_u32 v79, v144, v79, s33
	v_readlane_b32 s98, v251, 38
	s_nop 1
	v_subrev_u32_e32 v248, s98, v76
	v_bfe_u32 v249, v248, 11, 4
	v_lshlrev_b32_e32 v244, 4, v249
	v_bfe_u32 v249, v248, 9, 2
	v_lshl_or_b32 v244, v249, 13, v244
	v_bfe_u32 v249, v248, 6, 3
	v_lshl_or_b32 v244, v249, 10, v244
	v_bfe_u32 v249, v248, 4, 2
	v_lshl_or_b32 v244, v249, 8, v244
	v_and_b32_e32 v249, 0x7ff0, v248
	v_sub_u32_e32 v244, v244, v249
	v_add_u32_e32 v244, 0xa00, v244
	v_ashrrev_i32_e32 v245, 31, v244
	v_lshl_add_u64 v[244:245], v[76:77], 0, v[244:245]
	global_store_short_d16_hi v[244:245], v79, off offset:-2048
	v_bfe_u32 v79, v118, 16, 1
	v_add3_u32 v79, v118, v79, s33
	global_store_short_d16_hi v[244:245], v79, off offset:2048
	v_add_co_u32_e32 v76, vcc, s56, v76
	v_bfe_u32 v79, v125, 16, 1
	s_nop 0
	v_addc_co_u32_e32 v77, vcc, 0, v77, vcc
	v_add3_u32 v79, v125, v79, s33
	v_readlane_b32 s98, v251, 38
	s_nop 1
	v_subrev_u32_e32 v248, s98, v76
	v_bfe_u32 v249, v248, 11, 4
	v_lshlrev_b32_e32 v244, 4, v249
	v_bfe_u32 v249, v248, 9, 2
	v_lshl_or_b32 v244, v249, 13, v244
	v_bfe_u32 v249, v248, 6, 3
	v_lshl_or_b32 v244, v249, 10, v244
	v_bfe_u32 v249, v248, 4, 2
	v_lshl_or_b32 v244, v249, 8, v244
	v_and_b32_e32 v249, 0x7ff0, v248
	v_sub_u32_e32 v244, v244, v249
	v_add_u32_e32 v244, 0xa00, v244
	v_ashrrev_i32_e32 v245, 31, v244
	v_lshl_add_u64 v[244:245], v[76:77], 0, v[244:245]
	global_store_short_d16_hi v[244:245], v87, off offset:-2048
	global_store_short_d16_hi v[244:245], v79, off offset:2048
	v_lshlrev_b64 v[76:77], 11, v[126:127]
	v_bfe_u32 v79, v143, 16, 1
	v_lshl_add_u64 v[76:77], v[74:75], 0, v[76:77]
	v_add3_u32 v79, v143, v79, s33
	v_readlane_b32 s98, v251, 38
	s_nop 1
	v_subrev_u32_e32 v248, s98, v76
	v_bfe_u32 v249, v248, 11, 4
	v_lshlrev_b32_e32 v244, 4, v249
	v_bfe_u32 v249, v248, 9, 2
	v_lshl_or_b32 v244, v249, 13, v244
	v_bfe_u32 v249, v248, 6, 3
	v_lshl_or_b32 v244, v249, 10, v244
	v_bfe_u32 v249, v248, 4, 2
	v_lshl_or_b32 v244, v249, 8, v244
	v_and_b32_e32 v249, 0x7ff0, v248
	v_sub_u32_e32 v244, v244, v249
	v_add_u32_e32 v244, 0xa00, v244
	v_ashrrev_i32_e32 v245, 31, v244
	v_lshl_add_u64 v[244:245], v[76:77], 0, v[244:245]
	global_store_short_d16_hi v[244:245], v79, off offset:-2048
	v_bfe_u32 v79, v123, 16, 1
	v_add3_u32 v79, v123, v79, s33
	global_store_short_d16_hi v[244:245], v79, off offset:2048
	v_add_co_u32_e32 v76, vcc, s56, v76
	v_bfe_u32 v79, v80, 16, 1
	s_nop 0
	v_addc_co_u32_e32 v77, vcc, 0, v77, vcc
	v_add3_u32 v79, v80, v79, s33
	v_readlane_b32 s98, v251, 38
	s_nop 1
	v_subrev_u32_e32 v248, s98, v76
	v_bfe_u32 v249, v248, 11, 4
	v_lshlrev_b32_e32 v244, 4, v249
	v_bfe_u32 v249, v248, 9, 2
	v_lshl_or_b32 v244, v249, 13, v244
	v_bfe_u32 v249, v248, 6, 3
	v_lshl_or_b32 v244, v249, 10, v244
	v_bfe_u32 v249, v248, 4, 2
	v_lshl_or_b32 v244, v249, 8, v244
	v_and_b32_e32 v249, 0x7ff0, v248
	v_sub_u32_e32 v244, v244, v249
	v_add_u32_e32 v244, 0xa00, v244
	v_ashrrev_i32_e32 v245, 31, v244
	v_lshl_add_u64 v[244:245], v[76:77], 0, v[244:245]
	global_store_short_d16_hi v[244:245], v120, off offset:-2048
	global_store_short_d16_hi v[244:245], v79, off offset:2048
	v_lshlrev_b64 v[76:77], 11, v[112:113]
	v_lshl_add_u64 v[74:75], v[74:75], 0, v[76:77]
	v_bfe_u32 v76, v145, 16, 1
	v_add3_u32 v76, v145, v76, s33
	v_readlane_b32 s98, v251, 38
	s_nop 1
	v_subrev_u32_e32 v248, s98, v74
	v_bfe_u32 v249, v248, 11, 4
	v_lshlrev_b32_e32 v244, 4, v249
	v_bfe_u32 v249, v248, 9, 2
	v_lshl_or_b32 v244, v249, 13, v244
	v_bfe_u32 v249, v248, 6, 3
	v_lshl_or_b32 v244, v249, 10, v244
	v_bfe_u32 v249, v248, 4, 2
	v_lshl_or_b32 v244, v249, 8, v244
	v_and_b32_e32 v249, 0x7ff0, v248
	v_sub_u32_e32 v244, v244, v249
	v_add_u32_e32 v244, 0xa00, v244
	v_ashrrev_i32_e32 v245, 31, v244
	v_lshl_add_u64 v[244:245], v[74:75], 0, v[244:245]
	global_store_short_d16_hi v[244:245], v76, off offset:-2048
	v_bfe_u32 v76, v119, 16, 1
	v_add3_u32 v76, v119, v76, s33
	global_store_short_d16_hi v[244:245], v76, off offset:2048
	v_add_co_u32_e32 v74, vcc, 0x1000000, v74
	v_bfe_u32 v76, v81, 16, 1
	s_nop 0
	v_addc_co_u32_e32 v75, vcc, 0, v75, vcc
	v_add3_u32 v76, v81, v76, s33
	s_mov_b64 s[2:3], 0
	v_readlane_b32 s98, v251, 38
	s_nop 1
	v_subrev_u32_e32 v248, s98, v74
	v_bfe_u32 v249, v248, 11, 4
	v_lshlrev_b32_e32 v244, 4, v249
	v_bfe_u32 v249, v248, 9, 2
	v_lshl_or_b32 v244, v249, 13, v244
	v_bfe_u32 v249, v248, 6, 3
	v_lshl_or_b32 v244, v249, 10, v244
	v_bfe_u32 v249, v248, 4, 2
	v_lshl_or_b32 v244, v249, 8, v244
	v_and_b32_e32 v249, 0x7ff0, v248
	v_sub_u32_e32 v244, v244, v249
	v_add_u32_e32 v244, 0xa00, v244
	v_ashrrev_i32_e32 v245, 31, v244
	v_lshl_add_u64 v[244:245], v[74:75], 0, v[244:245]
	global_store_short_d16_hi v[244:245], v121, off offset:-2048
	global_store_short_d16_hi v[244:245], v76, off offset:2048

.LBB0_1088:
	v_mul_f32_e32 v79, 0x41800000, v137
	v_mul_f32_e32 v80, 0.15915494, v79
	v_rndne_f32_e32 v80, v80
	v_fmac_f32_e32 v79, 0xc0c90000, v80
	v_fmac_f32_e32 v79, 0xbafdaa22, v80
	v_mul_f32_e32 v79, 0.15915494, v79
	v_sin_f32_e32 v112, v79
	v_cos_f32_e32 v113, v79
	v_mov_b32_e32 v141, v140
	v_mov_b32_e32 v139, v138
	v_mov_b32_e32 v80, v88
	v_pk_mul_f32 v[120:121], v[112:113], v[140:141]
	v_mov_b32_e32 v81, v88
	v_pk_fma_f32 v[118:119], v[112:113], v[138:139], v[120:121] op_sel:[0,0,1] op_sel_hi:[1,1,0] neg_lo:[1,0,0] neg_hi:[1,0,0]
	v_pk_fma_f32 v[122:123], v[112:113], v[138:139], v[120:121] op_sel:[0,0,1] op_sel_hi:[1,1,0]
	v_mov_b32_e32 v120, v118
	v_mov_b32_e32 v121, v123
	v_pk_mul_f32 v[140:141], v[80:81], v[120:121]
	v_mov_b32_e32 v126, v66
	v_pk_fma_f32 v[142:143], v[136:137], v[120:121], v[140:141] op_sel:[0,0,1] op_sel_hi:[0,1,0] neg_lo:[0,0,1] neg_hi:[0,0,1]
	v_pk_fma_f32 v[140:141], v[136:137], v[120:121], v[140:141] op_sel:[0,0,1] op_sel_hi:[0,1,0]
	v_pk_mov_b32 v[150:151], v[140:141], v[142:143] op_sel:[1,0]
	v_mov_b32_e32 v144, v142
	v_mov_b32_e32 v145, v141
	v_pk_mul_f32 v[150:151], v[80:81], v[150:151]
	v_mov_b32_e32 v127, v69
	v_pk_fma_f32 v[152:153], v[136:137], v[144:145], v[150:151] op_sel_hi:[0,1,1] neg_lo:[0,0,1] neg_hi:[0,0,1]
	v_pk_fma_f32 v[144:145], v[136:137], v[144:145], v[150:151] op_sel_hi:[0,1,1]
	v_mov_b32_e32 v153, v145
	v_mul_f32_e32 v140, v135, v145
	v_pk_fma_f32 v[150:151], v[134:135], v[152:153], v[140:141] op_sel_hi:[1,1,0] neg_lo:[0,0,1] neg_hi:[0,0,1]
	v_mul_f32_e32 v140, v89, v145
	v_pk_fma_f32 v[154:155], v[88:89], v[152:153], v[140:141] op_sel_hi:[1,1,0]
	v_mov_b32_e32 v158, v118
	v_mov_b32_e32 v159, v150
	v_pk_mov_b32 v[178:179], v[122:123], v[154:155] op_sel:[1,0]
	v_mov_b32_e32 v124, v70
	v_mov_b32_e32 v125, v73
	v_pk_mul_f32 v[176:177], v[126:127], v[158:159]
	v_pk_mul_f32 v[126:127], v[126:127], v[178:179]
	v_mov_b32_e32 v138, v67
	v_mov_b32_e32 v139, v68
	v_pk_fma_f32 v[176:177], v[124:125], v[178:179], v[176:177]
	v_pk_fma_f32 v[126:127], v[124:125], v[158:159], v[126:127] neg_lo:[0,0,1] neg_hi:[0,0,1]
	v_mov_b32_e32 v143, v152
	v_mov_b32_e32 v124, v141
	v_mov_b32_e32 v125, v145
	v_mov_b32_e32 v87, v86
	v_mov_b32_e32 v85, v84
	v_mov_b32_e32 v130, v71
	v_mov_b32_e32 v131, v72
	v_pk_mul_f32 v[158:159], v[138:139], v[124:125]
	v_pk_mul_f32 v[138:139], v[138:139], v[142:143]
	v_mov_b32_e32 v140, v123
	v_pk_fma_f32 v[158:159], v[130:131], v[142:143], v[158:159] neg_lo:[0,0,1] neg_hi:[0,0,1]
	v_pk_fma_f32 v[130:131], v[130:131], v[124:125], v[138:139]
	v_mov_b32_e32 v124, v118
	v_mov_b32_e32 v125, v142
	v_pk_mul_f32 v[138:139], v[84:85], v[140:141]
	v_pk_mul_f32 v[140:141], v[86:87], v[140:141]
	v_pk_fma_f32 v[138:139], v[86:87], v[124:125], v[138:139]
	v_pk_fma_f32 v[124:125], v[84:85], v[124:125], v[140:141] neg_lo:[0,0,1] neg_hi:[0,0,1]
	v_pk_mul_f32 v[140:141], v[66:67], v[138:139]
	v_mul_f32_e32 v79, v66, v124
	v_mul_f32_e32 v66, v67, v125
	v_fma_f32 v66, v71, v139, -v66
	v_fma_f32 v79, v70, v138, -v79
	v_pk_fma_f32 v[140:141], v[70:71], v[124:125], v[140:141]
	v_mul_f32_e32 v137, v66, v109
	v_pk_mov_b32 v[66:67], v[144:145], v[154:155] op_sel:[1,0]
	v_mul_f32_e32 v79, v79, v108
	v_pk_mul_f32 v[70:71], v[140:141], v[108:109]
	v_pk_mul_f32 v[108:109], v[130:131], v[132:133]
	v_mov_b32_e32 v153, v150
	v_pk_mul_f32 v[130:131], v[84:85], v[66:67]
	v_pk_mul_f32 v[66:67], v[86:87], v[66:67]
	v_pk_mul_f32 v[124:125], v[158:159], v[132:133]
	v_pk_fma_f32 v[66:67], v[84:85], v[152:153], v[66:67] neg_lo:[0,0,1] neg_hi:[0,0,1]
	v_pk_fma_f32 v[130:131], v[86:87], v[152:153], v[130:131]
	v_mul_f32_e32 v132, v68, v66
	v_fma_f32 v132, v72, v130, -v132
	v_mul_f32_e32 v138, v132, v128
	v_pk_mul_f32 v[132:133], v[68:69], v[130:131]
	v_bfe_u32 v68, v137, 16, 1
	v_pk_fma_f32 v[132:133], v[72:73], v[66:67], v[132:133]
	v_mul_f32_e32 v66, v69, v67
	v_fma_f32 v66, v73, v131, -v66
	v_mul_f32_e32 v66, v66, v129
	v_bfe_u32 v67, v79, 16, 1
	v_bfe_u32 v69, v138, 16, 1
	v_bfe_u32 v131, v66, 16, 1
	v_pk_mul_f32 v[126:127], v[126:127], v[110:111]
	v_pk_mul_f32 v[110:111], v[176:177], v[110:111]
	v_pk_mul_f32 v[72:73], v[132:133], v[128:129]
	s_mov_b64 s[2:3], -1
	s_and_b64 vcc, exec, s[0:1]
	v_add3_u32 v128, v79, v67, s33
	v_add3_u32 v129, v137, v68, s33
	v_add3_u32 v130, v138, v69, s33
	v_add3_u32 v131, v66, v131, s33
	s_cbranch_vccnz .LBB0_1090
	v_mov_b32_e32 v79, v1
	v_lshl_add_u64 v[66:67], v[106:107], 0, v[78:79]
	v_lshlrev_b64 v[68:69], 11, v[116:117]
	v_lshl_add_u64 v[66:67], v[66:67], 0, v[68:69]
	s_mov_b64 s[2:3], 0x8000
	v_bfe_u32 v79, v126, 16, 1
	v_lshl_add_u64 v[68:69], v[66:67], 0, s[2:3]
	v_add3_u32 v79, v126, v79, s33
	v_readlane_b32 s98, v251, 38
	s_nop 1
	v_subrev_u32_e32 v248, s98, v68
	v_bfe_u32 v249, v248, 11, 4
	v_lshlrev_b32_e32 v244, 4, v249
	v_bfe_u32 v249, v248, 9, 2
	v_lshl_or_b32 v244, v249, 13, v244
	v_bfe_u32 v249, v248, 6, 3
	v_lshl_or_b32 v244, v249, 10, v244
	v_bfe_u32 v249, v248, 4, 2
	v_lshl_or_b32 v244, v249, 8, v244
	v_and_b32_e32 v249, 0x7ff0, v248
	v_sub_u32_e32 v244, v244, v249
	v_add_u32_e32 v244, 0xa00, v244
	v_ashrrev_i32_e32 v245, 31, v244
	v_lshl_add_u64 v[244:245], v[68:69], 0, v[244:245]
	global_store_short_d16_hi v[244:245], v79, off offset:-2048
	v_bfe_u32 v79, v110, 16, 1
	v_add3_u32 v79, v110, v79, s33
	s_mov_b32 s2, 0x1008000
	global_store_short_d16_hi v[244:245], v79, off offset:2048
	v_add_co_u32_e32 v68, vcc, s2, v66
	v_bfe_u32 v79, v70, 16, 1
	s_nop 0
	v_addc_co_u32_e32 v69, vcc, 0, v67, vcc
	v_add3_u32 v79, v70, v79, s33
	v_readlane_b32 s98, v251, 38
	s_nop 1
	v_subrev_u32_e32 v248, s98, v68
	v_bfe_u32 v249, v248, 11, 4
	v_lshlrev_b32_e32 v244, 4, v249
	v_bfe_u32 v249, v248, 9, 2
	v_lshl_or_b32 v244, v249, 13, v244
	v_bfe_u32 v249, v248, 6, 3
	v_lshl_or_b32 v244, v249, 10, v244
	v_bfe_u32 v249, v248, 4, 2
	v_lshl_or_b32 v244, v249, 8, v244
	v_and_b32_e32 v249, 0x7ff0, v248
	v_sub_u32_e32 v244, v244, v249
	v_add_u32_e32 v244, 0xa00, v244
	v_ashrrev_i32_e32 v245, 31, v244
	v_lshl_add_u64 v[244:245], v[68:69], 0, v[244:245]
	global_store_short_d16_hi v[244:245], v79, off offset:2048
	s_mov_b64 s[2:3], 0x8800
	v_bfe_u32 v79, v124, 16, 1
	v_lshl_add_u64 v[132:133], v[66:67], 0, s[2:3]
	v_add3_u32 v79, v124, v79, s33
	v_readlane_b32 s98, v251, 38
	s_nop 1
	v_subrev_u32_e32 v248, s98, v132
	v_bfe_u32 v249, v248, 11, 4
	v_lshlrev_b32_e32 v246, 4, v249
	v_bfe_u32 v249, v248, 9, 2
	v_lshl_or_b32 v246, v249, 13, v246
	v_bfe_u32 v249, v248, 6, 3
	v_lshl_or_b32 v246, v249, 10, v246
	v_bfe_u32 v249, v248, 4, 2
	v_lshl_or_b32 v246, v249, 8, v246
	v_and_b32_e32 v249, 0x7ff0, v248
	v_sub_u32_e32 v246, v246, v249
	v_add_u32_e32 v246, 0xa00, v246
	v_ashrrev_i32_e32 v247, 31, v246
	v_lshl_add_u64 v[246:247], v[132:133], 0, v[246:247]
	global_store_short_d16_hi v[246:247], v79, off offset:-2048
	v_bfe_u32 v79, v108, 16, 1
	v_add3_u32 v79, v108, v79, s33
	global_store_short_d16_hi v[244:245], v128, off offset:-2048
	global_store_short_d16_hi v[246:247], v79, off offset:2048
	global_store_short_d16_hi v[244:245], v129, off offset:-2032
	v_bfe_u32 v79, v71, 16, 1
	v_add3_u32 v79, v71, v79, s33
	global_store_short_d16_hi v[244:245], v79, off offset:2064
	s_mov_b64 s[2:3], 0x9000
	v_bfe_u32 v79, v125, 16, 1
	v_lshl_add_u64 v[68:69], v[66:67], 0, s[2:3]
	v_add3_u32 v79, v125, v79, s33
	v_readlane_b32 s98, v251, 38
	s_nop 1
	v_subrev_u32_e32 v248, s98, v68
	v_bfe_u32 v249, v248, 11, 4
	v_lshlrev_b32_e32 v244, 4, v249
	v_bfe_u32 v249, v248, 9, 2
	v_lshl_or_b32 v244, v249, 13, v244
	v_bfe_u32 v249, v248, 6, 3
	v_lshl_or_b32 v244, v249, 10, v244
	v_bfe_u32 v249, v248, 4, 2
	v_lshl_or_b32 v244, v249, 8, v244
	v_and_b32_e32 v249, 0x7ff0, v248
	v_sub_u32_e32 v244, v244, v249
	v_add_u32_e32 v244, 0xa00, v244
	v_ashrrev_i32_e32 v245, 31, v244
	v_lshl_add_u64 v[244:245], v[68:69], 0, v[244:245]
	global_store_short_d16_hi v[244:245], v79, off offset:-2048
	v_bfe_u32 v79, v109, 16, 1
	v_add3_u32 v79, v109, v79, s33
	global_store_short_d16_hi v[244:245], v79, off offset:2048
	v_add_co_u32_e32 v68, vcc, s57, v66
	v_bfe_u32 v79, v72, 16, 1
	s_nop 0
	v_addc_co_u32_e32 v69, vcc, 0, v67, vcc
	v_add3_u32 v79, v72, v79, s33
	v_readlane_b32 s98, v251, 38
	s_nop 1
	v_subrev_u32_e32 v248, s98, v68
	v_bfe_u32 v249, v248, 11, 4
	v_lshlrev_b32_e32 v244, 4, v249
	v_bfe_u32 v249, v248, 9, 2
	v_lshl_or_b32 v244, v249, 13, v244
	v_bfe_u32 v249, v248, 6, 3
	v_lshl_or_b32 v244, v249, 10, v244
	v_bfe_u32 v249, v248, 4, 2
	v_lshl_or_b32 v244, v249, 8, v244
	v_and_b32_e32 v249, 0x7ff0, v248
	v_sub_u32_e32 v244, v244, v249
	v_add_u32_e32 v244, 0xa00, v244
	v_ashrrev_i32_e32 v245, 31, v244
	v_lshl_add_u64 v[244:245], v[68:69], 0, v[244:245]
	global_store_short_d16_hi v[244:245], v79, off offset:2048
	s_mov_b64 s[2:3], 0x9800
	v_bfe_u32 v79, v127, 16, 1
	v_lshl_add_u64 v[66:67], v[66:67], 0, s[2:3]
	v_add3_u32 v79, v127, v79, s33
	v_readlane_b32 s98, v251, 38
	s_nop 1
	v_subrev_u32_e32 v248, s98, v66
	v_bfe_u32 v249, v248, 11, 4
	v_lshlrev_b32_e32 v246, 4, v249
	v_bfe_u32 v249, v248, 9, 2
	v_lshl_or_b32 v246, v249, 13, v246
	v_bfe_u32 v249, v248, 6, 3
	v_lshl_or_b32 v246, v249, 10, v246
	v_bfe_u32 v249, v248, 4, 2
	v_lshl_or_b32 v246, v249, 8, v246
	v_and_b32_e32 v249, 0x7ff0, v248
	v_sub_u32_e32 v246, v246, v249
	v_add_u32_e32 v246, 0xa00, v246
	v_ashrrev_i32_e32 v247, 31, v246
	v_lshl_add_u64 v[246:247], v[66:67], 0, v[246:247]
	global_store_short_d16_hi v[246:247], v79, off offset:-2048
	v_bfe_u32 v79, v111, 16, 1
	v_add3_u32 v79, v111, v79, s33
	global_store_short_d16_hi v[244:245], v130, off offset:-2048
	global_store_short_d16_hi v[246:247], v79, off offset:2048
	global_store_short_d16_hi v[244:245], v131, off offset:-2032
	v_bfe_u32 v66, v73, 16, 1
	v_add3_u32 v66, v73, v66, s33
	s_mov_b64 s[2:3], 0
	global_store_short_d16_hi v[244:245], v66, off offset:2064

.LBB0_1092:
	v_pk_mov_b32 v[70:71], v[122:123], v[118:119] op_sel:[1,0]
	v_mov_b32_e32 v137, v89
	v_pk_mul_f32 v[72:73], v[112:113], v[70:71] op_sel_hi:[0,1]
	v_pk_fma_f32 v[70:71], v[112:113], v[120:121], v[72:73] op_sel:[1,0,0] neg_lo:[0,0,1] neg_hi:[0,0,1]
	v_pk_fma_f32 v[108:109], v[112:113], v[120:121], v[72:73] op_sel:[1,0,0]
	v_mov_b32_e32 v72, v70
	v_mov_b32_e32 v73, v109
	v_pk_mul_f32 v[124:125], v[80:81], v[72:73]
	v_mov_b32_e32 v118, v58
	v_pk_fma_f32 v[126:127], v[136:137], v[72:73], v[124:125] op_sel:[0,0,1] op_sel_hi:[1,1,0] neg_lo:[0,0,1] neg_hi:[0,0,1]
	v_pk_fma_f32 v[124:125], v[136:137], v[72:73], v[124:125] op_sel:[0,0,1] op_sel_hi:[1,1,0]
	v_mov_b32_e32 v128, v126
	v_pk_mov_b32 v[130:131], v[124:125], v[126:127] op_sel:[1,0]
	v_mov_b32_e32 v129, v125
	v_pk_mul_f32 v[130:131], v[80:81], v[130:131]
	v_mov_b32_e32 v119, v61
	v_pk_fma_f32 v[132:133], v[136:137], v[128:129], v[130:131] neg_lo:[0,0,1] neg_hi:[0,0,1]
	v_pk_fma_f32 v[128:129], v[136:137], v[128:129], v[130:131]
	v_mov_b32_e32 v140, v70
	v_mov_b32_e32 v133, v129
	v_mul_f32_e32 v124, v135, v129
	v_pk_fma_f32 v[130:131], v[134:135], v[132:133], v[124:125] op_sel_hi:[1,1,0] neg_lo:[0,0,1] neg_hi:[0,0,1]
	v_mul_f32_e32 v124, v89, v129
	v_pk_fma_f32 v[138:139], v[88:89], v[132:133], v[124:125] op_sel_hi:[1,1,0]
	v_mov_b32_e32 v141, v130
	v_pk_mov_b32 v[144:145], v[108:109], v[138:139] op_sel:[1,0]
	v_mov_b32_e32 v110, v62
	v_mov_b32_e32 v111, v65
	v_pk_mul_f32 v[142:143], v[118:119], v[140:141]
	v_pk_mul_f32 v[118:119], v[118:119], v[144:145]
	v_mov_b32_e32 v122, v59
	v_mov_b32_e32 v123, v60
	v_pk_fma_f32 v[142:143], v[110:111], v[144:145], v[142:143]
	v_pk_fma_f32 v[118:119], v[110:111], v[140:141], v[118:119] neg_lo:[0,0,1] neg_hi:[0,0,1]
	v_mov_b32_e32 v127, v132
	v_mov_b32_e32 v110, v125
	v_mov_b32_e32 v111, v129
	v_mov_b32_e32 v120, v63
	v_mov_b32_e32 v121, v64
	v_pk_mul_f32 v[140:141], v[122:123], v[110:111]
	v_pk_mul_f32 v[122:123], v[122:123], v[126:127]
	v_mov_b32_e32 v124, v109
	v_pk_fma_f32 v[140:141], v[120:121], v[126:127], v[140:141] neg_lo:[0,0,1] neg_hi:[0,0,1]
	v_pk_fma_f32 v[120:121], v[120:121], v[110:111], v[122:123]
	v_mov_b32_e32 v110, v70
	v_mov_b32_e32 v111, v126
	v_pk_mul_f32 v[122:123], v[84:85], v[124:125]
	v_pk_mul_f32 v[124:125], v[86:87], v[124:125]
	v_pk_fma_f32 v[122:123], v[86:87], v[110:111], v[122:123]
	v_pk_fma_f32 v[110:111], v[84:85], v[110:111], v[124:125] neg_lo:[0,0,1] neg_hi:[0,0,1]
	v_pk_mul_f32 v[124:125], v[58:59], v[122:123]
	v_mul_f32_e32 v79, v58, v110
	v_mul_f32_e32 v58, v59, v111
	v_fma_f32 v58, v63, v123, -v58
	v_fma_f32 v79, v62, v122, -v79
	v_pk_fma_f32 v[124:125], v[62:63], v[110:111], v[124:125]
	v_mul_f32_e32 v126, v58, v99
	v_pk_mov_b32 v[58:59], v[128:129], v[138:139] op_sel:[1,0]
	v_mul_f32_e32 v79, v79, v98
	v_pk_mul_f32 v[62:63], v[124:125], v[98:99]
	v_pk_mul_f32 v[110:111], v[140:141], v[104:105]
	v_pk_mul_f32 v[98:99], v[120:121], v[104:105]
	v_mov_b32_e32 v133, v130
	v_pk_mul_f32 v[104:105], v[84:85], v[58:59]
	v_pk_mul_f32 v[58:59], v[86:87], v[58:59]
	v_pk_fma_f32 v[120:121], v[86:87], v[132:133], v[104:105]
	v_pk_fma_f32 v[58:59], v[84:85], v[132:133], v[58:59] neg_lo:[0,0,1] neg_hi:[0,0,1]
	s_mov_b64 s[2:3], -1
	v_mul_f32_e32 v104, v60, v58
	v_fma_f32 v104, v64, v120, -v104
	v_mul_f32_e32 v124, v104, v102
	v_pk_mul_f32 v[104:105], v[60:61], v[120:121]
	v_bfe_u32 v60, v126, 16, 1
	v_pk_fma_f32 v[122:123], v[64:65], v[58:59], v[104:105]
	v_mul_f32_e32 v58, v61, v59
	v_fma_f32 v58, v65, v121, -v58
	v_mul_f32_e32 v58, v58, v103
	v_pk_mul_f32 v[104:105], v[118:119], v[100:101]
	v_bfe_u32 v59, v79, 16, 1
	v_bfe_u32 v61, v124, 16, 1
	v_bfe_u32 v119, v58, 16, 1
	v_pk_mul_f32 v[100:101], v[142:143], v[100:101]
	v_pk_mul_f32 v[64:65], v[122:123], v[102:103]
	s_and_b64 vcc, exec, s[0:1]
	v_add3_u32 v102, v79, v59, s33
	v_add3_u32 v103, v126, v60, s33
	v_add3_u32 v118, v124, v61, s33
	v_add3_u32 v119, v58, v119, s33
	s_cbranch_vccnz .LBB0_1094
	v_mov_b32_e32 v79, v1
	v_lshl_add_u64 v[58:59], v[106:107], 0, v[78:79]
	v_lshlrev_b64 v[60:61], 11, v[116:117]
	v_lshl_add_u64 v[58:59], v[58:59], 0, v[60:61]
	s_mov_b64 s[2:3], 0x10000
	v_bfe_u32 v79, v104, 16, 1
	v_lshl_add_u64 v[60:61], v[58:59], 0, s[2:3]
	v_add3_u32 v79, v104, v79, s33
	v_readlane_b32 s98, v251, 38
	s_nop 1
	v_subrev_u32_e32 v248, s98, v60
	v_bfe_u32 v249, v248, 11, 4
	v_lshlrev_b32_e32 v244, 4, v249
	v_bfe_u32 v249, v248, 9, 2
	v_lshl_or_b32 v244, v249, 13, v244
	v_bfe_u32 v249, v248, 6, 3
	v_lshl_or_b32 v244, v249, 10, v244
	v_bfe_u32 v249, v248, 4, 2
	v_lshl_or_b32 v244, v249, 8, v244
	v_and_b32_e32 v249, 0x7ff0, v248
	v_sub_u32_e32 v244, v244, v249
	v_add_u32_e32 v244, 0xa00, v244
	v_ashrrev_i32_e32 v245, 31, v244
	v_lshl_add_u64 v[244:245], v[60:61], 0, v[244:245]
	global_store_short_d16_hi v[244:245], v79, off offset:-2048
	v_bfe_u32 v79, v100, 16, 1
	v_add3_u32 v79, v100, v79, s33
	s_mov_b32 s2, 0x1010000
	global_store_short_d16_hi v[244:245], v79, off offset:2048
	v_add_co_u32_e32 v60, vcc, s2, v58
	v_bfe_u32 v79, v62, 16, 1
	s_nop 0
	v_addc_co_u32_e32 v61, vcc, 0, v59, vcc
	v_add3_u32 v79, v62, v79, s33
	v_readlane_b32 s98, v251, 38
	s_nop 1
	v_subrev_u32_e32 v248, s98, v60
	v_bfe_u32 v249, v248, 11, 4
	v_lshlrev_b32_e32 v244, 4, v249
	v_bfe_u32 v249, v248, 9, 2
	v_lshl_or_b32 v244, v249, 13, v244
	v_bfe_u32 v249, v248, 6, 3
	v_lshl_or_b32 v244, v249, 10, v244
	v_bfe_u32 v249, v248, 4, 2
	v_lshl_or_b32 v244, v249, 8, v244
	v_and_b32_e32 v249, 0x7ff0, v248
	v_sub_u32_e32 v244, v244, v249
	v_add_u32_e32 v244, 0xa00, v244
	v_ashrrev_i32_e32 v245, 31, v244
	v_lshl_add_u64 v[244:245], v[60:61], 0, v[244:245]
	global_store_short_d16_hi v[244:245], v79, off offset:2048
	s_mov_b64 s[2:3], 0x10800
	v_bfe_u32 v79, v110, 16, 1
	v_lshl_add_u64 v[120:121], v[58:59], 0, s[2:3]
	v_add3_u32 v79, v110, v79, s33
	v_readlane_b32 s98, v251, 38
	s_nop 1
	v_subrev_u32_e32 v248, s98, v120
	v_bfe_u32 v249, v248, 11, 4
	v_lshlrev_b32_e32 v246, 4, v249
	v_bfe_u32 v249, v248, 9, 2
	v_lshl_or_b32 v246, v249, 13, v246
	v_bfe_u32 v249, v248, 6, 3
	v_lshl_or_b32 v246, v249, 10, v246
	v_bfe_u32 v249, v248, 4, 2
	v_lshl_or_b32 v246, v249, 8, v246
	v_and_b32_e32 v249, 0x7ff0, v248
	v_sub_u32_e32 v246, v246, v249
	v_add_u32_e32 v246, 0xa00, v246
	v_ashrrev_i32_e32 v247, 31, v246
	v_lshl_add_u64 v[246:247], v[120:121], 0, v[246:247]
	global_store_short_d16_hi v[246:247], v79, off offset:-2048
	v_bfe_u32 v79, v98, 16, 1
	v_add3_u32 v79, v98, v79, s33
	global_store_short_d16_hi v[244:245], v102, off offset:-2048
	global_store_short_d16_hi v[246:247], v79, off offset:2048
	global_store_short_d16_hi v[244:245], v103, off offset:-2032
	v_bfe_u32 v79, v63, 16, 1
	v_add3_u32 v79, v63, v79, s33
	global_store_short_d16_hi v[244:245], v79, off offset:2064
	s_mov_b64 s[2:3], 0x11000
	v_bfe_u32 v79, v111, 16, 1
	v_lshl_add_u64 v[60:61], v[58:59], 0, s[2:3]
	v_add3_u32 v79, v111, v79, s33
	v_readlane_b32 s98, v251, 38
	s_nop 1
	v_subrev_u32_e32 v248, s98, v60
	v_bfe_u32 v249, v248, 11, 4
	v_lshlrev_b32_e32 v244, 4, v249
	v_bfe_u32 v249, v248, 9, 2
	v_lshl_or_b32 v244, v249, 13, v244
	v_bfe_u32 v249, v248, 6, 3
	v_lshl_or_b32 v244, v249, 10, v244
	v_bfe_u32 v249, v248, 4, 2
	v_lshl_or_b32 v244, v249, 8, v244
	v_and_b32_e32 v249, 0x7ff0, v248
	v_sub_u32_e32 v244, v244, v249
	v_add_u32_e32 v244, 0xa00, v244
	v_ashrrev_i32_e32 v245, 31, v244
	v_lshl_add_u64 v[244:245], v[60:61], 0, v[244:245]
	global_store_short_d16_hi v[244:245], v79, off offset:-2048
	v_bfe_u32 v79, v99, 16, 1
	v_add3_u32 v79, v99, v79, s33
	global_store_short_d16_hi v[244:245], v79, off offset:2048
	v_add_co_u32_e32 v60, vcc, s58, v58
	v_bfe_u32 v79, v64, 16, 1
	s_nop 0
	v_addc_co_u32_e32 v61, vcc, 0, v59, vcc
	v_add3_u32 v79, v64, v79, s33
	v_readlane_b32 s98, v251, 38
	s_nop 1
	v_subrev_u32_e32 v248, s98, v60
	v_bfe_u32 v249, v248, 11, 4
	v_lshlrev_b32_e32 v244, 4, v249
	v_bfe_u32 v249, v248, 9, 2
	v_lshl_or_b32 v244, v249, 13, v244
	v_bfe_u32 v249, v248, 6, 3
	v_lshl_or_b32 v244, v249, 10, v244
	v_bfe_u32 v249, v248, 4, 2
	v_lshl_or_b32 v244, v249, 8, v244
	v_and_b32_e32 v249, 0x7ff0, v248
	v_sub_u32_e32 v244, v244, v249
	v_add_u32_e32 v244, 0xa00, v244
	v_ashrrev_i32_e32 v245, 31, v244
	v_lshl_add_u64 v[244:245], v[60:61], 0, v[244:245]
	global_store_short_d16_hi v[244:245], v79, off offset:2048
	s_mov_b64 s[2:3], 0x11800
	v_bfe_u32 v79, v105, 16, 1
	v_lshl_add_u64 v[58:59], v[58:59], 0, s[2:3]
	v_add3_u32 v79, v105, v79, s33
	v_readlane_b32 s98, v251, 38
	s_nop 1
	v_subrev_u32_e32 v248, s98, v58
	v_bfe_u32 v249, v248, 11, 4
	v_lshlrev_b32_e32 v246, 4, v249
	v_bfe_u32 v249, v248, 9, 2
	v_lshl_or_b32 v246, v249, 13, v246
	v_bfe_u32 v249, v248, 6, 3
	v_lshl_or_b32 v246, v249, 10, v246
	v_bfe_u32 v249, v248, 4, 2
	v_lshl_or_b32 v246, v249, 8, v246
	v_and_b32_e32 v249, 0x7ff0, v248
	v_sub_u32_e32 v246, v246, v249
	v_add_u32_e32 v246, 0xa00, v246
	v_ashrrev_i32_e32 v247, 31, v246
	v_lshl_add_u64 v[246:247], v[58:59], 0, v[246:247]
	global_store_short_d16_hi v[246:247], v79, off offset:-2048
	v_bfe_u32 v79, v101, 16, 1
	v_add3_u32 v79, v101, v79, s33
	global_store_short_d16_hi v[244:245], v118, off offset:-2048
	global_store_short_d16_hi v[246:247], v79, off offset:2048
	global_store_short_d16_hi v[244:245], v119, off offset:-2032
	v_bfe_u32 v58, v65, 16, 1
	v_add3_u32 v58, v65, v58, s33
	s_mov_b64 s[2:3], 0
	global_store_short_d16_hi v[244:245], v58, off offset:2064

.LBB0_1096:
	v_mov_b32_e32 v62, v113
	v_mov_b32_e32 v63, v113
	v_mov_b32_e32 v113, v112
	v_pk_mov_b32 v[64:65], v[108:109], v[70:71] op_sel:[1,0]
	v_mov_b32_e32 v100, v50
	v_pk_mul_f32 v[64:65], v[112:113], v[64:65]
	v_mov_b32_e32 v101, v53
	v_pk_fma_f32 v[70:71], v[62:63], v[72:73], v[64:65] neg_lo:[0,0,1] neg_hi:[0,0,1]
	v_pk_fma_f32 v[62:63], v[62:63], v[72:73], v[64:65]
	v_mov_b32_e32 v64, v70
	v_pk_mov_b32 v[72:73], v[62:63], v[70:71] op_sel:[1,0]
	v_mov_b32_e32 v65, v63
	v_pk_mul_f32 v[72:73], v[80:81], v[72:73]
	v_mov_b32_e32 v98, v54
	v_pk_fma_f32 v[108:109], v[136:137], v[64:65], v[72:73] neg_lo:[0,0,1] neg_hi:[0,0,1]
	v_pk_fma_f32 v[64:65], v[136:137], v[64:65], v[72:73]
	v_mov_b32_e32 v72, v108
	v_pk_mov_b32 v[110:111], v[64:65], v[108:109] op_sel:[1,0]
	v_mov_b32_e32 v73, v65
	v_pk_mul_f32 v[80:81], v[80:81], v[110:111]
	v_mov_b32_e32 v99, v57
	v_pk_fma_f32 v[110:111], v[136:137], v[72:73], v[80:81] neg_lo:[0,0,1] neg_hi:[0,0,1]
	v_pk_fma_f32 v[72:73], v[136:137], v[72:73], v[80:81]
	v_mov_b32_e32 v102, v55
	v_mov_b32_e32 v111, v73
	v_mul_f32_e32 v64, v135, v73
	v_pk_fma_f32 v[80:81], v[134:135], v[110:111], v[64:65] op_sel_hi:[1,1,0] neg_lo:[0,0,1] neg_hi:[0,0,1]
	v_mul_f32_e32 v64, v89, v73
	v_pk_fma_f32 v[88:89], v[88:89], v[110:111], v[64:65] op_sel_hi:[1,1,0]
	v_mov_b32_e32 v71, v80
	v_pk_mov_b32 v[118:119], v[62:63], v[88:89] op_sel:[1,0]
	v_pk_mul_f32 v[112:113], v[100:101], v[70:71]
	v_pk_mul_f32 v[100:101], v[100:101], v[118:119]
	v_mov_b32_e32 v64, v63
	v_pk_fma_f32 v[112:113], v[98:99], v[118:119], v[112:113]
	v_pk_fma_f32 v[98:99], v[98:99], v[70:71], v[100:101] neg_lo:[0,0,1] neg_hi:[0,0,1]
	v_mov_b32_e32 v100, v65
	v_mov_b32_e32 v71, v108
	v_pk_mul_f32 v[62:63], v[84:85], v[64:65]
	v_pk_mul_f32 v[64:65], v[86:87], v[64:65]
	v_pk_fma_f32 v[62:63], v[86:87], v[70:71], v[62:63]
	v_pk_fma_f32 v[64:65], v[84:85], v[70:71], v[64:65] neg_lo:[0,0,1] neg_hi:[0,0,1]
	v_mov_b32_e32 v111, v80
	v_mul_f32_e32 v70, v50, v64
	v_fma_f32 v70, v54, v62, -v70
	v_mul_f32_e32 v79, v70, v90
	v_pk_mul_f32 v[70:71], v[50:51], v[62:63]
	v_mul_f32_e32 v50, v51, v65
	v_pk_fma_f32 v[70:71], v[54:55], v[64:65], v[70:71]
	v_fma_f32 v50, v55, v63, -v50
	v_pk_mov_b32 v[54:55], v[72:73], v[88:89] op_sel:[1,0]
	v_mov_b32_e32 v104, v51
	v_pk_mul_f32 v[64:65], v[84:85], v[54:55]
	v_pk_mul_f32 v[54:55], v[86:87], v[54:55]
	v_pk_fma_f32 v[80:81], v[86:87], v[110:111], v[64:65]
	v_pk_fma_f32 v[54:55], v[84:85], v[110:111], v[54:55] neg_lo:[0,0,1] neg_hi:[0,0,1]
	v_mov_b32_e32 v105, v52
	v_mul_f32_e32 v64, v52, v54
	v_fma_f32 v64, v56, v80, -v64
	v_mov_b32_e32 v109, v110
	v_mov_b32_e32 v101, v73
	v_mul_f32_e32 v86, v64, v94
	v_pk_mul_f32 v[64:65], v[52:53], v[80:81]
	v_mul_f32_e32 v52, v53, v55
	v_mov_b32_e32 v103, v56
	v_pk_mul_f32 v[118:119], v[104:105], v[100:101]
	v_pk_mul_f32 v[104:105], v[104:105], v[108:109]
	v_fma_f32 v52, v57, v81, -v52
	v_pk_fma_f32 v[118:119], v[102:103], v[108:109], v[118:119] neg_lo:[0,0,1] neg_hi:[0,0,1]
	v_pk_fma_f32 v[100:101], v[102:103], v[100:101], v[104:105]
	v_mul_f32_e32 v102, v50, v91
	v_pk_fma_f32 v[84:85], v[56:57], v[54:55], v[64:65]
	v_mul_f32_e32 v54, v52, v95
	v_pk_mul_f32 v[52:53], v[84:85], v[94:95]
	v_bfe_u32 v55, v79, 16, 1
	v_bfe_u32 v56, v102, 16, 1
	v_bfe_u32 v57, v86, 16, 1
	v_bfe_u32 v85, v54, 16, 1
	v_pk_mul_f32 v[50:51], v[70:71], v[90:91]
	v_pk_mul_f32 v[70:71], v[118:119], v[96:97]
	v_pk_mul_f32 v[62:63], v[100:101], v[96:97]
	v_pk_mul_f32 v[72:73], v[98:99], v[92:93]
	v_pk_mul_f32 v[64:65], v[112:113], v[92:93]
	s_mov_b64 s[2:3], -1
	s_and_b64 vcc, exec, s[0:1]
	v_add3_u32 v80, v79, v55, s33
	v_add3_u32 v81, v102, v56, s33
	v_add3_u32 v84, v86, v57, s33
	v_add3_u32 v85, v54, v85, s33
	s_cbranch_vccnz .LBB0_1099
	v_mov_b32_e32 v79, v1
	v_lshl_add_u64 v[54:55], v[106:107], 0, v[78:79]
	v_lshlrev_b64 v[56:57], 11, v[116:117]
	v_lshl_add_u64 v[54:55], v[54:55], 0, v[56:57]
	s_mov_b64 s[0:1], 0x18000
	v_bfe_u32 v78, v72, 16, 1
	v_lshl_add_u64 v[56:57], v[54:55], 0, s[0:1]
	v_add3_u32 v78, v72, v78, s33
	v_readlane_b32 s98, v251, 38
	s_nop 1
	v_subrev_u32_e32 v248, s98, v56
	v_bfe_u32 v249, v248, 11, 4
	v_lshlrev_b32_e32 v244, 4, v249
	v_bfe_u32 v249, v248, 9, 2
	v_lshl_or_b32 v244, v249, 13, v244
	v_bfe_u32 v249, v248, 6, 3
	v_lshl_or_b32 v244, v249, 10, v244
	v_bfe_u32 v249, v248, 4, 2
	v_lshl_or_b32 v244, v249, 8, v244
	v_and_b32_e32 v249, 0x7ff0, v248
	v_sub_u32_e32 v244, v244, v249
	v_add_u32_e32 v244, 0xa00, v244
	v_ashrrev_i32_e32 v245, 31, v244
	v_lshl_add_u64 v[244:245], v[56:57], 0, v[244:245]
	global_store_short_d16_hi v[244:245], v78, off offset:-2048
	v_bfe_u32 v78, v64, 16, 1
	v_add3_u32 v78, v64, v78, s33
	s_mov_b32 s0, 0x1018000
	global_store_short_d16_hi v[244:245], v78, off offset:2048
	v_add_co_u32_e32 v56, vcc, s0, v54
	v_bfe_u32 v78, v50, 16, 1
	s_nop 0
	v_addc_co_u32_e32 v57, vcc, 0, v55, vcc
	v_add3_u32 v78, v50, v78, s33
	s_mov_b64 s[0:1], 0x18800
	v_bfe_u32 v86, v70, 16, 1
	v_readlane_b32 s98, v251, 38
	s_nop 1
	v_subrev_u32_e32 v248, s98, v56
	v_bfe_u32 v249, v248, 11, 4
	v_lshlrev_b32_e32 v244, 4, v249
	v_bfe_u32 v249, v248, 9, 2
	v_lshl_or_b32 v244, v249, 13, v244
	v_bfe_u32 v249, v248, 6, 3
	v_lshl_or_b32 v244, v249, 10, v244
	v_bfe_u32 v249, v248, 4, 2
	v_lshl_or_b32 v244, v249, 8, v244
	v_and_b32_e32 v249, 0x7ff0, v248
	v_sub_u32_e32 v244, v244, v249
	v_add_u32_e32 v244, 0xa00, v244
	v_ashrrev_i32_e32 v245, 31, v244
	v_lshl_add_u64 v[244:245], v[56:57], 0, v[244:245]
	global_store_short_d16_hi v[244:245], v78, off offset:2048
	v_lshl_add_u64 v[78:79], v[54:55], 0, s[0:1]
	v_add3_u32 v86, v70, v86, s33
	v_readlane_b32 s98, v251, 38
	s_nop 1
	v_subrev_u32_e32 v248, s98, v78
	v_bfe_u32 v249, v248, 11, 4
	v_lshlrev_b32_e32 v246, 4, v249
	v_bfe_u32 v249, v248, 9, 2
	v_lshl_or_b32 v246, v249, 13, v246
	v_bfe_u32 v249, v248, 6, 3
	v_lshl_or_b32 v246, v249, 10, v246
	v_bfe_u32 v249, v248, 4, 2
	v_lshl_or_b32 v246, v249, 8, v246
	v_and_b32_e32 v249, 0x7ff0, v248
	v_sub_u32_e32 v246, v246, v249
	v_add_u32_e32 v246, 0xa00, v246
	v_ashrrev_i32_e32 v247, 31, v246
	v_lshl_add_u64 v[246:247], v[78:79], 0, v[246:247]
	global_store_short_d16_hi v[246:247], v86, off offset:-2048
	v_bfe_u32 v86, v62, 16, 1
	v_add3_u32 v86, v62, v86, s33
	global_store_short_d16_hi v[244:245], v80, off offset:-2048
	global_store_short_d16_hi v[246:247], v86, off offset:2048
	global_store_short_d16_hi v[244:245], v81, off offset:-2032
	v_bfe_u32 v78, v51, 16, 1
	v_add3_u32 v78, v51, v78, s33
	global_store_short_d16_hi v[244:245], v78, off offset:2064
	s_mov_b64 s[0:1], 0x19000
	v_bfe_u32 v78, v71, 16, 1
	v_lshl_add_u64 v[56:57], v[54:55], 0, s[0:1]
	v_add3_u32 v78, v71, v78, s33
	v_readlane_b32 s98, v251, 38
	s_nop 1
	v_subrev_u32_e32 v248, s98, v56
	v_bfe_u32 v249, v248, 11, 4
	v_lshlrev_b32_e32 v244, 4, v249
	v_bfe_u32 v249, v248, 9, 2
	v_lshl_or_b32 v244, v249, 13, v244
	v_bfe_u32 v249, v248, 6, 3
	v_lshl_or_b32 v244, v249, 10, v244
	v_bfe_u32 v249, v248, 4, 2
	v_lshl_or_b32 v244, v249, 8, v244
	v_and_b32_e32 v249, 0x7ff0, v248
	v_sub_u32_e32 v244, v244, v249
	v_add_u32_e32 v244, 0xa00, v244
	v_ashrrev_i32_e32 v245, 31, v244
	v_lshl_add_u64 v[244:245], v[56:57], 0, v[244:245]
	global_store_short_d16_hi v[244:245], v78, off offset:-2048
	v_bfe_u32 v78, v63, 16, 1
	v_add3_u32 v78, v63, v78, s33
	global_store_short_d16_hi v[244:245], v78, off offset:2048
	v_add_co_u32_e32 v56, vcc, s59, v54
	v_bfe_u32 v78, v52, 16, 1
	s_nop 0
	v_addc_co_u32_e32 v57, vcc, 0, v55, vcc
	v_add3_u32 v78, v52, v78, s33
	v_readlane_b32 s98, v251, 38
	s_nop 1
	v_subrev_u32_e32 v248, s98, v56
	v_bfe_u32 v249, v248, 11, 4
	v_lshlrev_b32_e32 v244, 4, v249
	v_bfe_u32 v249, v248, 9, 2
	v_lshl_or_b32 v244, v249, 13, v244
	v_bfe_u32 v249, v248, 6, 3
	v_lshl_or_b32 v244, v249, 10, v244
	v_bfe_u32 v249, v248, 4, 2
	v_lshl_or_b32 v244, v249, 8, v244
	v_and_b32_e32 v249, 0x7ff0, v248
	v_sub_u32_e32 v244, v244, v249
	v_add_u32_e32 v244, 0xa00, v244
	v_ashrrev_i32_e32 v245, 31, v244
	v_lshl_add_u64 v[244:245], v[56:57], 0, v[244:245]
	global_store_short_d16_hi v[244:245], v78, off offset:2048
	s_mov_b64 s[0:1], 0x19800
	v_bfe_u32 v78, v73, 16, 1
	v_lshl_add_u64 v[54:55], v[54:55], 0, s[0:1]
	v_add3_u32 v78, v73, v78, s33
	v_readlane_b32 s98, v251, 38
	s_nop 1
	v_subrev_u32_e32 v248, s98, v54
	v_bfe_u32 v249, v248, 11, 4
	v_lshlrev_b32_e32 v246, 4, v249
	v_bfe_u32 v249, v248, 9, 2
	v_lshl_or_b32 v246, v249, 13, v246
	v_bfe_u32 v249, v248, 6, 3
	v_lshl_or_b32 v246, v249, 10, v246
	v_bfe_u32 v249, v248, 4, 2
	v_lshl_or_b32 v246, v249, 8, v246
	v_and_b32_e32 v249, 0x7ff0, v248
	v_sub_u32_e32 v246, v246, v249
	v_add_u32_e32 v246, 0xa00, v246
	v_ashrrev_i32_e32 v247, 31, v246
	v_lshl_add_u64 v[246:247], v[54:55], 0, v[246:247]
	global_store_short_d16_hi v[246:247], v78, off offset:-2048
	v_bfe_u32 v78, v65, 16, 1
	v_add3_u32 v78, v65, v78, s33
	global_store_short_d16_hi v[244:245], v84, off offset:-2048
	global_store_short_d16_hi v[246:247], v78, off offset:2048
	global_store_short_d16_hi v[244:245], v85, off offset:-2032
	v_bfe_u32 v54, v53, 16, 1
	v_add3_u32 v54, v53, v54, s33
	global_store_short_d16_hi v[244:245], v54, off offset:2064
	v_mov_b64_e32 v[54:55], 0
	v_mov_b64_e32 v[56:57], 0
	s_cbranch_execz .LBB0_1100

.LBB0_1154:
	s_or_b64 exec, exec, s[0:1]
	v_readlane_b32 s0, v253, 13
	v_lshrrev_b32_e32 v58, 4, v167
	v_readlane_b32 s1, v253, 14
	v_lshlrev_b32_e32 v120, 4, v201
	s_waitcnt vmcnt(1)
	v_and_b32_e32 v35, 15, v200
	s_andn2_b64 vcc, exec, s[0:1]
	v_lshlrev_b32_e32 v34, 3, v58
	v_lshlrev_b32_e32 v59, 3, v200
	s_waitcnt vmcnt(0)
	v_ashrrev_i32_e32 v37, 31, v120
	s_waitcnt lgkmcnt(0)
	s_barrier
	s_cbranch_vccnz .LBB0_1163
	s_movk_i32 s0, 0xfff
	v_cmp_lt_i32_e64 s[0:1], s0, v200
	v_lshl_or_b32 v2, v58, 2, v120
	v_or_b32_e32 v4, 16, v35
	v_writelane_b32 v251, s0, 20
	v_or_b32_e32 v5, 32, v35
	v_or_b32_e32 v6, 48, v35
	v_writelane_b32 v251, s1, 21
	v_cmp_ge_i32_e64 s[0:1], v2, v35
	v_or_b32_e32 v7, 64, v35
	v_or_b32_e32 v8, 0x50, v35
	v_writelane_b32 v251, s0, 18
	v_or_b32_e32 v9, 0x60, v35
	v_or_b32_e32 v10, 0x70, v35
	v_writelane_b32 v251, s1, 19
	v_cmp_ge_i32_e64 s[0:1], v35, v2
	v_or_b32_e32 v12, 1, v2
	v_add_u32_e32 v13, 0xffffff82, v2
	v_writelane_b32 v251, s0, 0
	v_add_u32_e32 v11, 0xffffff81, v2
	v_cvt_f32_i32_e32 v62, v12
	v_writelane_b32 v251, s1, 1
	v_cmp_ge_i32_e64 s[0:1], v2, v4
	v_cvt_f32_i32_e32 v63, v13
	v_lshlrev_b32_e32 v13, 7, v12
	v_writelane_b32 v251, s0, 58
	v_add_u32_e32 v14, 0xffffff83, v2
	v_cvt_f32_i32_e32 v60, v2
	v_writelane_b32 v251, s1, 59
	v_cmp_ge_i32_e64 s[0:1], v4, v2
	v_cvt_f32_i32_e32 v61, v11
	v_lshlrev_b32_e32 v11, 7, v2
	v_writelane_b32 v252, s0, 0
	v_cmp_gt_i32_e64 s[92:93], v10, v2
	v_cvt_f32_i32_e32 v65, v14
	v_writelane_b32 v252, s1, 1
	v_cmp_ge_i32_e64 s[0:1], v2, v5
	v_lshl_add_u32 v0, v58, 4, 16
	v_mul_u32_u24_e32 v3, 0x210, v35
	v_writelane_b32 v254, s0, 17
	s_waitcnt vmcnt(0)
	v_or_b32_e32 v38, v35, v11
	v_or_b32_e32 v40, v35, v13
	v_writelane_b32 v254, s1, 18
	v_cmp_ge_i32_e64 s[0:1], v5, v2
	v_readlane_b32 s70, v252, 21
	v_or_b32_e32 v36, v120, v35
	v_writelane_b32 v254, s0, 19
	v_ashrrev_i32_e32 v39, 31, v38
	v_ashrrev_i32_e32 v41, 31, v40
	v_writelane_b32 v254, s1, 20
	v_cmp_ge_i32_e64 s[0:1], v2, v6
	v_ashrrev_i32_e32 v47, 31, v11
	v_mov_b32_e32 v46, v38
	v_writelane_b32 v254, s0, 21
	v_ashrrev_i32_e32 v49, 31, v13
	v_mov_b32_e32 v48, v40
	v_writelane_b32 v254, s1, 22
	v_cmp_ge_i32_e64 s[0:1], v6, v2
	v_lshlrev_b32_e32 v54, 1, v34
	v_add_u32_e32 v68, v0, v3
	v_writelane_b32 v254, s0, 23
	s_mov_b32 s89, s70
	v_readlane_b32 s71, v252, 22
	v_writelane_b32 v254, s1, 24
	v_cmp_ge_i32_e64 s[0:1], v2, v7
	s_nop 1
	v_writelane_b32 v254, s0, 25
	s_nop 1
	v_writelane_b32 v254, s1, 26
	v_cmp_ge_i32_e64 s[0:1], v7, v2
	s_nop 1
	v_writelane_b32 v254, s0, 27
	s_nop 1
	v_writelane_b32 v254, s1, 28
	v_cmp_ge_i32_e64 s[0:1], v2, v8
	s_nop 1
	v_writelane_b32 v254, s0, 29
	s_nop 1
	v_writelane_b32 v254, s1, 30
	v_cmp_ge_i32_e64 s[0:1], v8, v2
	s_nop 1
	v_writelane_b32 v254, s0, 31
	s_nop 1
	v_writelane_b32 v254, s1, 32
	v_cmp_ge_i32_e64 s[0:1], v2, v9
	s_nop 1
	v_writelane_b32 v254, s0, 33
	s_nop 1
	v_writelane_b32 v254, s1, 34
	v_cmp_ge_i32_e64 s[0:1], v9, v2
	s_nop 1
	v_writelane_b32 v254, s0, 35
	s_nop 1
	v_writelane_b32 v254, s1, 36
	v_cmp_ge_i32_e64 s[0:1], v2, v10
	s_nop 1
	v_writelane_b32 v254, s0, 37
	s_nop 1
	v_writelane_b32 v254, s1, 38
	v_cmp_ge_i32_e64 s[0:1], v10, v2
	s_nop 1
	v_writelane_b32 v254, s0, 39
	s_nop 1
	v_writelane_b32 v254, s1, 40
	v_cmp_ge_i32_e64 s[0:1], v12, v35
	s_nop 1
	v_writelane_b32 v254, s0, 41
	s_nop 1
	v_writelane_b32 v254, s1, 42
	v_cmp_gt_i32_e64 s[0:1], v35, v2
	s_nop 1
	v_writelane_b32 v254, s0, 43
	s_nop 1
	v_writelane_b32 v254, s1, 44
	v_cmp_ge_i32_e64 s[0:1], v12, v4
	s_nop 1
	v_writelane_b32 v254, s0, 45
	s_nop 1
	v_writelane_b32 v254, s1, 46
	v_cmp_gt_i32_e64 s[0:1], v4, v2
	s_nop 1
	v_writelane_b32 v254, s0, 47
	s_nop 1
	v_writelane_b32 v254, s1, 48
	v_cmp_ge_i32_e64 s[0:1], v12, v5
	s_nop 1
	v_writelane_b32 v254, s0, 49
	s_nop 1
	v_writelane_b32 v254, s1, 50
	v_cmp_gt_i32_e64 s[0:1], v5, v2
	s_nop 1
	v_writelane_b32 v254, s0, 51
	s_nop 1
	v_writelane_b32 v254, s1, 52
	v_cmp_ge_i32_e64 s[0:1], v12, v6
	s_nop 1
	v_writelane_b32 v254, s0, 53
	s_nop 1
	v_writelane_b32 v254, s1, 54
	v_cmp_gt_i32_e64 s[0:1], v6, v2
	s_nop 1
	v_writelane_b32 v254, s0, 55
	s_nop 1
	v_writelane_b32 v254, s1, 56
	v_cmp_ge_i32_e64 s[0:1], v12, v7
	s_nop 1
	v_writelane_b32 v254, s0, 57
	s_nop 1
	v_writelane_b32 v254, s1, 58
	v_cmp_gt_i32_e64 s[0:1], v7, v2
	s_nop 1
	v_writelane_b32 v254, s0, 59
	s_nop 1
	v_writelane_b32 v254, s1, 60
	v_cmp_ge_i32_e64 s[0:1], v12, v8
	s_nop 1
	v_writelane_b32 v254, s0, 61
	s_nop 1
	v_writelane_b32 v254, s1, 62
	v_cmp_gt_i32_e64 s[0:1], v8, v2
	s_nop 1
	v_writelane_b32 v254, s0, 63
	s_nop 1
	v_writelane_b32 v255, s1, 0
	v_cmp_ge_i32_e64 s[0:1], v12, v9
	s_nop 1
	v_writelane_b32 v255, s0, 1
	s_nop 1
	v_writelane_b32 v255, s1, 2
	v_cmp_gt_i32_e64 s[0:1], v9, v2
	s_nop 1
	v_writelane_b32 v255, s0, 3
	s_nop 1
	v_writelane_b32 v255, s1, 4
	v_cmp_ge_i32_e64 s[0:1], v12, v10
	v_or_b32_e32 v12, 2, v2
	v_cvt_f32_i32_e32 v64, v12
	v_writelane_b32 v255, s0, 5
	v_lshlrev_b32_e32 v14, 7, v12
	v_cmp_ge_i32_e64 s[94:95], v12, v35
	v_writelane_b32 v255, s1, 6
	v_cmp_ge_i32_e64 s[96:97], v35, v12
	v_cmp_ge_i32_e64 s[6:7], v12, v4
	v_cmp_ge_i32_e64 s[16:17], v4, v12
	v_cmp_ge_i32_e64 s[18:19], v12, v5
	v_cmp_ge_i32_e64 s[20:21], v5, v12
	v_cmp_ge_i32_e64 s[22:23], v12, v6
	v_cmp_ge_i32_e64 s[24:25], v6, v12
	v_cmp_ge_i32_e64 s[26:27], v12, v7
	v_cmp_ge_i32_e64 s[28:29], v7, v12
	v_cmp_ge_i32_e64 s[30:31], v12, v8
	v_cmp_ge_i32_e64 s[34:35], v8, v12
	v_cmp_ge_i32_e64 s[36:37], v12, v9
	v_cmp_ge_i32_e64 s[0:1], v9, v12
	v_cmp_ge_i32_e64 s[2:3], v12, v10
	v_cmp_ge_i32_e64 s[4:5], v10, v12
	v_or_b32_e32 v12, 3, v2
	v_add_u32_e32 v2, 0xffffff84, v2
	v_cvt_f32_i32_e32 v66, v12
	v_cvt_f32_i32_e32 v67, v2
	v_lshlrev_b32_e32 v2, 7, v12
	v_or_b32_e32 v42, v35, v14
	v_or_b32_e32 v44, v35, v2
	v_ashrrev_i32_e32 v43, 31, v42
	v_cmp_ge_i32_e64 s[38:39], v12, v35
	v_cmp_ge_i32_e64 s[40:41], v35, v12
	v_ashrrev_i32_e32 v45, 31, v44
	v_cmp_ge_i32_e64 s[42:43], v12, v4
	v_cmp_ge_i32_e64 s[44:45], v4, v12
	v_cmp_ge_i32_e64 s[46:47], v12, v5
	v_cmp_ge_i32_e64 s[48:49], v5, v12
	v_cmp_ge_i32_e64 s[50:51], v12, v6
	v_cmp_ge_i32_e64 s[52:53], v6, v12
	v_cmp_ge_i32_e64 s[54:55], v12, v7
	v_cmp_ge_i32_e64 s[56:57], v7, v12
	v_cmp_ge_i32_e64 s[58:59], v12, v8
	v_cmp_ge_i32_e64 s[60:61], v8, v12
	v_cmp_ge_i32_e64 s[62:63], v12, v9
	v_cmp_ge_i32_e64 s[64:65], v9, v12
	v_cmp_ge_i32_e64 s[66:67], v12, v10
	v_cmp_ge_i32_e64 s[68:69], v10, v12
	v_ashrrev_i32_e32 v51, 31, v14
	v_mov_b32_e32 v50, v42
	v_ashrrev_i32_e32 v53, 31, v2
	v_mov_b32_e32 v52, v44
	v_mbcnt_lo_u32_b32 v56, -1, 0
	v_mbcnt_hi_u32_b32 v56, -1, v56
	v_lshrrev_b32_e32 v57, 4, v56
	v_mul_u32_u24_e32 v57, 0x1e0, v57
	v_lshrrev_b32_e32 v56, 3, v35
	v_mul_u32_u24_e32 v56, 0x78, v56
	v_sub_u32_e32 v56, v56, v57
	v_add_u32_e32 v38, v38, v56
	v_add_u32_e32 v46, v46, v56
	v_add_u32_e32 v40, v40, v56
	v_add_u32_e32 v40, 0xffffff88, v40
	v_add_u32_e32 v48, v48, v56
	v_add_u32_e32 v48, 0xffffff88, v48
	v_add_u32_e32 v42, v42, v56
	v_add_u32_e32 v42, 0xffffff10, v42
	v_add_u32_e32 v50, v50, v56
	v_add_u32_e32 v50, 0xffffff10, v50
	v_add_u32_e32 v44, v44, v56
	v_add_u32_e32 v44, 0xfffffe98, v44
	v_add_u32_e32 v52, v52, v56
	v_add_u32_e32 v52, 0xfffffe98, v52
	v_mbcnt_lo_u32_b32 v56, -1, 0
	v_mbcnt_hi_u32_b32 v56, -1, v56
	v_lshrrev_b32_e32 v56, 4, v56
	v_mul_u32_u24_e32 v56, 0xf0, v56
	v_mul_u32_u24_e32 v57, 0x7f0, v35
	v_sub_u32_e32 v56, v56, v57
	v_add_u32_e32 v56, 0x1000, v56
	v_add_u32_e32 v54, v54, v56
	s_branch .LBB0_1157
.LBB0_1156:
	s_or_b64 exec, exec, s[78:79]
	s_lshl_b64 s[72:73], s[76:77], 24
	v_readlane_b32 s8, v251, 38
	v_lshl_add_u64 v[4:5], v[36:37], 0, v[4:5]
	v_readlane_b32 s9, v251, 39
	s_add_u32 s72, s8, s72
	v_lshlrev_b64 v[4:5], 11, v[4:5]
	s_addc_u32 s73, s9, s73
	v_lshl_add_u64 v[4:5], s[72:73], 0, v[4:5]
	v_mul_u32_u24_e32 v57, 30, v2
	v_lshl_add_u64 v[2:3], v[2:3], 1, v[4:5]
	v_ashrrev_i32_e32 v55, 31, v54
	v_lshl_add_u64 v[2:3], v[2:3], 0, v[54:55]
	v_mov_b32_e32 v55, 0
	v_mov_b32_e32 v56, v57
	v_mov_b32_e32 v57, 0
	v_lshl_add_u64 v[2:3], v[2:3], 0, v[56:57]
	s_waitcnt vmcnt(0)
	v_mul_f32_e32 v0, 0x3fb8aa3b, v6
	s_waitcnt lgkmcnt(0)
	s_barrier
	global_load_dwordx4 v[4:7], v[2:3], off offset:-4096
	ds_read_b128 v[8:11], v68
	ds_read_b128 v[78:81], v68 offset:64
	ds_read_b128 v[12:15], v68 offset:8448
	ds_read_b128 v[16:19], v68 offset:16896
	ds_read_b128 v[20:23], v68 offset:25344
	ds_read_b128 v[24:27], v68 offset:33792
	ds_read_b128 v[28:31], v68 offset:42240
	ds_read_b128 v[70:73], v68 offset:50688
	ds_read_b128 v[74:77], v68 offset:59136
	s_lshl_b64 s[70:71], s[70:71], 21
	v_readlane_b32 s8, v252, 26
	v_readlane_b32 s9, v252, 27
	s_add_u32 s70, s8, s70
	v_exp_f32_e32 v0, v0
	s_addc_u32 s71, s9, s71
	s_lshl_b32 s72, s90, 15
	s_add_u32 s76, s70, s72
	s_addc_u32 s77, s71, 0
	s_cmpk_lt_u32 s89, 0x100
	s_cselect_b64 s[70:71], -1, 0
	v_mul_f32_e32 v55, v0, v60
	v_mul_f32_e64 v56, -v0, v61
	v_readlane_b32 s8, v251, 18
	v_cndmask_b32_e64 v55, v55, v56, s[70:71]
	v_readlane_b32 s9, v251, 19
	v_mul_f32_e32 v55, 0x3fb8aa3b, v55
	v_exp_f32_e32 v55, v55
	v_cndmask_b32_e64 v56, 0, 1, s[8:9]
	v_readlane_b32 s8, v251, 0
	v_readlane_b32 s9, v251, 1
	s_waitcnt vmcnt(0) lgkmcnt(8)
	v_mfma_f32_16x16x32_bf16 v[8:11], v[4:7], v[8:11], 0
	v_cndmask_b32_e64 v57, 0, 1, s[8:9]
	v_cndmask_b32_e64 v56, v57, v56, s[70:71]
	v_and_b32_e32 v56, 1, v56
	s_waitcnt lgkmcnt(6)
	v_mfma_f32_16x16x32_bf16 v[12:15], v[4:7], v[12:15], 0
	v_cmp_eq_u32_e32 vcc, 1, v56
	v_readlane_b32 s8, v251, 58
	v_readlane_b32 s9, v251, 59
	s_waitcnt lgkmcnt(5)
	v_mfma_f32_16x16x32_bf16 v[16:19], v[4:7], v[16:19], 0
	s_waitcnt lgkmcnt(4)
	v_mfma_f32_16x16x32_bf16 v[20:23], v[4:7], v[20:23], 0
	s_waitcnt lgkmcnt(3)
	v_mfma_f32_16x16x32_bf16 v[24:27], v[4:7], v[24:27], 0
	s_waitcnt lgkmcnt(2)
	v_mfma_f32_16x16x32_bf16 v[28:31], v[4:7], v[28:31], 0
	s_waitcnt lgkmcnt(1)
	v_mfma_f32_16x16x32_bf16 v[70:73], v[4:7], v[70:73], 0
	s_waitcnt lgkmcnt(0)
	v_mfma_f32_16x16x32_bf16 v[4:7], v[4:7], v[74:77], 0
	global_load_dwordx4 v[74:77], v[2:3], off offset:-3072
	s_waitcnt vmcnt(0)
	v_mfma_f32_16x16x32_bf16 v[8:11], v[74:77], v[78:81], v[8:11]
	ds_read_b128 v[78:81], v68 offset:8512
	s_waitcnt lgkmcnt(0)
	v_mfma_f32_16x16x32_bf16 v[12:15], v[74:77], v[78:81], v[12:15]
	ds_read_b128 v[78:81], v68 offset:16960
	s_waitcnt lgkmcnt(0)
	v_mfma_f32_16x16x32_bf16 v[16:19], v[74:77], v[78:81], v[16:19]
	ds_read_b128 v[78:81], v68 offset:25408
	s_waitcnt lgkmcnt(0)
	v_mfma_f32_16x16x32_bf16 v[20:23], v[74:77], v[78:81], v[20:23]
	ds_read_b128 v[78:81], v68 offset:33856
	s_waitcnt lgkmcnt(0)
	v_mfma_f32_16x16x32_bf16 v[24:27], v[74:77], v[78:81], v[24:27]
	ds_read_b128 v[78:81], v68 offset:42304
	s_waitcnt lgkmcnt(0)
	v_mfma_f32_16x16x32_bf16 v[28:31], v[74:77], v[78:81], v[28:31]
	ds_read_b128 v[78:81], v68 offset:50752
	s_waitcnt lgkmcnt(0)
	v_mfma_f32_16x16x32_bf16 v[70:73], v[74:77], v[78:81], v[70:73]
	ds_read_b128 v[78:81], v68 offset:59200
	s_waitcnt lgkmcnt(0)
	v_mfma_f32_16x16x32_bf16 v[4:7], v[74:77], v[78:81], v[4:7]
	global_load_dwordx4 v[74:77], v[2:3], off offset:-2048
	ds_read_b128 v[78:81], v68 offset:128
	s_waitcnt vmcnt(0) lgkmcnt(0)
	v_mfma_f32_16x16x32_bf16 v[8:11], v[74:77], v[78:81], v[8:11]
	ds_read_b128 v[78:81], v68 offset:8576
	s_waitcnt lgkmcnt(0)
	v_mfma_f32_16x16x32_bf16 v[12:15], v[74:77], v[78:81], v[12:15]
	ds_read_b128 v[78:81], v68 offset:17024
	s_waitcnt lgkmcnt(0)
	v_mfma_f32_16x16x32_bf16 v[16:19], v[74:77], v[78:81], v[16:19]
	ds_read_b128 v[78:81], v68 offset:25472
	s_waitcnt lgkmcnt(0)
	v_mfma_f32_16x16x32_bf16 v[20:23], v[74:77], v[78:81], v[20:23]
	ds_read_b128 v[78:81], v68 offset:33920
	s_waitcnt lgkmcnt(0)
	v_mfma_f32_16x16x32_bf16 v[24:27], v[74:77], v[78:81], v[24:27]
	ds_read_b128 v[78:81], v68 offset:42368
	s_waitcnt lgkmcnt(0)
	v_mfma_f32_16x16x32_bf16 v[28:31], v[74:77], v[78:81], v[28:31]
	ds_read_b128 v[78:81], v68 offset:50816
	s_waitcnt lgkmcnt(0)
	v_mfma_f32_16x16x32_bf16 v[70:73], v[74:77], v[78:81], v[70:73]
	ds_read_b128 v[78:81], v68 offset:59264
	s_waitcnt lgkmcnt(0)
	v_mfma_f32_16x16x32_bf16 v[4:7], v[74:77], v[78:81], v[4:7]
	global_load_dwordx4 v[74:77], v[2:3], off offset:-1024
	ds_read_b128 v[78:81], v68 offset:192
	s_waitcnt vmcnt(0) lgkmcnt(0)
	v_mfma_f32_16x16x32_bf16 v[8:11], v[74:77], v[78:81], v[8:11]
	ds_read_b128 v[78:81], v68 offset:8640
	s_waitcnt lgkmcnt(0)
	v_mfma_f32_16x16x32_bf16 v[12:15], v[74:77], v[78:81], v[12:15]
	ds_read_b128 v[78:81], v68 offset:17088
	s_waitcnt lgkmcnt(0)
	v_mfma_f32_16x16x32_bf16 v[16:19], v[74:77], v[78:81], v[16:19]
	ds_read_b128 v[78:81], v68 offset:25536
	s_waitcnt lgkmcnt(0)
	v_mfma_f32_16x16x32_bf16 v[20:23], v[74:77], v[78:81], v[20:23]
	ds_read_b128 v[78:81], v68 offset:33984
	s_waitcnt lgkmcnt(0)
	v_mfma_f32_16x16x32_bf16 v[24:27], v[74:77], v[78:81], v[24:27]
	ds_read_b128 v[78:81], v68 offset:42432
	s_waitcnt lgkmcnt(0)
	v_mfma_f32_16x16x32_bf16 v[28:31], v[74:77], v[78:81], v[28:31]
	ds_read_b128 v[78:81], v68 offset:50880
	s_waitcnt lgkmcnt(0)
	v_mfma_f32_16x16x32_bf16 v[70:73], v[74:77], v[78:81], v[70:73]
	ds_read_b128 v[78:81], v68 offset:59328
	s_waitcnt lgkmcnt(0)
	v_mfma_f32_16x16x32_bf16 v[4:7], v[74:77], v[78:81], v[4:7]
	global_load_dwordx4 v[74:77], v[2:3], off offset:0
	ds_read_b128 v[78:81], v68 offset:256
	s_waitcnt vmcnt(0) lgkmcnt(0)
	v_mfma_f32_16x16x32_bf16 v[8:11], v[74:77], v[78:81], v[8:11]
	ds_read_b128 v[78:81], v68 offset:8704
	s_waitcnt lgkmcnt(0)
	v_mfma_f32_16x16x32_bf16 v[12:15], v[74:77], v[78:81], v[12:15]
	ds_read_b128 v[78:81], v68 offset:17152
	s_waitcnt lgkmcnt(0)
	v_mfma_f32_16x16x32_bf16 v[16:19], v[74:77], v[78:81], v[16:19]
	ds_read_b128 v[78:81], v68 offset:25600
	s_waitcnt lgkmcnt(0)
	v_mfma_f32_16x16x32_bf16 v[20:23], v[74:77], v[78:81], v[20:23]
	ds_read_b128 v[78:81], v68 offset:34048
	s_waitcnt lgkmcnt(0)
	v_mfma_f32_16x16x32_bf16 v[24:27], v[74:77], v[78:81], v[24:27]
	ds_read_b128 v[78:81], v68 offset:42496
	s_waitcnt lgkmcnt(0)
	v_mfma_f32_16x16x32_bf16 v[28:31], v[74:77], v[78:81], v[28:31]
	ds_read_b128 v[78:81], v68 offset:50944
	s_waitcnt lgkmcnt(0)
	v_mfma_f32_16x16x32_bf16 v[70:73], v[74:77], v[78:81], v[70:73]
	ds_read_b128 v[78:81], v68 offset:59392
	s_waitcnt lgkmcnt(0)
	v_mfma_f32_16x16x32_bf16 v[4:7], v[74:77], v[78:81], v[4:7]
	global_load_dwordx4 v[74:77], v[2:3], off offset:1024
	ds_read_b128 v[78:81], v68 offset:320
	s_waitcnt vmcnt(0) lgkmcnt(0)
	v_mfma_f32_16x16x32_bf16 v[8:11], v[74:77], v[78:81], v[8:11]
	ds_read_b128 v[78:81], v68 offset:8768
	s_waitcnt lgkmcnt(0)
	v_mfma_f32_16x16x32_bf16 v[12:15], v[74:77], v[78:81], v[12:15]
	ds_read_b128 v[78:81], v68 offset:17216
	s_waitcnt lgkmcnt(0)
	v_mfma_f32_16x16x32_bf16 v[16:19], v[74:77], v[78:81], v[16:19]
	ds_read_b128 v[78:81], v68 offset:25664
	s_waitcnt lgkmcnt(0)
	v_mfma_f32_16x16x32_bf16 v[20:23], v[74:77], v[78:81], v[20:23]
	ds_read_b128 v[78:81], v68 offset:34112
	s_waitcnt lgkmcnt(0)
	v_mfma_f32_16x16x32_bf16 v[24:27], v[74:77], v[78:81], v[24:27]
	ds_read_b128 v[78:81], v68 offset:42560
	s_waitcnt lgkmcnt(0)
	v_mfma_f32_16x16x32_bf16 v[28:31], v[74:77], v[78:81], v[28:31]
	ds_read_b128 v[78:81], v68 offset:51008
	s_waitcnt lgkmcnt(0)
	v_mfma_f32_16x16x32_bf16 v[70:73], v[74:77], v[78:81], v[70:73]
	ds_read_b128 v[78:81], v68 offset:59456
	s_waitcnt lgkmcnt(0)
	v_mfma_f32_16x16x32_bf16 v[4:7], v[74:77], v[78:81], v[4:7]
	global_load_dwordx4 v[74:77], v[2:3], off offset:2048
	ds_read_b128 v[78:81], v68 offset:384
	s_waitcnt vmcnt(0) lgkmcnt(0)
	v_mfma_f32_16x16x32_bf16 v[8:11], v[74:77], v[78:81], v[8:11]
	ds_read_b128 v[78:81], v68 offset:8832
	s_waitcnt lgkmcnt(0)
	v_mfma_f32_16x16x32_bf16 v[12:15], v[74:77], v[78:81], v[12:15]
	ds_read_b128 v[78:81], v68 offset:17280
	s_waitcnt lgkmcnt(0)
	v_mfma_f32_16x16x32_bf16 v[16:19], v[74:77], v[78:81], v[16:19]
	ds_read_b128 v[78:81], v68 offset:25728
	s_waitcnt lgkmcnt(0)
	v_mfma_f32_16x16x32_bf16 v[78:81], v[74:77], v[78:81], v[20:23]
	s_nop 2
	ds_read_b128 v[20:23], v68 offset:34176
	s_waitcnt lgkmcnt(0)
	v_mfma_f32_16x16x32_bf16 v[82:85], v[74:77], v[20:23], v[24:27]
	ds_read_b128 v[20:23], v68 offset:42624
	s_waitcnt lgkmcnt(0)
	v_mfma_f32_16x16x32_bf16 v[86:89], v[74:77], v[20:23], v[28:31]
	ds_read_b128 v[20:23], v68 offset:51072
	s_waitcnt lgkmcnt(0)
	v_mfma_f32_16x16x32_bf16 v[70:73], v[74:77], v[20:23], v[70:73]
	ds_read_b128 v[20:23], v68 offset:59520
	s_waitcnt lgkmcnt(0)
	v_mfma_f32_16x16x32_bf16 v[74:77], v[74:77], v[20:23], v[4:7]
	ds_read_b128 v[20:23], v68 offset:448
	s_nop 1
	global_load_dwordx4 v[2:5], v[2:3], off offset:3072
	s_waitcnt vmcnt(0) lgkmcnt(0)
	v_mfma_f32_16x16x32_bf16 v[30:33], v[2:5], v[20:23], v[8:11]
	s_nop 2
	ds_read_b128 v[6:9], v68 offset:8896
	s_nop 3
	v_mul_f32_e32 v30, v55, v30
	v_cndmask_b32_e32 v30, 0, v30, vcc
	v_bfe_u32 v56, v30, 16, 1
	v_add3_u32 v30, v30, v56, s33
	v_lshl_add_u64 v[56:57], v[38:39], 1, s[76:77]
	global_store_short_d16_hi v[56:57], v30, off
	v_cndmask_b32_e64 v30, 0, 1, s[8:9]
	v_readlane_b32 s8, v252, 0
	s_waitcnt lgkmcnt(0)
	v_mfma_f32_16x16x32_bf16 v[26:29], v[2:5], v[6:9], v[12:15]
	v_readlane_b32 s9, v252, 1
	ds_read_b128 v[6:9], v68 offset:17344
	s_nop 0
	v_cndmask_b32_e64 v56, 0, 1, s[8:9]
	v_cndmask_b32_e64 v30, v56, v30, s[70:71]
	v_and_b32_e32 v30, 1, v30
	v_cmp_eq_u32_e32 vcc, 1, v30
	s_nop 0
	v_mul_f32_e32 v26, v55, v26
	v_readlane_b32 s8, v254, 17
	v_cndmask_b32_e32 v26, 0, v26, vcc
	v_bfe_u32 v30, v26, 16, 1
	v_add3_u32 v26, v26, v30, s33
	v_lshl_add_u64 v[56:57], v[46:47], 1, s[76:77]
	v_readlane_b32 s9, v254, 18
	global_store_short_d16_hi v[56:57], v26, off offset:512
	s_waitcnt lgkmcnt(0)
	v_mfma_f32_16x16x32_bf16 v[22:25], v[2:5], v[6:9], v[16:19]
	v_cndmask_b32_e64 v26, 0, 1, s[8:9]
	v_readlane_b32 s8, v254, 19
	v_readlane_b32 s9, v254, 20
	ds_read_b128 v[6:9], v68 offset:25792
	s_waitcnt lgkmcnt(0)
	v_mfma_f32_16x16x32_bf16 v[18:21], v[2:5], v[6:9], v[78:81]
	v_cndmask_b32_e64 v30, 0, 1, s[8:9]
	v_cndmask_b32_e64 v26, v30, v26, s[70:71]
	v_and_b32_e32 v26, 1, v26
	v_cmp_eq_u32_e32 vcc, 1, v26
	v_mul_f32_e32 v22, v55, v22
	v_readlane_b32 s8, v254, 21
	v_cndmask_b32_e32 v22, 0, v22, vcc
	v_bfe_u32 v26, v22, 16, 1
	v_add3_u32 v22, v22, v26, s33
	v_readlane_b32 s9, v254, 22
	global_store_short_d16_hi v[56:57], v22, off offset:1024
	ds_read_b128 v[6:9], v68 offset:34240
	v_cndmask_b32_e64 v22, 0, 1, s[8:9]
	v_readlane_b32 s8, v254, 23
	v_readlane_b32 s9, v254, 24
	v_mul_f32_e32 v18, v55, v18
	s_waitcnt lgkmcnt(0)
	v_mfma_f32_16x16x32_bf16 v[14:17], v[2:5], v[6:9], v[82:85]
	v_cndmask_b32_e64 v26, 0, 1, s[8:9]
	v_cndmask_b32_e64 v22, v26, v22, s[70:71]
	v_and_b32_e32 v22, 1, v22
	v_cmp_eq_u32_e32 vcc, 1, v22
	v_readlane_b32 s8, v254, 25
	v_readlane_b32 s9, v254, 26
	v_cndmask_b32_e32 v18, 0, v18, vcc
	v_bfe_u32 v22, v18, 16, 1
	v_add3_u32 v18, v18, v22, s33
	global_store_short_d16_hi v[56:57], v18, off offset:1536
	v_cndmask_b32_e64 v18, 0, 1, s[8:9]
	v_readlane_b32 s8, v254, 27
	v_readlane_b32 s9, v254, 28
	ds_read_b128 v[6:9], v68 offset:42688
	v_mul_f32_e32 v14, v55, v14
	v_cndmask_b32_e64 v22, 0, 1, s[8:9]
	v_cndmask_b32_e64 v18, v22, v18, s[70:71]
	v_and_b32_e32 v18, 1, v18
	v_cmp_eq_u32_e32 vcc, 1, v18
	v_readlane_b32 s8, v254, 29
	v_readlane_b32 s9, v254, 30
	v_cndmask_b32_e32 v14, 0, v14, vcc
	v_bfe_u32 v18, v14, 16, 1
	v_add3_u32 v14, v14, v18, s33
	global_store_short_d16_hi v[56:57], v14, off offset:2048
	v_cndmask_b32_e64 v14, 0, 1, s[8:9]
	v_readlane_b32 s8, v254, 31
	s_waitcnt lgkmcnt(0)
	v_mfma_f32_16x16x32_bf16 v[10:13], v[2:5], v[6:9], v[86:89]
	v_readlane_b32 s9, v254, 32
	ds_read_b128 v[6:9], v68 offset:51136
	s_nop 0
	v_cndmask_b32_e64 v18, 0, 1, s[8:9]
	v_cndmask_b32_e64 v14, v18, v14, s[70:71]
	v_and_b32_e32 v14, 1, v14
	v_cmp_eq_u32_e32 vcc, 1, v14
	s_nop 0
	v_mul_f32_e32 v10, v55, v10
	v_readlane_b32 s8, v254, 33
	v_cndmask_b32_e32 v10, 0, v10, vcc
	v_bfe_u32 v14, v10, 16, 1
	v_add3_u32 v10, v10, v14, s33
	v_readlane_b32 s9, v254, 34
	global_store_short_d16_hi v[56:57], v10, off offset:2560
	s_waitcnt lgkmcnt(0)
	v_mfma_f32_16x16x32_bf16 v[6:9], v[2:5], v[6:9], v[70:73]
	v_cndmask_b32_e64 v10, 0, 1, s[8:9]
	v_readlane_b32 s8, v254, 35
	v_readlane_b32 s9, v254, 36
	ds_read_b128 v[70:73], v68 offset:59584
	s_waitcnt lgkmcnt(0)
	v_mfma_f32_16x16x32_bf16 v[2:5], v[2:5], v[70:73], v[74:77]
	v_cndmask_b32_e64 v14, 0, 1, s[8:9]
	v_cndmask_b32_e64 v10, v14, v10, s[70:71]
	v_and_b32_e32 v10, 1, v10
	v_cmp_eq_u32_e32 vcc, 1, v10
	v_mul_f32_e32 v6, v55, v6
	v_readlane_b32 s8, v254, 37
	v_cndmask_b32_e32 v6, 0, v6, vcc
	v_bfe_u32 v10, v6, 16, 1
	v_add3_u32 v6, v6, v10, s33
	v_readlane_b32 s9, v254, 38
	global_store_short_d16_hi v[56:57], v6, off offset:3072
	v_mul_f32_e32 v2, v55, v2
	v_cndmask_b32_e64 v6, 0, 1, s[8:9]
	v_readlane_b32 s8, v254, 39
	v_readlane_b32 s9, v254, 40
	s_nop 1
	v_cndmask_b32_e64 v10, 0, 1, s[8:9]
	v_cndmask_b32_e64 v6, v10, v6, s[70:71]
	v_and_b32_e32 v6, 1, v6
	v_cmp_eq_u32_e32 vcc, 1, v6
	v_readlane_b32 s8, v254, 41
	v_readlane_b32 s9, v254, 42
	v_cndmask_b32_e32 v2, 0, v2, vcc
	v_bfe_u32 v6, v2, 16, 1
	v_add3_u32 v2, v2, v6, s33
	global_store_short_d16_hi v[56:57], v2, off offset:3584
	v_mul_f32_e64 v2, -v0, v63
	v_mul_f32_e32 v6, v0, v62
	v_cndmask_b32_e64 v2, v6, v2, s[70:71]
	v_mul_f32_e32 v2, 0x3fb8aa3b, v2
	v_cndmask_b32_e64 v6, 0, 1, s[8:9]
	v_readlane_b32 s8, v254, 43
	v_exp_f32_e32 v2, v2
	v_readlane_b32 s9, v254, 44
	s_nop 1
	v_cndmask_b32_e64 v10, 0, 1, s[8:9]
	v_cndmask_b32_e64 v6, v10, v6, s[70:71]
	v_and_b32_e32 v6, 1, v6
	v_cmp_eq_u32_e32 vcc, 1, v6
	v_mul_f32_e32 v6, v2, v31
	v_readlane_b32 s8, v254, 45
	v_cndmask_b32_e32 v6, 0, v6, vcc
	v_bfe_u32 v10, v6, 16, 1
	v_add3_u32 v6, v6, v10, s33
	v_lshl_add_u64 v[30:31], v[40:41], 1, s[76:77]
	v_readlane_b32 s9, v254, 46
	global_store_short_d16_hi v[30:31], v6, off
	s_nop 0
	v_cndmask_b32_e64 v6, 0, 1, s[8:9]
	v_readlane_b32 s8, v254, 47
	v_readlane_b32 s9, v254, 48
	s_nop 1
	v_cndmask_b32_e64 v10, 0, 1, s[8:9]
	v_cndmask_b32_e64 v6, v10, v6, s[70:71]
	v_and_b32_e32 v6, 1, v6
	v_cmp_eq_u32_e32 vcc, 1, v6
	v_mul_f32_e32 v6, v2, v27
	v_readlane_b32 s8, v254, 49
	v_cndmask_b32_e32 v6, 0, v6, vcc
	v_bfe_u32 v10, v6, 16, 1
	v_add3_u32 v6, v6, v10, s33
	v_lshl_add_u64 v[26:27], v[48:49], 1, s[76:77]
	v_readlane_b32 s9, v254, 50
	global_store_short_d16_hi v[26:27], v6, off offset:512
	s_nop 0
	v_cndmask_b32_e64 v6, 0, 1, s[8:9]
	v_readlane_b32 s8, v254, 51
	v_readlane_b32 s9, v254, 52
	s_nop 1
	v_cndmask_b32_e64 v10, 0, 1, s[8:9]
	v_cndmask_b32_e64 v6, v10, v6, s[70:71]
	v_and_b32_e32 v6, 1, v6
	v_cmp_eq_u32_e32 vcc, 1, v6
	v_mul_f32_e32 v6, v2, v23
	v_readlane_b32 s8, v254, 53
	v_cndmask_b32_e32 v6, 0, v6, vcc
	v_bfe_u32 v10, v6, 16, 1
	v_add3_u32 v6, v6, v10, s33
	v_readlane_b32 s9, v254, 54
	global_store_short_d16_hi v[26:27], v6, off offset:1024
	s_nop 0
	v_cndmask_b32_e64 v6, 0, 1, s[8:9]
	v_readlane_b32 s8, v254, 55
	v_readlane_b32 s9, v254, 56
	s_nop 1
	v_cndmask_b32_e64 v10, 0, 1, s[8:9]
	v_cndmask_b32_e64 v6, v10, v6, s[70:71]
	v_and_b32_e32 v6, 1, v6
	v_cmp_eq_u32_e32 vcc, 1, v6
	v_mul_f32_e32 v6, v2, v19
	v_readlane_b32 s8, v254, 57
	v_cndmask_b32_e32 v6, 0, v6, vcc
	v_bfe_u32 v10, v6, 16, 1
	v_add3_u32 v6, v6, v10, s33
	v_readlane_b32 s9, v254, 58
	global_store_short_d16_hi v[26:27], v6, off offset:1536
	s_nop 0
	v_cndmask_b32_e64 v6, 0, 1, s[8:9]
	v_readlane_b32 s8, v254, 59
	v_readlane_b32 s9, v254, 60
	s_nop 1
	v_cndmask_b32_e64 v10, 0, 1, s[8:9]
	v_cndmask_b32_e64 v6, v10, v6, s[70:71]
	v_and_b32_e32 v6, 1, v6
	v_cmp_eq_u32_e32 vcc, 1, v6
	v_mul_f32_e32 v6, v2, v15
	v_readlane_b32 s8, v254, 61
	v_cndmask_b32_e32 v6, 0, v6, vcc
	v_bfe_u32 v10, v6, 16, 1
	v_add3_u32 v6, v6, v10, s33
	v_readlane_b32 s9, v254, 62
	global_store_short_d16_hi v[26:27], v6, off offset:2048
	s_nop 0
	v_cndmask_b32_e64 v6, 0, 1, s[8:9]
	v_readlane_b32 s8, v254, 63
	v_readlane_b32 s9, v255, 0
	s_nop 1
	v_cndmask_b32_e64 v10, 0, 1, s[8:9]
	v_cndmask_b32_e64 v6, v10, v6, s[70:71]
	v_and_b32_e32 v6, 1, v6
	v_cmp_eq_u32_e32 vcc, 1, v6
	v_mul_f32_e32 v6, v2, v11
	v_readlane_b32 s8, v255, 1
	v_cndmask_b32_e32 v6, 0, v6, vcc
	v_bfe_u32 v10, v6, 16, 1
	v_add3_u32 v6, v6, v10, s33
	v_readlane_b32 s9, v255, 2
	global_store_short_d16_hi v[26:27], v6, off offset:2560
	s_nop 0
	v_cndmask_b32_e64 v6, 0, 1, s[8:9]
	v_readlane_b32 s8, v255, 3
	v_readlane_b32 s9, v255, 4
	s_nop 1
	v_cndmask_b32_e64 v10, 0, 1, s[8:9]
	v_cndmask_b32_e64 v6, v10, v6, s[70:71]
	v_and_b32_e32 v6, 1, v6
	v_cmp_eq_u32_e32 vcc, 1, v6
	v_mul_f32_e32 v6, v2, v7
	v_readlane_b32 s8, v255, 5
	v_cndmask_b32_e32 v6, 0, v6, vcc
	v_bfe_u32 v7, v6, 16, 1
	v_add3_u32 v6, v6, v7, s33
	v_readlane_b32 s9, v255, 6
	global_store_short_d16_hi v[26:27], v6, off offset:3072
	v_cndmask_b32_e64 v7, 0, 1, s[92:93]
	v_cndmask_b32_e64 v6, 0, 1, s[8:9]
	v_cndmask_b32_e64 v6, v7, v6, s[70:71]
	v_and_b32_e32 v6, 1, v6
	v_cmp_eq_u32_e32 vcc, 1, v6
	v_mul_f32_e32 v2, v2, v3
	v_cndmask_b32_e64 v10, 0, 1, s[20:21]
	v_cndmask_b32_e32 v2, 0, v2, vcc
	v_bfe_u32 v3, v2, 16, 1
	v_add3_u32 v2, v2, v3, s33
	global_store_short_d16_hi v[26:27], v2, off offset:3584
	v_mul_f32_e64 v2, -v0, v65
	v_mul_f32_e32 v3, v0, v64
	v_cndmask_b32_e64 v2, v3, v2, s[70:71]
	v_mul_f32_e32 v2, 0x3fb8aa3b, v2
	v_exp_f32_e32 v6, v2
	v_cndmask_b32_e64 v2, 0, 1, s[94:95]
	v_cndmask_b32_e64 v3, 0, 1, s[96:97]
	v_cndmask_b32_e64 v2, v3, v2, s[70:71]
	v_and_b32_e32 v2, 1, v2
	v_cmp_eq_u32_e32 vcc, 1, v2
	v_mul_f32_e32 v2, v6, v32
	v_mul_f32_e32 v4, v6, v4
	v_cndmask_b32_e32 v2, 0, v2, vcc
	v_bfe_u32 v3, v2, 16, 1
	v_add3_u32 v7, v2, v3, s33
	v_lshl_add_u64 v[2:3], v[42:43], 1, s[76:77]
	global_store_short_d16_hi v[2:3], v7, off
	v_cndmask_b32_e64 v2, 0, 1, s[6:7]
	v_cndmask_b32_e64 v3, 0, 1, s[16:17]
	v_cndmask_b32_e64 v2, v3, v2, s[70:71]
	v_and_b32_e32 v2, 1, v2
	v_cmp_eq_u32_e32 vcc, 1, v2
	v_mul_f32_e32 v2, v6, v28
	s_nop 0
	v_cndmask_b32_e32 v2, 0, v2, vcc
	v_bfe_u32 v3, v2, 16, 1
	v_add3_u32 v7, v2, v3, s33
	v_lshl_add_u64 v[2:3], v[50:51], 1, s[76:77]
	global_store_short_d16_hi v[2:3], v7, off offset:512
	v_cndmask_b32_e64 v7, 0, 1, s[18:19]
	v_cndmask_b32_e64 v7, v10, v7, s[70:71]
	v_and_b32_e32 v7, 1, v7
	v_cmp_eq_u32_e32 vcc, 1, v7
	v_mul_f32_e32 v7, v6, v24
	s_nop 0
	v_cndmask_b32_e32 v7, 0, v7, vcc
	v_bfe_u32 v10, v7, 16, 1
	v_add3_u32 v7, v7, v10, s33
	global_store_short_d16_hi v[2:3], v7, off offset:1024
	v_cndmask_b32_e64 v7, 0, 1, s[22:23]
	v_cndmask_b32_e64 v10, 0, 1, s[24:25]
	v_cndmask_b32_e64 v7, v10, v7, s[70:71]
	v_and_b32_e32 v7, 1, v7
	v_cmp_eq_u32_e32 vcc, 1, v7
	v_mul_f32_e32 v7, v6, v20
	s_nop 0
	v_cndmask_b32_e32 v7, 0, v7, vcc
	v_bfe_u32 v10, v7, 16, 1
	v_add3_u32 v7, v7, v10, s33
	global_store_short_d16_hi v[2:3], v7, off offset:1536
	v_cndmask_b32_e64 v7, 0, 1, s[26:27]
	v_cndmask_b32_e64 v10, 0, 1, s[28:29]
	v_cndmask_b32_e64 v7, v10, v7, s[70:71]
	v_and_b32_e32 v7, 1, v7
	v_cmp_eq_u32_e32 vcc, 1, v7
	v_mul_f32_e32 v7, v6, v16
	s_nop 0
	v_cndmask_b32_e32 v7, 0, v7, vcc
	v_bfe_u32 v10, v7, 16, 1
	v_add3_u32 v7, v7, v10, s33
	global_store_short_d16_hi v[2:3], v7, off offset:2048
	v_cndmask_b32_e64 v7, 0, 1, s[30:31]
	v_cndmask_b32_e64 v10, 0, 1, s[34:35]
	v_cndmask_b32_e64 v7, v10, v7, s[70:71]
	v_and_b32_e32 v7, 1, v7
	v_cmp_eq_u32_e32 vcc, 1, v7
	v_mul_f32_e32 v7, v6, v12
	s_nop 0
	v_cndmask_b32_e32 v7, 0, v7, vcc
	v_bfe_u32 v10, v7, 16, 1
	v_add3_u32 v7, v7, v10, s33
	global_store_short_d16_hi v[2:3], v7, off offset:2560
	v_cndmask_b32_e64 v7, 0, 1, s[36:37]
	v_cndmask_b32_e64 v10, 0, 1, s[0:1]
	v_cndmask_b32_e64 v7, v10, v7, s[70:71]
	v_and_b32_e32 v7, 1, v7
	v_cmp_eq_u32_e32 vcc, 1, v7
	v_mul_f32_e32 v7, v6, v8
	s_nop 0
	v_cndmask_b32_e32 v7, 0, v7, vcc
	v_bfe_u32 v8, v7, 16, 1
	v_add3_u32 v7, v7, v8, s33
	global_store_short_d16_hi v[2:3], v7, off offset:3072
	v_cndmask_b32_e64 v7, 0, 1, s[2:3]
	v_cndmask_b32_e64 v8, 0, 1, s[4:5]
	v_cndmask_b32_e64 v7, v8, v7, s[70:71]
	v_and_b32_e32 v7, 1, v7
	v_cmp_eq_u32_e32 vcc, 1, v7
	s_nop 1
	v_cndmask_b32_e32 v4, 0, v4, vcc
	v_bfe_u32 v6, v4, 16, 1
	v_add3_u32 v4, v4, v6, s33
	global_store_short_d16_hi v[2:3], v4, off offset:3584
	v_mul_f32_e64 v2, -v0, v67
	v_mul_f32_e32 v0, v0, v66
	v_cndmask_b32_e64 v0, v0, v2, s[70:71]
	v_mul_f32_e32 v0, 0x3fb8aa3b, v0
	v_exp_f32_e32 v0, v0
	v_cndmask_b32_e64 v2, 0, 1, s[38:39]
	v_cndmask_b32_e64 v3, 0, 1, s[40:41]
	v_cndmask_b32_e64 v2, v3, v2, s[70:71]
	v_and_b32_e32 v2, 1, v2
	v_cmp_eq_u32_e32 vcc, 1, v2
	v_mul_f32_e32 v2, v0, v33
	v_cndmask_b32_e64 v6, 0, 1, s[48:49]
	v_cndmask_b32_e32 v2, 0, v2, vcc
	v_bfe_u32 v3, v2, 16, 1
	v_add3_u32 v4, v2, v3, s33
	v_lshl_add_u64 v[2:3], v[44:45], 1, s[76:77]
	global_store_short_d16_hi v[2:3], v4, off
	v_cndmask_b32_e64 v2, 0, 1, s[42:43]
	v_cndmask_b32_e64 v3, 0, 1, s[44:45]
	v_cndmask_b32_e64 v2, v3, v2, s[70:71]
	v_and_b32_e32 v2, 1, v2
	v_cmp_eq_u32_e32 vcc, 1, v2
	v_mul_f32_e32 v2, v0, v29
	s_nop 0
	v_cndmask_b32_e32 v2, 0, v2, vcc
	v_bfe_u32 v3, v2, 16, 1
	v_add3_u32 v4, v2, v3, s33
	v_lshl_add_u64 v[2:3], v[52:53], 1, s[76:77]
	global_store_short_d16_hi v[2:3], v4, off offset:512
	v_cndmask_b32_e64 v4, 0, 1, s[46:47]
	v_cndmask_b32_e64 v4, v6, v4, s[70:71]
	v_and_b32_e32 v4, 1, v4
	v_cmp_eq_u32_e32 vcc, 1, v4
	v_mul_f32_e32 v4, v0, v25
	v_readlane_b32 s76, v252, 17
	v_cndmask_b32_e32 v4, 0, v4, vcc
	v_bfe_u32 v6, v4, 16, 1
	v_add3_u32 v4, v4, v6, s33
	global_store_short_d16_hi v[2:3], v4, off offset:1024
	v_cndmask_b32_e64 v4, 0, 1, s[50:51]
	v_cndmask_b32_e64 v6, 0, 1, s[52:53]
	v_cndmask_b32_e64 v4, v6, v4, s[70:71]
	v_and_b32_e32 v4, 1, v4
	v_cmp_eq_u32_e32 vcc, 1, v4
	v_mul_f32_e32 v4, v0, v21
	v_readlane_b32 s78, v252, 19
	v_cndmask_b32_e32 v4, 0, v4, vcc
	v_bfe_u32 v6, v4, 16, 1
	v_add3_u32 v4, v4, v6, s33
	global_store_short_d16_hi v[2:3], v4, off offset:1536
	v_cndmask_b32_e64 v4, 0, 1, s[54:55]
	v_cndmask_b32_e64 v6, 0, 1, s[56:57]
	v_cndmask_b32_e64 v4, v6, v4, s[70:71]
	v_and_b32_e32 v4, 1, v4
	v_cmp_eq_u32_e32 vcc, 1, v4
	v_mul_f32_e32 v4, v0, v17
	s_add_i32 s89, s89, s78
	v_cndmask_b32_e32 v4, 0, v4, vcc
	v_bfe_u32 v6, v4, 16, 1
	v_add3_u32 v4, v4, v6, s33
	global_store_short_d16_hi v[2:3], v4, off offset:2048
	v_cndmask_b32_e64 v4, 0, 1, s[58:59]
	v_cndmask_b32_e64 v6, 0, 1, s[60:61]
	v_cndmask_b32_e64 v4, v6, v4, s[70:71]
	v_and_b32_e32 v4, 1, v4
	v_cmp_eq_u32_e32 vcc, 1, v4
	v_mul_f32_e32 v4, v0, v13
	v_readlane_b32 s77, v252, 18
	v_cndmask_b32_e32 v4, 0, v4, vcc
	v_bfe_u32 v6, v4, 16, 1
	v_add3_u32 v4, v4, v6, s33
	global_store_short_d16_hi v[2:3], v4, off offset:2560
	v_cndmask_b32_e64 v4, 0, 1, s[62:63]
	v_cndmask_b32_e64 v6, 0, 1, s[64:65]
	v_cndmask_b32_e64 v4, v6, v4, s[70:71]
	v_and_b32_e32 v4, 1, v4
	v_cmp_eq_u32_e32 vcc, 1, v4
	v_mul_f32_e32 v4, v0, v9
	v_mul_f32_e32 v0, v0, v5
	v_cndmask_b32_e32 v4, 0, v4, vcc
	v_bfe_u32 v6, v4, 16, 1
	v_add3_u32 v4, v4, v6, s33
	global_store_short_d16_hi v[2:3], v4, off offset:3072
	v_cndmask_b32_e64 v4, 0, 1, s[66:67]
	v_cndmask_b32_e64 v6, 0, 1, s[68:69]
	v_cndmask_b32_e64 v4, v6, v4, s[70:71]
	v_and_b32_e32 v4, 1, v4
	v_cmp_eq_u32_e32 vcc, 1, v4
	s_cmpk_gt_i32 s89, 0x1ff
	v_readlane_b32 s79, v252, 20
	v_cndmask_b32_e32 v0, 0, v0, vcc
	v_bfe_u32 v4, v0, 16, 1
	v_add3_u32 v0, v0, v4, s33
	global_store_short_d16_hi v[2:3], v0, off offset:3584
	s_cbranch_scc1 .LBB0_1163

.LBB0_1220:
	s_or_b64 exec, exec, s[12:13]
	s_waitcnt vmcnt(8)
	v_mul_f32_e32 v40, 0x3fb8aa3b, v40
	v_exp_f32_e32 v46, v40
	s_lshl_b64 s[10:11], s[10:11], 13
	v_lshl_add_u64 v[40:41], s[10:11], 0, v[120:121]
	v_or_b32_e32 v42, v40, v124
	v_mul_f32_e32 v43, 0xc3000000, v46
	v_mul_f32_e32 v47, 0x3fb8aa3b, v43
	v_mov_b32_e32 v43, v41
	v_readlane_b32 s10, v251, 38
	v_lshlrev_b64 v[42:43], 11, v[42:43]
	v_readlane_b32 s11, v251, 39
	s_lshl_b32 s82, s19, 1
	s_lshl_b64 s[8:9], s[8:9], 21
	v_lshl_add_u64 v[42:43], s[10:11], 0, v[42:43]
	v_lshl_add_u64 v[42:43], v[42:43], 0, s[82:83]
	s_lshl_b32 s82, s17, 1
	s_cmpk_lt_u32 s16, 0x80
	s_cselect_b64 vcc, -1, 0
	v_cndmask_b32_e32 v48, v186, v187, vcc
	v_cvt_f32_i32_e32 v48, v48
	v_cndmask_b32_e32 v49, v188, v189, vcc
	v_cvt_f32_i32_e32 v49, v49
	v_or_b32_e32 v44, v40, v134
	v_mul_f32_e64 v48, -v46, v48
	v_mul_f32_e32 v48, 0x3fb8aa3b, v48
	v_exp_f32_e32 v226, v48
	v_mul_f32_e64 v48, -v46, v49
	v_mul_f32_e32 v48, 0x3fb8aa3b, v48
	v_cndmask_b32_e32 v49, v190, v191, vcc
	v_exp_f32_e32 v227, v48
	v_cndmask_b32_e32 v48, v192, v193, vcc
	v_cvt_f32_i32_e32 v49, v49
	v_cvt_f32_i32_e32 v48, v48
	v_mov_b32_e32 v45, v41
	v_readlane_b32 s10, v251, 2
	v_lshlrev_b64 v[44:45], 12, v[44:45]
	v_readlane_b32 s11, v251, 3
	v_or_b32_e32 v40, v40, v136
	v_lshlrev_b64 v[40:41], 9, v[40:41]
	v_lshl_add_u64 v[44:45], s[10:11], 0, v[44:45]
	v_readlane_b32 s10, v252, 24
	v_readlane_b32 s11, v252, 25
	v_mul_f32_e64 v49, -v46, v49
	v_mul_f32_e64 v46, -v46, v48
	v_lshl_add_u64 v[44:45], v[44:45], 0, s[82:83]
	v_lshl_add_u64 v[40:41], s[10:11], 0, v[40:41]
	v_mul_f32_e32 v49, 0x3fb8aa3b, v49
	v_mul_f32_e32 v46, 0x3fb8aa3b, v46
	v_exp_f32_e32 v146, v47
	s_lshl_b32 s82, s15, 7
	v_exp_f32_e32 v228, v49
	v_exp_f32_e32 v229, v46
	v_lshl_add_u64 v[40:41], v[40:41], 0, s[82:83]
	s_lshl_b32 s82, s14, 2
	v_mov_b32_e32 v139, v1
	v_lshl_add_u64 v[150:151], v[130:131], 0, s[8:9]
	v_mov_b32_e32 v141, v1
	s_and_b64 s[8:9], s[6:7], exec
	v_lshl_add_u64 v[148:149], v[42:43], 0, v[138:139]
	v_lshl_add_u64 v[152:153], v[44:45], 0, v[140:141]
	v_lshl_add_u64 v[154:155], v[40:41], 0, s[82:83]
	s_movk_i32 s8, 0x2080
	v_mov_b32_e32 v48, v1
	v_mov_b32_e32 v49, v1
	v_mov_b32_e32 v92, 0
	v_mov_b64_e32 v[46:47], v[2:3]
	v_mov_b64_e32 v[42:43], v[2:3]
	v_mov_b64_e32 v[70:71], v[2:3]
	v_mov_b64_e32 v[74:75], v[2:3]
	v_mov_b64_e32 v[78:79], v[2:3]
	v_mov_b64_e32 v[82:83], v[2:3]
	v_mov_b32_e32 v156, v146
	v_mov_b32_e32 v157, v146
	s_cselect_b32 s19, 0x2000, s8
	s_mov_b32 s9, -2
	s_mov_b32 s20, 64
	v_mov_b64_e32 v[44:45], v[0:1]
	v_mov_b64_e32 v[40:41], v[0:1]
	v_mov_b64_e32 v[68:69], v[0:1]
	v_mov_b64_e32 v[72:73], v[0:1]
	v_mov_b64_e32 v[76:77], v[0:1]
	v_mov_b64_e32 v[80:81], v[0:1]
	v_mov_b64_e32 v[66:67], v[48:49]
	v_mov_b64_e32 v[64:65], v[48:49]
	v_mov_b64_e32 v[86:87], v[48:49]
	v_mov_b64_e32 v[84:85], v[48:49]
	v_mov_b64_e32 v[90:91], v[48:49]
	v_mov_b64_e32 v[88:89], v[48:49]
	v_mov_b64_e32 v[50:51], v[48:49]
	v_mov_b64_e32 v[60:61], v[48:49]
	v_mov_b64_e32 v[62:63], v[48:49]
	v_mov_b64_e32 v[56:57], v[48:49]
	v_mov_b64_e32 v[58:59], v[48:49]
	v_mov_b64_e32 v[52:53], v[48:49]
	v_mov_b64_e32 v[54:55], v[48:49]
	v_mov_b32_e32 v93, v92
	v_mov_b32_e32 v94, v92
	v_mov_b32_e32 v95, v92
	v_mov_b32_e32 v96, v92
	v_mov_b32_e32 v97, v92
	v_mov_b32_e32 v98, v92
	v_mov_b32_e32 v99, v92
	v_mbcnt_lo_u32_b32 v100, -1, 0
	v_mbcnt_hi_u32_b32 v100, -1, v100
	v_lshrrev_b32_e32 v100, 5, v100
	v_mul_u32_u24_e32 v100, 0x600, v100
	s_mul_i32 s98, s15, 0x1e00
	s_add_u32 s98, s98, 0x1000
	v_sub_u32_e32 v104, s98, v100
	v_ashrrev_i32_e32 v105, 31, v104
	v_lshl_add_u64 v[148:149], v[148:149], 0, v[104:105]
	s_branch .LBB0_1222

.LBB0_1226:
	s_cmp_gt_u32 s13, 1
	s_cselect_b64 s[14:15], -1, 0
	s_and_b32 s12, s13, 1
	s_cmp_lt_u32 s13, 2
	s_mul_i32 s22, s12, 0x2100
	s_cbranch_scc1 .Lscan_nl
	s_waitcnt vmcnt(25)
	s_and_saveexec_b64 s[10:11], s[2:3]
	ds_write_b128 v137, v[40:43]
	s_or_b64 exec, exec, s[10:11]
	v_and_b32_sdwa v3, v92, v204 dst_sel:DWORD dst_unused:UNUSED_PAD src0_sel:WORD_1 src1_sel:DWORD
	v_add3_u32 v100, v92, v3, s33
	v_and_b32_sdwa v3, v95, v204 dst_sel:DWORD dst_unused:UNUSED_PAD src0_sel:WORD_1 src1_sel:DWORD
	v_and_b32_sdwa v101, v93, v204 dst_sel:DWORD dst_unused:UNUSED_PAD src0_sel:WORD_1 src1_sel:DWORD
	v_and_b32_sdwa v2, v94, v204 dst_sel:DWORD dst_unused:UNUSED_PAD src0_sel:WORD_1 src1_sel:DWORD
	v_add3_u32 v3, v95, v3, s33
	v_add3_u32 v101, v93, v101, s33
	v_add3_u32 v2, v94, v2, s33
	v_and_b32_e32 v3, 0xffff0000, v3
	v_and_b32_e32 v101, 0xffff0000, v101
	v_or_b32_sdwa v3, v3, v2 dst_sel:DWORD dst_unused:UNUSED_PAD src0_sel:DWORD src1_sel:WORD_1
	v_or_b32_sdwa v2, v101, v100 dst_sel:DWORD dst_unused:UNUSED_PAD src0_sel:DWORD src1_sel:WORD_1
	v_and_b32_sdwa v101, v96, v204 dst_sel:DWORD dst_unused:UNUSED_PAD src0_sel:WORD_1 src1_sel:DWORD
	v_add3_u32 v102, v96, v101, s33
	v_and_b32_sdwa v101, v99, v204 dst_sel:DWORD dst_unused:UNUSED_PAD src0_sel:WORD_1 src1_sel:DWORD
	v_and_b32_sdwa v103, v97, v204 dst_sel:DWORD dst_unused:UNUSED_PAD src0_sel:WORD_1 src1_sel:DWORD
	v_and_b32_sdwa v100, v98, v204 dst_sel:DWORD dst_unused:UNUSED_PAD src0_sel:WORD_1 src1_sel:DWORD
	v_add3_u32 v101, v99, v101, s33
	v_add3_u32 v103, v97, v103, s33
	v_add3_u32 v100, v98, v100, s33
	v_and_b32_e32 v101, 0xffff0000, v101
	v_and_b32_e32 v103, 0xffff0000, v103
	v_add_u32_e32 v0, s22, v179
	v_or_b32_sdwa v101, v101, v100 dst_sel:DWORD dst_unused:UNUSED_PAD src0_sel:DWORD src1_sel:WORD_1
	v_or_b32_sdwa v100, v103, v102 dst_sel:DWORD dst_unused:UNUSED_PAD src0_sel:DWORD src1_sel:WORD_1
	ds_write2_b64 v0, v[2:3], v[100:101] offset1:4

.LBB0_1236:
	s_andn2_b64 vcc, exec, s[10:11]
	s_lshl_b32 s10, s12, 7
	s_mov_b32 s100, 0
	s_cbranch_vccnz .LBB0_1240
	s_lshl_b32 s99, s12, 15
	s_lshl_b32 s98, s10, 11
	s_mov_b32 s100, 1
	s_and_saveexec_b64 s[12:13], s[2:3]
	s_cbranch_execz .Lscan_ldq_gA
	s_lshl_b32 s16, s10, 12
	s_mov_b32 s17, 0
	v_lshl_add_u64 v[2:3], v[152:153], 0, s[16:17]
	global_load_dwordx4 v[40:43], v[2:3], off

.LBB0_1242:
	s_or_b64 exec, exec, s[16:17]
	v_lshl_add_u32 v0, s23, 1, v158
	v_lshl_add_u32 v2, v159, 1, v0
	s_waitcnt lgkmcnt(0)
	s_barrier
	v_lshl_add_u32 v3, v160, 1, v0
	ds_read_b128 v[112:115], v2
	ds_read_b128 v[108:111], v3
	v_lshl_add_u32 v2, v161, 1, v0
	v_lshl_add_u32 v0, v162, 1, v0
	ds_read_b128 v[104:107], v2
	ds_read_b128 v[100:103], v0
	s_andn2_b64 vcc, exec, s[14:15]
	s_cbranch_vccnz .LBB0_1248
	s_setprio 1
	v_add_u32_e32 v0, s22, v181
	ds_read_b128 v[242:245], v0
	ds_read_b128 v[116:119], v0 offset:64
	ds_read_b128 v[238:241], v0 offset:128
	ds_read_b128 v[246:249], v0 offset:192
	s_waitcnt vmcnt(14)
	s_waitcnt lgkmcnt(3)
	v_mfma_f32_16x16x32_bf16 v[234:237], v[44:47], v[242:245], 0
	ds_read_b128 v[242:245], v0 offset:256
	s_waitcnt lgkmcnt(3)
	v_mfma_f32_16x16x32_bf16 v[230:233], v[52:55], v[116:119], 0
	ds_read_b128 v[116:119], v0 offset:320
	s_waitcnt lgkmcnt(3)
	v_mfma_f32_16x16x32_bf16 v[234:237], v[56:59], v[238:241], v[234:237]
	ds_read_b128 v[238:241], v0 offset:384
	s_waitcnt lgkmcnt(3)
	v_mfma_f32_16x16x32_bf16 v[230:233], v[60:63], v[246:249], v[230:233]
	ds_read_b128 v[246:249], v0 offset:448
	s_waitcnt lgkmcnt(3)
	v_mfma_f32_16x16x32_bf16 v[234:237], v[48:51], v[242:245], v[234:237]
	s_waitcnt lgkmcnt(2)
	v_mfma_f32_16x16x32_bf16 v[230:233], v[64:67], v[116:119], v[230:233]
	s_waitcnt lgkmcnt(1)
	v_mfma_f32_16x16x32_bf16 v[234:237], v[84:87], v[238:241], v[234:237]
	s_waitcnt lgkmcnt(0)
	v_mfma_f32_16x16x32_bf16 v[230:233], v[88:91], v[246:249], v[230:233]
	v_mfma_f32_16x16x32_bf16 v[116:119], v[80:83], v[112:115], 0
	v_mfma_f32_16x16x32_bf16 v[116:119], v[76:79], v[108:111], v[116:119]
	v_mfma_f32_16x16x32_bf16 v[116:119], v[72:75], v[104:107], v[116:119]
	v_mfma_f32_16x16x32_bf16 v[116:119], v[68:71], v[100:103], v[116:119]
	s_setprio 0
	s_cmp_eq_u32 s100, 0
	s_cbranch_scc1 .Lscan_ldq_donea
	s_mov_b32 s16, s98
	s_mov_b32 s17, 0
	v_lshl_add_u64 v[2:3], v[148:149], 0, s[16:17]
	global_load_dwordx4 v[44:47], v[2:3], off offset:-4096
	global_load_dwordx4 v[52:55], v[2:3], off offset:-3072
	global_load_dwordx4 v[56:59], v[2:3], off offset:-2048
	global_load_dwordx4 v[60:63], v[2:3], off offset:-1024
	global_load_dwordx4 v[48:51], v[2:3], off offset:0
	global_load_dwordx4 v[64:67], v[2:3], off offset:1024
	global_load_dwordx4 v[84:87], v[2:3], off offset:2048
	global_load_dwordx4 v[88:91], v[2:3], off offset:3072
	s_mov_b32 s16, s99
	v_lshl_add_u64 v[2:3], v[150:151], 0, s[16:17]
	global_load_dwordx4 v[80:83], v[2:3], off
	global_load_dwordx4 v[76:79], v[2:3], off offset:1024
	global_load_dwordx4 v[72:75], v[2:3], off offset:2048
	global_load_dwordx4 v[68:71], v[2:3], off offset:3072

.LBB0_1248:
	s_cmp_eq_u32 s100, 0
	s_cbranch_scc1 .Lscan_ldq_doneb
	s_mov_b32 s16, s98
	s_mov_b32 s17, 0
	v_lshl_add_u64 v[2:3], v[148:149], 0, s[16:17]
	global_load_dwordx4 v[44:47], v[2:3], off offset:-4096
	global_load_dwordx4 v[52:55], v[2:3], off offset:-3072
	global_load_dwordx4 v[56:59], v[2:3], off offset:-2048
	global_load_dwordx4 v[60:63], v[2:3], off offset:-1024
	global_load_dwordx4 v[48:51], v[2:3], off offset:0
	global_load_dwordx4 v[64:67], v[2:3], off offset:1024
	global_load_dwordx4 v[84:87], v[2:3], off offset:2048
	global_load_dwordx4 v[88:91], v[2:3], off offset:3072
	s_mov_b32 s16, s99
	v_lshl_add_u64 v[2:3], v[150:151], 0, s[16:17]
	global_load_dwordx4 v[80:83], v[2:3], off
	global_load_dwordx4 v[76:79], v[2:3], off offset:1024
	global_load_dwordx4 v[72:75], v[2:3], off offset:2048
	global_load_dwordx4 v[68:71], v[2:3], off offset:3072
